# stack: attention bias batching + V hoist + softmax/PV interleave + write-through GEMM epilogue stores
# baseline (speedup 1.0000x reference)
; __device__ __forceinline__ unsigned cvt_pk_bf16(float lo, float hi) { unsigned r; asm volatile("v_cvt_pk_bf16_f32 %0, %1, %2" : "=v"(r) : "v"(lo), "v"(hi)); return r; }
;     __device__ __forceinline__ void operator()(const f32x4 (&acc)[2][2][4][2], const State& st, const Unit& u, int wr, int wc, int fr, int fq) const {
;     ...
;                 if (u.pn >= 16) {
;                     const f32x4 q0 = v[0][0] * v[1][0], q1 = v[0][1] * v[1][1];
;                     u32x4 w; w.x = cvt_pk_bf16(q0[0], q0[1]); w.y = cvt_pk_bf16(q0[2], q0[3]); w.z = cvt_pk_bf16(q1[0], q1[1]); w.w = cvt_pk_bf16(q1[2], q1[3]);
;                     *(u32x4*)(O + (size_t)row * ldc + 4096 + (u.pn - 16) * 128 + wc * 32 + 8 * fq) = w;
;                 } else {
;                 bf16_t* rowp = O + (size_t)row * ldc + col0;
; #pragma unroll
;                 for (int bj = 0; bj < 2; ++bj) { u32x4 w; w.x = cvt_pk_bf16(v[bj][0][0], v[bj][0][1]); w.y = cvt_pk_bf16(v[bj][0][2], v[bj][0][3]); w.z = cvt_pk_bf16(v[bj][1][0], v[bj][1][1]); w.w = cvt_pk_bf16(v[bj][1][2], v[bj][1][3]);
;                     *(u32x4*)(rowp + 32 * bj) = w; } } }
.LBB0_187:
	s_cmp_lt_i32 s79, 16
	v_lshl_or_b32 v128, s79, 8, v198
	s_cselect_b64 s[0:1], -1, 0
	v_lshl_add_u32 v200, s14, 8, v161
	v_ashrrev_i32_e32 v129, 31, v128
	s_mov_b64 s[6:7], -1
	s_and_b64 vcc, exec, s[0:1]
	s_cbranch_vccz .LBB0_189
	v_mov_b64_e32 v[202:203], s[18:19]
	v_mad_i64_i32 v[202:203], s[6:7], v200, s70, v[202:203]
	v_lshl_add_u64 v[206:207], v[128:129], 1, v[202:203]
	v_cvt_pk_bf16_f32 v202, v140, v141
	v_cvt_pk_bf16_f32 v203, v142, v143
	v_cvt_pk_bf16_f32 v204, v136, v137
	v_cvt_pk_bf16_f32 v205, v138, v139
	global_store_dwordx4 v[206:207], v[202:205], off sc1
	s_mov_b64 s[6:7], 0
	s_nop 0
	v_cvt_pk_bf16_f32 v202, v132, v133
	v_cvt_pk_bf16_f32 v203, v134, v135
	v_cvt_pk_bf16_f32 v204, v184, v185
	v_cvt_pk_bf16_f32 v205, v130, v131
	global_store_dwordx4 v[206:207], v[202:205], off offset:64 sc1
.LBB0_189:
	s_andn2_b64 vcc, exec, s[6:7]
	v_lshlrev_b32_e32 v144, 1, v160
	s_cbranch_vccnz .LBB0_191
	v_pk_mul_f32 v[134:135], v[134:135], v[142:143]
	v_pk_mul_f32 v[132:133], v[132:133], v[140:141]
	v_pk_mul_f32 v[138:139], v[130:131], v[138:139]
	v_cvt_pk_bf16_f32 v130, v132, v133
	v_cvt_pk_bf16_f32 v131, v134, v135
	v_mov_b64_e32 v[134:135], s[18:19]
	v_mad_i64_i32 v[134:135], s[6:7], v200, s70, v[134:135]
	s_lshl_b32 s14, s79, 8
	v_lshl_add_u64 v[134:135], v[134:135], 0, s[14:15]
	s_lshl_b32 s14, s71, 1
	v_lshl_add_u64 v[134:135], v[134:135], 0, s[14:15]
	v_lshl_add_u64 v[134:135], v[134:135], 0, v[144:145]
	v_add_co_u32_e32 v134, vcc, 0x1000, v134
	v_pk_mul_f32 v[136:137], v[184:185], v[136:137]
	s_nop 0
	v_addc_co_u32_e32 v135, vcc, 0, v135, vcc
	v_cvt_pk_bf16_f32 v132, v136, v137
	v_cvt_pk_bf16_f32 v133, v138, v139
	global_store_dwordx4 v[134:135], v[130:133], off sc1

; __device__ __forceinline__ unsigned cvt_pk_bf16(float lo, float hi) { unsigned r; asm volatile("v_cvt_pk_bf16_f32 %0, %1, %2" : "=v"(r) : "v"(lo), "v"(hi)); return r; }
;     __device__ __forceinline__ void operator()(const f32x4 (&acc)[2][2][4][2], const State& st, const Unit& u, int wr, int wc, int fr, int fq) const {
;     ...
;                 if (u.pn >= 16) {
;                     const f32x4 q0 = v[0][0] * v[1][0], q1 = v[0][1] * v[1][1];
;                     u32x4 w; w.x = cvt_pk_bf16(q0[0], q0[1]); w.y = cvt_pk_bf16(q0[2], q0[3]); w.z = cvt_pk_bf16(q1[0], q1[1]); w.w = cvt_pk_bf16(q1[2], q1[3]);
;                     *(u32x4*)(O + (size_t)row * ldc + 4096 + (u.pn - 16) * 128 + wc * 32 + 8 * fq) = w;
;                 } else {
;                 bf16_t* rowp = O + (size_t)row * ldc + col0;
; #pragma unroll
;                 for (int bj = 0; bj < 2; ++bj) { u32x4 w; w.x = cvt_pk_bf16(v[bj][0][0], v[bj][0][1]); w.y = cvt_pk_bf16(v[bj][0][2], v[bj][0][3]); w.z = cvt_pk_bf16(v[bj][1][0], v[bj][1][1]); w.w = cvt_pk_bf16(v[bj][1][2], v[bj][1][3]);
;                     *(u32x4*)(rowp + 32 * bj) = w; } } }
.LBB0_193:
	v_cndmask_b32_e64 v131, 0, 1, s[0:1]
	v_or_b32_e32 v130, 16, v200
	v_cmp_ne_u32_e64 s[42:43], 1, v131
	s_andn2_b64 vcc, exec, s[0:1]
	s_mov_b64 s[0:1], -1
	s_cbranch_vccnz .LBB0_195
	v_mov_b64_e32 v[132:133], s[18:19]
	v_mad_i64_i32 v[132:133], s[0:1], v130, s70, v[132:133]
	v_lshl_add_u64 v[136:137], v[128:129], 1, v[132:133]
	v_cvt_pk_bf16_f32 v132, v124, v125
	v_cvt_pk_bf16_f32 v133, v126, v127
	v_cvt_pk_bf16_f32 v134, v120, v121
	v_cvt_pk_bf16_f32 v135, v122, v123
	s_mov_b64 s[0:1], 0
	global_store_dwordx4 v[136:137], v[132:135], off sc1
	s_nop 1
	v_cvt_pk_bf16_f32 v132, v116, v117
	v_cvt_pk_bf16_f32 v133, v118, v119
	v_cvt_pk_bf16_f32 v134, v112, v113
	v_cvt_pk_bf16_f32 v135, v114, v115
	global_store_dwordx4 v[136:137], v[132:135], off offset:64 sc1
.LBB0_195:
	s_andn2_b64 vcc, exec, s[0:1]
	s_cbranch_vccnz .LBB0_197
	v_pk_mul_f32 v[116:117], v[116:117], v[124:125]
	v_pk_mul_f32 v[122:123], v[114:115], v[122:123]
	v_pk_mul_f32 v[114:115], v[112:113], v[120:121]
	v_cvt_pk_bf16_f32 v112, v116, v117
	v_mov_b64_e32 v[116:117], s[18:19]
	v_mad_i64_i32 v[116:117], s[0:1], v130, s70, v[116:117]
	s_lshl_b32 s14, s79, 8
	v_lshl_add_u64 v[116:117], v[116:117], 0, s[14:15]
	s_lshl_b32 s14, s71, 1
	v_lshl_add_u64 v[116:117], v[116:117], 0, s[14:15]
	v_lshl_add_u64 v[116:117], v[116:117], 0, v[144:145]
	v_add_co_u32_e32 v116, vcc, 0x1000, v116
	v_pk_mul_f32 v[118:119], v[118:119], v[126:127]
	s_nop 0
	v_addc_co_u32_e32 v117, vcc, 0, v117, vcc
	v_cvt_pk_bf16_f32 v113, v118, v119
	v_cvt_pk_bf16_f32 v114, v114, v115
	v_cvt_pk_bf16_f32 v115, v122, v123
	global_store_dwordx4 v[116:117], v[112:115], off sc1

; __device__ __forceinline__ unsigned cvt_pk_bf16(float lo, float hi) { unsigned r; asm volatile("v_cvt_pk_bf16_f32 %0, %1, %2" : "=v"(r) : "v"(lo), "v"(hi)); return r; }
;     __device__ __forceinline__ void operator()(const f32x4 (&acc)[2][2][4][2], const State& st, const Unit& u, int wr, int wc, int fr, int fq) const {
;     ...
;                 if (u.pn >= 16) {
;                     const f32x4 q0 = v[0][0] * v[1][0], q1 = v[0][1] * v[1][1];
;                     u32x4 w; w.x = cvt_pk_bf16(q0[0], q0[1]); w.y = cvt_pk_bf16(q0[2], q0[3]); w.z = cvt_pk_bf16(q1[0], q1[1]); w.w = cvt_pk_bf16(q1[2], q1[3]);
;                     *(u32x4*)(O + (size_t)row * ldc + 4096 + (u.pn - 16) * 128 + wc * 32 + 8 * fq) = w;
.LBB0_200:
	v_pk_mul_f32 v[100:101], v[100:101], v[108:109]
	v_pk_mul_f32 v[106:107], v[98:99], v[106:107]
	v_pk_mul_f32 v[98:99], v[96:97], v[104:105]
	v_cvt_pk_bf16_f32 v96, v100, v101
	v_mov_b64_e32 v[100:101], s[18:19]
	v_mad_i64_i32 v[100:101], s[0:1], v112, s70, v[100:101]
	s_lshl_b32 s14, s79, 8
	v_lshl_add_u64 v[100:101], v[100:101], 0, s[14:15]
	s_lshl_b32 s14, s71, 1
	v_lshl_add_u64 v[100:101], v[100:101], 0, s[14:15]
	v_lshl_add_u64 v[100:101], v[100:101], 0, v[144:145]
	v_add_co_u32_e32 v100, vcc, 0x1000, v100
	v_pk_mul_f32 v[102:103], v[102:103], v[110:111]
	s_nop 0
	v_addc_co_u32_e32 v101, vcc, 0, v101, vcc
	v_cvt_pk_bf16_f32 v97, v102, v103
	v_cvt_pk_bf16_f32 v98, v98, v99
	v_cvt_pk_bf16_f32 v99, v106, v107
	global_store_dwordx4 v[100:101], v[96:99], off sc1

; __device__ __forceinline__ unsigned cvt_pk_bf16(float lo, float hi) { unsigned r; asm volatile("v_cvt_pk_bf16_f32 %0, %1, %2" : "=v"(r) : "v"(lo), "v"(hi)); return r; }
;     __device__ __forceinline__ void operator()(const f32x4 (&acc)[2][2][4][2], const State& st, const Unit& u, int wr, int wc, int fr, int fq) const {
;     ...
;                 if (u.pn >= 16) {
;                     const f32x4 q0 = v[0][0] * v[1][0], q1 = v[0][1] * v[1][1];
;                     u32x4 w; w.x = cvt_pk_bf16(q0[0], q0[1]); w.y = cvt_pk_bf16(q0[2], q0[3]); w.z = cvt_pk_bf16(q1[0], q1[1]); w.w = cvt_pk_bf16(q1[2], q1[3]);
;                     *(u32x4*)(O + (size_t)row * ldc + 4096 + (u.pn - 16) * 128 + wc * 32 + 8 * fq) = w;
.LBB0_204:
	v_pk_mul_f32 v[84:85], v[84:85], v[92:93]
	v_pk_mul_f32 v[90:91], v[82:83], v[90:91]
	v_pk_mul_f32 v[82:83], v[80:81], v[88:89]
	v_cvt_pk_bf16_f32 v80, v84, v85
	v_mov_b64_e32 v[84:85], s[18:19]
	v_mad_i64_i32 v[84:85], s[0:1], v96, s70, v[84:85]
	s_lshl_b32 s14, s79, 8
	v_lshl_add_u64 v[84:85], v[84:85], 0, s[14:15]
	s_lshl_b32 s14, s71, 1
	v_lshl_add_u64 v[84:85], v[84:85], 0, s[14:15]
	v_lshl_add_u64 v[84:85], v[84:85], 0, v[144:145]
	v_add_co_u32_e32 v84, vcc, 0x1000, v84
	v_pk_mul_f32 v[86:87], v[86:87], v[94:95]
	s_nop 0
	v_addc_co_u32_e32 v85, vcc, 0, v85, vcc
	v_cvt_pk_bf16_f32 v81, v86, v87
	v_cvt_pk_bf16_f32 v82, v82, v83
	v_cvt_pk_bf16_f32 v83, v90, v91
	global_store_dwordx4 v[84:85], v[80:83], off sc1

; __device__ __forceinline__ unsigned cvt_pk_bf16(float lo, float hi) { unsigned r; asm volatile("v_cvt_pk_bf16_f32 %0, %1, %2" : "=v"(r) : "v"(lo), "v"(hi)); return r; }
;     __device__ __forceinline__ void operator()(const f32x4 (&acc)[2][2][4][2], const State& st, const Unit& u, int wr, int wc, int fr, int fq) const {
;     ...
;                 if (u.pn >= 16) {
;                     const f32x4 q0 = v[0][0] * v[1][0], q1 = v[0][1] * v[1][1];
;                     u32x4 w; w.x = cvt_pk_bf16(q0[0], q0[1]); w.y = cvt_pk_bf16(q0[2], q0[3]); w.z = cvt_pk_bf16(q1[0], q1[1]); w.w = cvt_pk_bf16(q1[2], q1[3]);
;                     *(u32x4*)(O + (size_t)row * ldc + 4096 + (u.pn - 16) * 128 + wc * 32 + 8 * fq) = w;
.LBB0_208:
	v_pk_mul_f32 v[68:69], v[68:69], v[76:77]
	v_pk_mul_f32 v[74:75], v[66:67], v[74:75]
	v_pk_mul_f32 v[66:67], v[64:65], v[72:73]
	v_cvt_pk_bf16_f32 v64, v68, v69
	v_mov_b64_e32 v[68:69], s[18:19]
	v_mad_i64_i32 v[68:69], s[0:1], v80, s70, v[68:69]
	s_lshl_b32 s14, s79, 8
	v_lshl_add_u64 v[68:69], v[68:69], 0, s[14:15]
	s_lshl_b32 s14, s71, 1
	v_lshl_add_u64 v[68:69], v[68:69], 0, s[14:15]
	v_lshl_add_u64 v[68:69], v[68:69], 0, v[144:145]
	v_add_co_u32_e32 v68, vcc, 0x1000, v68
	v_pk_mul_f32 v[70:71], v[70:71], v[78:79]
	s_nop 0
	v_addc_co_u32_e32 v69, vcc, 0, v69, vcc
	v_cvt_pk_bf16_f32 v65, v70, v71
	v_cvt_pk_bf16_f32 v66, v66, v67
	v_cvt_pk_bf16_f32 v67, v74, v75
	global_store_dwordx4 v[68:69], v[64:67], off sc1

; __device__ __forceinline__ unsigned cvt_pk_bf16(float lo, float hi) { unsigned r; asm volatile("v_cvt_pk_bf16_f32 %0, %1, %2" : "=v"(r) : "v"(lo), "v"(hi)); return r; }
;     __device__ __forceinline__ void operator()(const f32x4 (&acc)[2][2][4][2], const State& st, const Unit& u, int wr, int wc, int fr, int fq) const {
;     ...
;                 if (u.pn >= 16) {
;                     const f32x4 q0 = v[0][0] * v[1][0], q1 = v[0][1] * v[1][1];
;                     u32x4 w; w.x = cvt_pk_bf16(q0[0], q0[1]); w.y = cvt_pk_bf16(q0[2], q0[3]); w.z = cvt_pk_bf16(q1[0], q1[1]); w.w = cvt_pk_bf16(q1[2], q1[3]);
;                     *(u32x4*)(O + (size_t)row * ldc + 4096 + (u.pn - 16) * 128 + wc * 32 + 8 * fq) = w;
.LBB0_212:
	v_pk_mul_f32 v[36:37], v[36:37], v[44:45]
	v_pk_mul_f32 v[42:43], v[34:35], v[42:43]
	v_pk_mul_f32 v[34:35], v[32:33], v[40:41]
	v_cvt_pk_bf16_f32 v32, v36, v37
	v_mov_b64_e32 v[36:37], s[18:19]
	v_mad_i64_i32 v[36:37], s[0:1], v64, s70, v[36:37]
	s_lshl_b32 s14, s79, 8
	v_lshl_add_u64 v[36:37], v[36:37], 0, s[14:15]
	s_lshl_b32 s14, s71, 1
	v_lshl_add_u64 v[36:37], v[36:37], 0, s[14:15]
	v_lshl_add_u64 v[36:37], v[36:37], 0, v[144:145]
	v_add_co_u32_e32 v36, vcc, 0x1000, v36
	v_pk_mul_f32 v[38:39], v[38:39], v[46:47]
	s_nop 0
	v_addc_co_u32_e32 v37, vcc, 0, v37, vcc
	v_cvt_pk_bf16_f32 v33, v38, v39
	v_cvt_pk_bf16_f32 v34, v34, v35
	v_cvt_pk_bf16_f32 v35, v42, v43
	global_store_dwordx4 v[36:37], v[32:35], off sc1

; __device__ __forceinline__ unsigned cvt_pk_bf16(float lo, float hi) { unsigned r; asm volatile("v_cvt_pk_bf16_f32 %0, %1, %2" : "=v"(r) : "v"(lo), "v"(hi)); return r; }
;     __device__ __forceinline__ void operator()(const f32x4 (&acc)[2][2][4][2], const State& st, const Unit& u, int wr, int wc, int fr, int fq) const {
;     ...
;                 if (u.pn >= 16) {
;                     const f32x4 q0 = v[0][0] * v[1][0], q1 = v[0][1] * v[1][1];
;                     u32x4 w; w.x = cvt_pk_bf16(q0[0], q0[1]); w.y = cvt_pk_bf16(q0[2], q0[3]); w.z = cvt_pk_bf16(q1[0], q1[1]); w.w = cvt_pk_bf16(q1[2], q1[3]);
;                     *(u32x4*)(O + (size_t)row * ldc + 4096 + (u.pn - 16) * 128 + wc * 32 + 8 * fq) = w;
.LBB0_216:
	v_pk_mul_f32 v[20:21], v[20:21], v[28:29]
	v_pk_mul_f32 v[26:27], v[18:19], v[26:27]
	v_pk_mul_f32 v[18:19], v[16:17], v[24:25]
	v_cvt_pk_bf16_f32 v16, v20, v21
	v_mov_b64_e32 v[20:21], s[18:19]
	v_mad_i64_i32 v[20:21], s[0:1], v32, s70, v[20:21]
	s_lshl_b32 s14, s79, 8
	v_lshl_add_u64 v[20:21], v[20:21], 0, s[14:15]
	s_lshl_b32 s14, s71, 1
	v_lshl_add_u64 v[20:21], v[20:21], 0, s[14:15]
	v_lshl_add_u64 v[20:21], v[20:21], 0, v[144:145]
	v_add_co_u32_e32 v20, vcc, 0x1000, v20
	v_pk_mul_f32 v[22:23], v[22:23], v[30:31]
	s_nop 0
	v_addc_co_u32_e32 v21, vcc, 0, v21, vcc
	v_cvt_pk_bf16_f32 v17, v22, v23
	v_cvt_pk_bf16_f32 v18, v18, v19
	v_cvt_pk_bf16_f32 v19, v26, v27
	global_store_dwordx4 v[20:21], v[16:19], off sc1

; __device__ __forceinline__ unsigned cvt_pk_bf16(float lo, float hi) { unsigned r; asm volatile("v_cvt_pk_bf16_f32 %0, %1, %2" : "=v"(r) : "v"(lo), "v"(hi)); return r; }
;     __device__ __forceinline__ void operator()(const f32x4 (&acc)[2][2][4][2], const State& st, const Unit& u, int wr, int wc, int fr, int fq) const {
;     ...
;                 if (u.pn >= 16) {
;                     const f32x4 q0 = v[0][0] * v[1][0], q1 = v[0][1] * v[1][1];
;                     u32x4 w; w.x = cvt_pk_bf16(q0[0], q0[1]); w.y = cvt_pk_bf16(q0[2], q0[3]); w.z = cvt_pk_bf16(q1[0], q1[1]); w.w = cvt_pk_bf16(q1[2], q1[3]);
;                     *(u32x4*)(O + (size_t)row * ldc + 4096 + (u.pn - 16) * 128 + wc * 32 + 8 * fq) = w;
.LBB0_220:
	v_pk_mul_f32 v[4:5], v[4:5], v[12:13]
	v_pk_mul_f32 v[10:11], v[2:3], v[10:11]
	v_pk_mul_f32 v[2:3], v[0:1], v[8:9]
	v_cvt_pk_bf16_f32 v0, v4, v5
	v_mov_b64_e32 v[4:5], s[18:19]
	v_mad_i64_i32 v[4:5], s[0:1], v16, s70, v[4:5]
	s_lshl_b32 s14, s79, 8
	v_lshl_add_u64 v[4:5], v[4:5], 0, s[14:15]
	s_lshl_b32 s14, s71, 1
	v_lshl_add_u64 v[4:5], v[4:5], 0, s[14:15]
	v_lshl_add_u64 v[4:5], v[4:5], 0, v[144:145]
	v_add_co_u32_e32 v4, vcc, 0x1000, v4
	v_pk_mul_f32 v[6:7], v[6:7], v[14:15]
	s_nop 0
	v_addc_co_u32_e32 v5, vcc, 0, v5, vcc
	v_cvt_pk_bf16_f32 v1, v6, v7
	v_cvt_pk_bf16_f32 v2, v2, v3
	v_cvt_pk_bf16_f32 v3, v10, v11
	global_store_dwordx4 v[4:5], v[0:3], off sc1
	s_andn2_b64 vcc, exec, s[38:39]
	s_mov_b64 s[0:1], -1
	s_cbranch_vccnz .LBB0_166
	s_branch .LBB0_234

; __device__ __forceinline__ unsigned cvt_pk_bf16(float lo, float hi) { unsigned r; asm volatile("v_cvt_pk_bf16_f32 %0, %1, %2" : "=v"(r) : "v"(lo), "v"(hi)); return r; }
;     __device__ __forceinline__ void operator()(const f32x4 (&acc)[2][2][4][2], const State& st, const Unit& u, int wr, int wc, int fr, int fq) const {
;     ...
;                 } else {
;                 bf16_t* rowp = O + (size_t)row * ldc + col0;
; #pragma unroll
;                 for (int bj = 0; bj < 2; ++bj) { u32x4 w; w.x = cvt_pk_bf16(v[bj][0][0], v[bj][0][1]); w.y = cvt_pk_bf16(v[bj][0][2], v[bj][0][3]); w.z = cvt_pk_bf16(v[bj][1][0], v[bj][1][1]); w.w = cvt_pk_bf16(v[bj][1][2], v[bj][1][3]);
;                     *(u32x4*)(rowp + 32 * bj) = w; } } }
.LBB0_222:
	v_mov_b64_e32 v[114:115], s[18:19]
	v_mad_i64_i32 v[114:115], s[0:1], v112, s70, v[114:115]
	v_lshl_add_u64 v[118:119], v[128:129], 1, v[114:115]
	v_cvt_pk_bf16_f32 v114, v108, v109
	v_cvt_pk_bf16_f32 v115, v110, v111
	v_cvt_pk_bf16_f32 v116, v104, v105
	v_cvt_pk_bf16_f32 v117, v106, v107
	global_store_dwordx4 v[118:119], v[114:117], off sc1
	s_nop 1
	v_cvt_pk_bf16_f32 v114, v100, v101
	v_cvt_pk_bf16_f32 v115, v102, v103
	v_cvt_pk_bf16_f32 v116, v96, v97
	v_cvt_pk_bf16_f32 v117, v98, v99
	global_store_dwordx4 v[118:119], v[114:117], off offset:64 sc1
	s_cbranch_execz .LBB0_200
	s_branch .LBB0_201

; __device__ __forceinline__ unsigned cvt_pk_bf16(float lo, float hi) { unsigned r; asm volatile("v_cvt_pk_bf16_f32 %0, %1, %2" : "=v"(r) : "v"(lo), "v"(hi)); return r; }
;     __device__ __forceinline__ void operator()(const f32x4 (&acc)[2][2][4][2], const State& st, const Unit& u, int wr, int wc, int fr, int fq) const {
;     ...
;                 } else {
;                 bf16_t* rowp = O + (size_t)row * ldc + col0;
; #pragma unroll
;                 for (int bj = 0; bj < 2; ++bj) { u32x4 w; w.x = cvt_pk_bf16(v[bj][0][0], v[bj][0][1]); w.y = cvt_pk_bf16(v[bj][0][2], v[bj][0][3]); w.z = cvt_pk_bf16(v[bj][1][0], v[bj][1][1]); w.w = cvt_pk_bf16(v[bj][1][2], v[bj][1][3]);
;                     *(u32x4*)(rowp + 32 * bj) = w; } } }
.LBB0_224:
	v_mov_b64_e32 v[98:99], s[18:19]
	v_mad_i64_i32 v[98:99], s[0:1], v96, s70, v[98:99]
	v_lshl_add_u64 v[102:103], v[128:129], 1, v[98:99]
	v_cvt_pk_bf16_f32 v98, v92, v93
	v_cvt_pk_bf16_f32 v99, v94, v95
	v_cvt_pk_bf16_f32 v100, v88, v89
	v_cvt_pk_bf16_f32 v101, v90, v91
	global_store_dwordx4 v[102:103], v[98:101], off sc1
	s_nop 1
	v_cvt_pk_bf16_f32 v98, v84, v85
	v_cvt_pk_bf16_f32 v99, v86, v87
	v_cvt_pk_bf16_f32 v100, v80, v81
	v_cvt_pk_bf16_f32 v101, v82, v83
	global_store_dwordx4 v[102:103], v[98:101], off offset:64 sc1
	s_cbranch_execz .LBB0_204
	s_branch .LBB0_205

; __device__ __forceinline__ unsigned cvt_pk_bf16(float lo, float hi) { unsigned r; asm volatile("v_cvt_pk_bf16_f32 %0, %1, %2" : "=v"(r) : "v"(lo), "v"(hi)); return r; }
;     __device__ __forceinline__ void operator()(const f32x4 (&acc)[2][2][4][2], const State& st, const Unit& u, int wr, int wc, int fr, int fq) const {
;     ...
;                 } else {
;                 bf16_t* rowp = O + (size_t)row * ldc + col0;
; #pragma unroll
;                 for (int bj = 0; bj < 2; ++bj) { u32x4 w; w.x = cvt_pk_bf16(v[bj][0][0], v[bj][0][1]); w.y = cvt_pk_bf16(v[bj][0][2], v[bj][0][3]); w.z = cvt_pk_bf16(v[bj][1][0], v[bj][1][1]); w.w = cvt_pk_bf16(v[bj][1][2], v[bj][1][3]);
;                     *(u32x4*)(rowp + 32 * bj) = w; } } }
.LBB0_226:
	v_mov_b64_e32 v[82:83], s[18:19]
	v_mad_i64_i32 v[82:83], s[0:1], v80, s70, v[82:83]
	v_lshl_add_u64 v[86:87], v[128:129], 1, v[82:83]
	v_cvt_pk_bf16_f32 v82, v76, v77
	v_cvt_pk_bf16_f32 v83, v78, v79
	v_cvt_pk_bf16_f32 v84, v72, v73
	v_cvt_pk_bf16_f32 v85, v74, v75
	global_store_dwordx4 v[86:87], v[82:85], off sc1
	s_nop 1
	v_cvt_pk_bf16_f32 v82, v68, v69
	v_cvt_pk_bf16_f32 v83, v70, v71
	v_cvt_pk_bf16_f32 v84, v64, v65
	v_cvt_pk_bf16_f32 v85, v66, v67
	global_store_dwordx4 v[86:87], v[82:85], off offset:64 sc1
	s_cbranch_execz .LBB0_208
	s_branch .LBB0_209

; __device__ __forceinline__ unsigned cvt_pk_bf16(float lo, float hi) { unsigned r; asm volatile("v_cvt_pk_bf16_f32 %0, %1, %2" : "=v"(r) : "v"(lo), "v"(hi)); return r; }
;     __device__ __forceinline__ void operator()(const f32x4 (&acc)[2][2][4][2], const State& st, const Unit& u, int wr, int wc, int fr, int fq) const {
;     ...
;                 } else {
;                 bf16_t* rowp = O + (size_t)row * ldc + col0;
; #pragma unroll
;                 for (int bj = 0; bj < 2; ++bj) { u32x4 w; w.x = cvt_pk_bf16(v[bj][0][0], v[bj][0][1]); w.y = cvt_pk_bf16(v[bj][0][2], v[bj][0][3]); w.z = cvt_pk_bf16(v[bj][1][0], v[bj][1][1]); w.w = cvt_pk_bf16(v[bj][1][2], v[bj][1][3]);
;                     *(u32x4*)(rowp + 32 * bj) = w; } } }
.LBB0_228:
	v_mov_b64_e32 v[66:67], s[18:19]
	v_mad_i64_i32 v[66:67], s[0:1], v64, s70, v[66:67]
	v_lshl_add_u64 v[70:71], v[128:129], 1, v[66:67]
	v_cvt_pk_bf16_f32 v66, v44, v45
	v_cvt_pk_bf16_f32 v67, v46, v47
	v_cvt_pk_bf16_f32 v68, v40, v41
	v_cvt_pk_bf16_f32 v69, v42, v43
	global_store_dwordx4 v[70:71], v[66:69], off sc1
	s_nop 1
	v_cvt_pk_bf16_f32 v66, v36, v37
	v_cvt_pk_bf16_f32 v67, v38, v39
	v_cvt_pk_bf16_f32 v68, v32, v33
	v_cvt_pk_bf16_f32 v69, v34, v35
	global_store_dwordx4 v[70:71], v[66:69], off offset:64 sc1
	s_cbranch_execz .LBB0_212
	s_branch .LBB0_213

; __device__ __forceinline__ unsigned cvt_pk_bf16(float lo, float hi) { unsigned r; asm volatile("v_cvt_pk_bf16_f32 %0, %1, %2" : "=v"(r) : "v"(lo), "v"(hi)); return r; }
;     __device__ __forceinline__ void operator()(const f32x4 (&acc)[2][2][4][2], const State& st, const Unit& u, int wr, int wc, int fr, int fq) const {
;     ...
;                 } else {
;                 bf16_t* rowp = O + (size_t)row * ldc + col0;
; #pragma unroll
;                 for (int bj = 0; bj < 2; ++bj) { u32x4 w; w.x = cvt_pk_bf16(v[bj][0][0], v[bj][0][1]); w.y = cvt_pk_bf16(v[bj][0][2], v[bj][0][3]); w.z = cvt_pk_bf16(v[bj][1][0], v[bj][1][1]); w.w = cvt_pk_bf16(v[bj][1][2], v[bj][1][3]);
;                     *(u32x4*)(rowp + 32 * bj) = w; } } }
.LBB0_230:
	v_mov_b64_e32 v[34:35], s[18:19]
	v_mad_i64_i32 v[34:35], s[0:1], v32, s70, v[34:35]
	v_lshl_add_u64 v[38:39], v[128:129], 1, v[34:35]
	v_cvt_pk_bf16_f32 v34, v28, v29
	v_cvt_pk_bf16_f32 v35, v30, v31
	v_cvt_pk_bf16_f32 v36, v24, v25
	v_cvt_pk_bf16_f32 v37, v26, v27
	global_store_dwordx4 v[38:39], v[34:37], off sc1
	s_nop 1
	v_cvt_pk_bf16_f32 v34, v20, v21
	v_cvt_pk_bf16_f32 v35, v22, v23
	v_cvt_pk_bf16_f32 v36, v16, v17
	v_cvt_pk_bf16_f32 v37, v18, v19
	global_store_dwordx4 v[38:39], v[34:37], off offset:64 sc1
	s_cbranch_execz .LBB0_216
	s_branch .LBB0_217

; __device__ __forceinline__ unsigned cvt_pk_bf16(float lo, float hi) { unsigned r; asm volatile("v_cvt_pk_bf16_f32 %0, %1, %2" : "=v"(r) : "v"(lo), "v"(hi)); return r; }
;     __device__ __forceinline__ void operator()(const f32x4 (&acc)[2][2][4][2], const State& st, const Unit& u, int wr, int wc, int fr, int fq) const {
;     ...
;                 } else {
;                 bf16_t* rowp = O + (size_t)row * ldc + col0;
; #pragma unroll
;                 for (int bj = 0; bj < 2; ++bj) { u32x4 w; w.x = cvt_pk_bf16(v[bj][0][0], v[bj][0][1]); w.y = cvt_pk_bf16(v[bj][0][2], v[bj][0][3]); w.z = cvt_pk_bf16(v[bj][1][0], v[bj][1][1]); w.w = cvt_pk_bf16(v[bj][1][2], v[bj][1][3]);
;                     *(u32x4*)(rowp + 32 * bj) = w; } } }
.LBB0_232:
	v_mov_b64_e32 v[18:19], s[18:19]
	v_mad_i64_i32 v[18:19], s[0:1], v16, s70, v[18:19]
	v_lshl_add_u64 v[22:23], v[128:129], 1, v[18:19]
	v_cvt_pk_bf16_f32 v18, v12, v13
	v_cvt_pk_bf16_f32 v19, v14, v15
	v_cvt_pk_bf16_f32 v20, v8, v9
	v_cvt_pk_bf16_f32 v21, v10, v11
	global_store_dwordx4 v[22:23], v[18:21], off sc1
	s_nop 1
	v_cvt_pk_bf16_f32 v18, v4, v5
	v_cvt_pk_bf16_f32 v19, v6, v7
	v_cvt_pk_bf16_f32 v20, v0, v1
	v_cvt_pk_bf16_f32 v21, v2, v3
	global_store_dwordx4 v[22:23], v[18:21], off offset:64 sc1
	s_cbranch_execz .LBB0_220

; #define SBAR() __builtin_amdgcn_sched_barrier(0)
; __device__ __forceinline__ void qkt(f32x16& p0, f32x16& p1, const char* Ks, const bf16x8* qr, int r32, int hi, int m, const f32x16& cinit) {
;   bf16x8 kf[8];
; #pragma unroll
;   for (int d0 = 0; d0 < 4; ++d0) { const int cb = (m * 64 + d0 * 16 + hi * 8) * 2;
;     kf[2 * d0] = *reinterpret_cast<const bf16x8*>(Ks + KSWZ(r32, cb)); kf[2 * d0 + 1] = *reinterpret_cast<const bf16x8*>(Ks + KSWZ(32 + r32, cb)); }
;   SBAR();
;   p0 = __builtin_amdgcn_mfma_f32_32x32x16_bf16(kf[0], qr[0], cinit, 0, 0, 0);
;   p1 = __builtin_amdgcn_mfma_f32_32x32x16_bf16(kf[1], qr[0], cinit, 0, 0, 0);
; #pragma unroll
;   for (int d0 = 1; d0 < 4; ++d0) {
;     p0 = __builtin_amdgcn_mfma_f32_32x32x16_bf16(kf[2 * d0], qr[d0], p0, 0, 0, 0);
;     p1 = __builtin_amdgcn_mfma_f32_32x32x16_bf16(kf[2 * d0 + 1], qr[d0], p1, 0, 0, 0); }
;   SBAR();
; }
; __device__ __forceinline__ void bias_mask(f32x16& p0, f32x16& p1, const float* bt, int base) {
; #pragma unroll
;   for (int r = 0; r < 16; ++r) { const int c = (r & 3) + 8 * (r >> 2); p0[r] += bt[base - c]; }
;   SBAR();
; #pragma unroll
;   for (int r = 0; r < 16; ++r) { const int c = (r & 3) + 8 * (r >> 2); p1[r] += bt[base - c - 32]; }
; }
.LBB0_316:
	s_cmp_ge_i32 s39, s29
	s_mov_b64 s[8:9], -1
	s_cbranch_scc0 .LBB0_318
	s_add_i32 s8, s59, 0
	v_add_u32_e32 v80, s8, v171
	v_add_u32_e32 v85, v80, v175
	v_add_u32_e32 v87, v80, v174
	v_add_u32_e32 v89, v80, v173
	v_add_u32_e32 v91, v80, v172
	v_add3_u32 v80, s8, v172, v171
	v_add3_u32 v86, s8, v175, v171
	v_add3_u32 v88, s8, v174, v171
	v_add3_u32 v90, s8, v173, v171
	ds_read_b128 v[80:83], v80
	ds_read_b128 v[96:99], v91 offset:8192
	ds_read_b128 v[198:201], v90
	ds_read_b128 v[202:205], v89 offset:8192
	ds_read_b128 v[206:209], v88
	ds_read_b128 v[210:213], v87 offset:8192
	ds_read_b128 v[214:217], v86
	ds_read_b128 v[218:221], v85 offset:8192
	v_add_u32_e32 v230, s44, v178
	v_add_u32_e32 v230, 0x18914, v230
	s_waitcnt lgkmcnt(0)
	v_mfma_f32_32x32x16_bf16 v[80:95], v[80:83], v[112:115], 0
	v_mfma_f32_32x32x16_bf16 v[96:111], v[96:99], v[112:115], 0
	v_mfma_f32_32x32x16_bf16 v[80:95], v[198:201], v[116:119], v[80:95]
	v_mfma_f32_32x32x16_bf16 v[96:111], v[202:205], v[116:119], v[96:111]
	v_mfma_f32_32x32x16_bf16 v[80:95], v[206:209], v[120:123], v[80:95]
	v_mfma_f32_32x32x16_bf16 v[96:111], v[210:213], v[120:123], v[96:111]
	v_mfma_f32_32x32x16_bf16 v[80:95], v[214:217], v[124:127], v[80:95]
	v_mfma_f32_32x32x16_bf16 v[96:111], v[218:221], v[124:127], v[96:111]
	ds_read2_b32 v[198:199], v230 offset0:58 offset1:59
	ds_read2_b32 v[200:201], v230 offset0:56 offset1:57
	ds_read2_b32 v[202:203], v230 offset0:50 offset1:51
	ds_read2_b32 v[204:205], v230 offset0:48 offset1:49
	ds_read2_b32 v[206:207], v230 offset0:42 offset1:43
	ds_read2_b32 v[208:209], v230 offset0:40 offset1:41
	ds_read2_b32 v[210:211], v230 offset0:34 offset1:35
	ds_read2_b32 v[212:213], v230 offset0:32 offset1:33
	ds_read2_b32 v[214:215], v230 offset0:26 offset1:27
	ds_read2_b32 v[216:217], v230 offset0:24 offset1:25
	ds_read2_b32 v[218:219], v230 offset0:18 offset1:19
	ds_read2_b32 v[220:221], v230 offset0:16 offset1:17
	ds_read2_b32 v[222:223], v230 offset0:10 offset1:11
	ds_read2_b32 v[224:225], v230 offset0:8 offset1:9
	ds_read2_b32 v[226:227], v230 offset0:2 offset1:3
	ds_read2_b32 v[228:229], v230 offset0:0 offset1:1
	s_mov_b64 s[8:9], 0
	s_waitcnt lgkmcnt(0)
	v_add_f32_e32 v80, v80, v199
	v_add_f32_e32 v81, v81, v198
	v_pk_add_f32 v[82:83], v[82:83], v[200:201] op_sel:[0,1] op_sel_hi:[1,0]
	v_pk_add_f32 v[84:85], v[84:85], v[202:203] op_sel:[0,1] op_sel_hi:[1,0]
	v_pk_add_f32 v[86:87], v[86:87], v[204:205] op_sel:[0,1] op_sel_hi:[1,0]
	v_pk_add_f32 v[88:89], v[88:89], v[206:207] op_sel:[0,1] op_sel_hi:[1,0]
	v_pk_add_f32 v[90:91], v[90:91], v[208:209] op_sel:[0,1] op_sel_hi:[1,0]
	v_pk_add_f32 v[92:93], v[92:93], v[210:211] op_sel:[0,1] op_sel_hi:[1,0]
	v_pk_add_f32 v[94:95], v[94:95], v[212:213] op_sel:[0,1] op_sel_hi:[1,0]
	v_pk_add_f32 v[96:97], v[96:97], v[214:215] op_sel:[0,1] op_sel_hi:[1,0]
	v_pk_add_f32 v[98:99], v[98:99], v[216:217] op_sel:[0,1] op_sel_hi:[1,0]
	v_pk_add_f32 v[100:101], v[100:101], v[218:219] op_sel:[0,1] op_sel_hi:[1,0]
	v_pk_add_f32 v[102:103], v[102:103], v[220:221] op_sel:[0,1] op_sel_hi:[1,0]
	v_pk_add_f32 v[104:105], v[104:105], v[222:223] op_sel:[0,1] op_sel_hi:[1,0]
	v_pk_add_f32 v[106:107], v[106:107], v[224:225] op_sel:[0,1] op_sel_hi:[1,0]
	v_pk_add_f32 v[108:109], v[108:109], v[226:227] op_sel:[0,1] op_sel_hi:[1,0]
	v_pk_add_f32 v[110:111], v[110:111], v[228:229] op_sel:[0,1] op_sel_hi:[1,0]

; #define SBAR() __builtin_amdgcn_sched_barrier(0)
; __device__ __forceinline__ void finishSM(f32x16& p0, f32x16& p1, float alpha, float& l_reg, bf16x8& pa0, bf16x8& pa1, bf16x8& pa2, bf16x8& pa3) {
; #pragma unroll
;   for (int r = 0; r < 16; ++r) p1[r] = __builtin_amdgcn_exp2f(p1[r]);
;   float ps = 0;
; #pragma unroll
;   for (int r = 0; r < 16; ++r) ps += p0[r];
; #pragma unroll
;   for (int r = 0; r < 16; ++r) ps += p1[r];
;   { auto rr = __builtin_amdgcn_permlane32_swap(__float_as_uint(ps), __float_as_uint(ps), false, false);
;     ps = __uint_as_float(rr[0]) + __uint_as_float(rr[1]); }
;   l_reg = l_reg * alpha + ps;
;     ...
;   PK4(p0, 0, pa0); PK4(p0, 8, pa1); PK4(p1, 0, pa2); PK4(p1, 8, pa3);
;     ...
; }
; __device__ __forceinline__ void pv_slice(f32x16* o, const VFrag& f, bf16x8 pa) {
; #pragma unroll
;   for (int d0 = 0; d0 < 4; ++d0) { const bf16x8 vf = (bf16x8){f.lo[d0][0], f.lo[d0][1], f.lo[d0][2], f.lo[d0][3], f.hi[d0][0], f.hi[d0][1], f.hi[d0][2], f.hi[d0][3]};
;     o[d0] = __builtin_amdgcn_mfma_f32_32x32x16_bf16(pa, vf, o[d0], 0, 0, 0); }
; }
; __device__ __forceinline__ void pv_all(f32x16* o, lds_cptr vp, bf16x8 pa0, bf16x8 pa1, bf16x8 pa2, bf16x8 pa3) {
;   VFrag fa, fb;
;   v_read<0>(fa, vp); v_read<1>(fb, vp); SBAR();
;   pv_slice(o, fa, pa0); SBAR(); v_read<2>(fa, vp); SBAR();
;   pv_slice(o, fb, pa1); SBAR(); v_read<3>(fb, vp); SBAR();
;   pv_slice(o, fa, pa2); SBAR();
;   pv_slice(o, fb, pa3); SBAR();
; }
.LBB0_320:
	v_add_u32_e32 v244, s59, v170
	ds_read_b64_tr_b16 v[232:233], v244 offset:16384
	ds_read_b64_tr_b16 v[236:237], v244 offset:16896
	ds_read_b64_tr_b16 v[240:241], v244 offset:17408
	ds_read_b64_tr_b16 v[198:199], v244 offset:17920
	ds_read_b64_tr_b16 v[234:235], v244 offset:18432
	ds_read_b64_tr_b16 v[238:239], v244 offset:18944
	ds_read_b64_tr_b16 v[242:243], v244 offset:19456
	ds_read_b64_tr_b16 v[200:201], v244 offset:19968
	ds_read_b64_tr_b16 v[202:203], v244 offset:20480
	ds_read_b64_tr_b16 v[206:207], v244 offset:20992
	ds_read_b64_tr_b16 v[210:211], v244 offset:21504
	ds_read_b64_tr_b16 v[214:215], v244 offset:22016
	ds_read_b64_tr_b16 v[204:205], v244 offset:22528
	ds_read_b64_tr_b16 v[208:209], v244 offset:23040
	ds_read_b64_tr_b16 v[212:213], v244 offset:23552
	ds_read_b64_tr_b16 v[216:217], v244 offset:24064
	s_nop 1
	v_exp_f32_e32 v179, v80
	v_exp_f32_e32 v180, v81
	v_exp_f32_e32 v181, v82
	v_exp_f32_e32 v83, v83
	v_add_f32_e32 v80, 0, v179
	v_exp_f32_e32 v84, v84
	v_add_f32_e32 v80, v180, v80
	v_exp_f32_e32 v85, v85
	v_add_f32_e32 v80, v181, v80
	v_exp_f32_e32 v86, v86
	v_add_f32_e32 v80, v83, v80
	v_exp_f32_e32 v87, v87
	v_add_f32_e32 v80, v84, v80
	v_add_f32_e32 v80, v85, v80
	v_add_f32_e32 v80, v86, v80
	v_add_f32_e32 v80, v87, v80
	v_cvt_pk_bf16_f32 v82, v179, v180
	v_cvt_pk_bf16_f32 v83, v181, v83
	v_cvt_pk_bf16_f32 v84, v84, v85
	v_cvt_pk_bf16_f32 v85, v86, v87
	ds_read_b64_tr_b16 v[246:247], v244 offset:24576
	ds_read_b64_tr_b16 v[218:219], v244 offset:25088
	ds_read_b64_tr_b16 v[222:223], v244 offset:25600
	ds_read_b64_tr_b16 v[250:251], v244 offset:26112
	ds_read_b64_tr_b16 v[248:249], v244 offset:26624
	ds_read_b64_tr_b16 v[220:221], v244 offset:27136
	ds_read_b64_tr_b16 v[224:225], v244 offset:27648
	ds_read_b64_tr_b16 v[252:253], v244 offset:28160
	v_permlane32_swap_b32_e32 v82, v84
	v_permlane32_swap_b32_e32 v83, v85
	s_waitcnt lgkmcnt(8)
	v_exp_f32_e32 v88, v88
	v_mfma_f32_32x32x16_bf16 v[0:15], v[82:85], v[232:235], v[0:15]
	v_exp_f32_e32 v89, v89
	v_exp_f32_e32 v90, v90
	v_add_f32_e32 v80, v88, v80
	v_exp_f32_e32 v91, v91
	v_add_f32_e32 v80, v89, v80
	v_mfma_f32_32x32x16_bf16 v[16:31], v[82:85], v[236:239], v[16:31]
	v_exp_f32_e32 v92, v92
	v_add_f32_e32 v80, v90, v80
	v_exp_f32_e32 v93, v93
	v_add_f32_e32 v80, v91, v80
	v_exp_f32_e32 v94, v94
	v_add_f32_e32 v80, v92, v80
	v_mfma_f32_32x32x16_bf16 v[32:47], v[82:85], v[240:243], v[32:47]
	v_exp_f32_e32 v95, v95
	v_add_f32_e32 v80, v93, v80
	v_add_f32_e32 v80, v94, v80
	v_add_f32_e32 v80, v95, v80
	v_cvt_pk_bf16_f32 v86, v88, v89
	v_cvt_pk_bf16_f32 v87, v90, v91
	v_mfma_f32_32x32x16_bf16 v[48:63], v[82:85], v[198:201], v[48:63]
	v_cvt_pk_bf16_f32 v88, v92, v93
	v_cvt_pk_bf16_f32 v89, v94, v95
	s_nop 0
	v_permlane32_swap_b32_e32 v86, v88
	v_permlane32_swap_b32_e32 v87, v89
	v_exp_f32_e32 v96, v96
	v_exp_f32_e32 v97, v97
	v_mfma_f32_32x32x16_bf16 v[0:15], v[86:89], v[202:205], v[0:15]
	v_exp_f32_e32 v98, v98
	v_add_f32_e32 v80, v96, v80
	v_exp_f32_e32 v99, v99
	v_add_f32_e32 v80, v97, v80
	v_exp_f32_e32 v100, v100
	v_add_f32_e32 v80, v98, v80
	v_mfma_f32_32x32x16_bf16 v[16:31], v[86:89], v[206:209], v[16:31]
	v_exp_f32_e32 v101, v101
	v_add_f32_e32 v80, v99, v80
	v_exp_f32_e32 v102, v102
	v_add_f32_e32 v80, v100, v80
	v_exp_f32_e32 v103, v103
	v_add_f32_e32 v80, v101, v80
	v_mfma_f32_32x32x16_bf16 v[32:47], v[86:89], v[210:213], v[32:47]
	v_add_f32_e32 v80, v102, v80
	v_add_f32_e32 v80, v103, v80
	v_cvt_pk_bf16_f32 v90, v96, v97
	v_cvt_pk_bf16_f32 v91, v98, v99
	v_cvt_pk_bf16_f32 v92, v100, v101
	v_mfma_f32_32x32x16_bf16 v[48:63], v[86:89], v[214:217], v[48:63]
	v_cvt_pk_bf16_f32 v93, v102, v103
	ds_read_b64_tr_b16 v[86:87], v244 offset:28672
	ds_read_b64_tr_b16 v[198:199], v244 offset:29184
	ds_read_b64_tr_b16 v[202:203], v244 offset:29696
	ds_read_b64_tr_b16 v[206:207], v244 offset:30208
	ds_read_b64_tr_b16 v[88:89], v244 offset:30720
	ds_read_b64_tr_b16 v[200:201], v244 offset:31232
	ds_read_b64_tr_b16 v[204:205], v244 offset:31744
	ds_read_b64_tr_b16 v[208:209], v244 offset:32256
	v_permlane32_swap_b32_e32 v90, v92
	v_permlane32_swap_b32_e32 v91, v93
	s_waitcnt lgkmcnt(8)
	v_exp_f32_e32 v104, v104
	v_exp_f32_e32 v105, v105
	v_mfma_f32_32x32x16_bf16 v[0:15], v[90:93], v[246:249], v[0:15]
	v_exp_f32_e32 v106, v106
	v_add_f32_e32 v80, v104, v80
	v_exp_f32_e32 v107, v107
	v_add_f32_e32 v80, v105, v80
	v_exp_f32_e32 v108, v108
	v_add_f32_e32 v80, v106, v80
	v_mfma_f32_32x32x16_bf16 v[16:31], v[90:93], v[218:221], v[16:31]
	v_exp_f32_e32 v109, v109
	v_add_f32_e32 v80, v107, v80
	v_exp_f32_e32 v110, v110
	v_add_f32_e32 v80, v108, v80
	v_exp_f32_e32 v111, v111
	v_add_f32_e32 v80, v109, v80
	v_mfma_f32_32x32x16_bf16 v[32:47], v[90:93], v[222:225], v[32:47]
	v_add_f32_e32 v80, v110, v80
	v_add_f32_e32 v80, v111, v80
	v_cvt_pk_bf16_f32 v94, v104, v105
	v_cvt_pk_bf16_f32 v95, v106, v107
	v_cvt_pk_bf16_f32 v96, v108, v109
	v_mfma_f32_32x32x16_bf16 v[48:63], v[90:93], v[250:253], v[48:63]
	v_cvt_pk_bf16_f32 v97, v110, v111
	v_mov_b32_e32 v81, v80
	s_nop 0
	v_permlane32_swap_b32_e32 v94, v96
	v_permlane32_swap_b32_e32 v95, v97
	s_waitcnt lgkmcnt(0)
	v_permlane32_swap_b32_e32 v80, v81
	v_mfma_f32_32x32x16_bf16 v[0:15], v[94:97], v[86:89], v[0:15]
	v_mfma_f32_32x32x16_bf16 v[16:31], v[94:97], v[198:201], v[16:31]
	v_mfma_f32_32x32x16_bf16 v[32:47], v[94:97], v[202:205], v[32:47]
	v_mfma_f32_32x32x16_bf16 v[48:63], v[94:97], v[206:209], v[48:63]
	s_mov_b64 s[8:9], -1
	s_and_b64 vcc, exec, s[6:7]
	s_cbranch_vccz .LBB0_322
	s_waitcnt vmcnt(0) lgkmcnt(0)
	s_barrier
	s_mov_b64 s[8:9], 0

; #define PG8_STAGE(bufoff, gbase, voff) do { _Pragma("unroll") for (int _i = 0; _i < 2; ++_i) \
;         __builtin_amdgcn_global_load_lds((const unsigned*)((const char*)(gbase) + (voff)[_i]), (PG8_LAS unsigned*)(lds + (bufoff) + ldsw + _i * 8192), 16, 0, 0); } while (0)
; #define PG8_LDA(dst, b, h) do { _Pragma("unroll") for (int m = 0; m < 4; ++m) _Pragma("unroll") for (int k = 0; k < 2; ++k) dst[m][k] = *(const PG8_LAS bf16x8*)(lds + PG8_SA(b, h) + aoff + m * 2048 + k * 1024); } while (0)
; #define PG8_LDB(dst, b, h) do { _Pragma("unroll") for (int n = 0; n < 2; ++n) _Pragma("unroll") for (int k = 0; k < 2; ++k) dst[n][k] = *(const PG8_LAS bf16x8*)(lds + PG8_SB(b, h) + boff + n * 2048 + k * 1024); } while (0)
; #define PG8_MMA(ai, bj, At, Bt) do { __builtin_amdgcn_s_setprio(1); _Pragma("unroll") for (int m = 0; m < 4; ++m) _Pragma("unroll") for (int n = 0; n < 2; ++n) _Pragma("unroll") for (int k = 0; k < 2; ++k) \
;         acc[ai][bj][m][n] = __builtin_amdgcn_mfma_f32_16x16x32_bf16(Bt[n][k], At[m][k], acc[ai][bj][m][n], 0, 0, 0); __builtin_amdgcn_s_setprio(0); } while (0)
; #define PG8_WAIT_V(n) asm volatile("s_waitcnt vmcnt(" #n ")" ::: "memory")
; template <class Epi, class Sched, bool ALIGN_EPI = false, bool SP2 = false>
; __device__ __forceinline__ void gemm_phase(PG8_LAS unsigned char* lds, const Gemm g, const Sched& S, const Epi& E) {
;     ...
;             PG8_LDB(B0, 0, 0); PG8_LDB(B1, 0, 1); PG8_SCHED; PG8_LDA(At, 0, 0); PG8_STAGE(PG8_SA(1, 1), a1 + hstepA, voffA);
;             PG8_WAIT_V(8); PG8_WAIT_L(0); PG8_BAR; PG8_MMA(0, 0, At, B0); PG8_MMA(0, 1, At, B1); PG8_BAR; PG8_SCHED;
;             PG8_LDA(At, 0, 1); PG8_STAGE(PG8_SB(0, 0), b2, voffB); PG8_STAGE(PG8_SB(0, 1), b2 + hstepB, voffB); PG8_STAGE(PG8_SA(0, 0), a2, voffA);
;             PG8_WAIT_V(8); PG8_WAIT_L(0); PG8_BAR; PG8_MMA(1, 0, At, B0); PG8_MMA(1, 1, At, B1); PG8_BAR; PG8_SCHED;
;             PG8_LDB(B0, 1, 0); PG8_LDB(B1, 1, 1); PG8_SCHED; PG8_LDA(At, 1, 0); PG8_STAGE(PG8_SA(0, 1), a2 + hstepA, voffA);
;             PG8_WAIT_V(8); PG8_WAIT_L(0); PG8_BAR; PG8_MMA(0, 0, At, B0); PG8_MMA(0, 1, At, B1); PG8_BAR; PG8_SCHED;
;             PG8_LDA(At, 1, 1); PG8_STAGE(PG8_SB(1, 0), b3, voffB); PG8_STAGE(PG8_SB(1, 1), b3 + hstepB, voffB); PG8_STAGE(PG8_SA(1, 0), a3, voffA);
;             PG8_WAIT_V(8); PG8_WAIT_L(0); PG8_BAR; PG8_MMA(1, 0, At, B0); PG8_MMA(1, 1, At, B1); PG8_BAR; PG8_SCHED;
.LBB0_458:
	s_add_u32 s6, s0, 0xfff80080
	s_addc_u32 s7, s1, -1
	s_add_i32 s41, 0, 0x10000
	s_cmp_eq_u32 s40, 28
	s_cselect_b32 s9, s25, s7
	s_cselect_b32 s8, s26, s6
	v_add_u32_e32 v144, s41, v166
	s_cselect_b32 s7, s27, s23
	s_cselect_b32 s6, s31, s22
	s_add_i32 s43, 0, 0x14000
	ds_read_b128 v[140:143], v144
	ds_read_b128 v[160:163], v144 offset:1024
	ds_read_b128 v[170:173], v144 offset:2048
	ds_read_b128 v[198:201], v144 offset:3072
	v_add_u32_e32 v144, s43, v166
	ds_read_b128 v[202:205], v144
	ds_read_b128 v[206:209], v144 offset:1024
	ds_read_b128 v[210:213], v144 offset:2048
	ds_read_b128 v[214:217], v144 offset:3072
	v_lshl_add_u64 v[174:175], s[0:1], 0, v[136:137]
	s_add_i32 m0, s53, 0xc000
	ds_read_b128 v[218:221], v168
	ds_read_b128 v[222:225], v168 offset:1024
	ds_read_b128 v[226:229], v168 offset:2048
	ds_read_b128 v[230:233], v168 offset:3072
	ds_read_b128 v[234:237], v168 offset:4096
	ds_read_b128 v[238:241], v168 offset:5120
	ds_read_b128 v[242:245], v168 offset:6144
	ds_read_b128 v[246:249], v168 offset:7168
	global_load_lds_dwordx4 v[174:175], off
	v_lshl_add_u64 v[174:175], s[0:1], 0, v[138:139]
	s_add_i32 m0, s53, 0xe000
	s_nop 0
	global_load_lds_dwordx4 v[174:175], off
	s_waitcnt vmcnt(8)
	s_waitcnt lgkmcnt(0)
	s_barrier
	s_setprio 1
	s_waitcnt lgkmcnt(0)
	v_mfma_f32_16x16x32_bf16 v[8:11], v[140:143], v[218:221], v[8:11]
	v_mfma_f32_16x16x32_bf16 v[12:15], v[170:173], v[218:221], v[12:15]
	v_mfma_f32_16x16x32_bf16 v[4:7], v[140:143], v[226:229], v[4:7]
	v_mfma_f32_16x16x32_bf16 v[0:3], v[170:173], v[226:229], v[0:3]
	v_mfma_f32_16x16x32_bf16 v[16:19], v[140:143], v[234:237], v[16:19]
	v_mfma_f32_16x16x32_bf16 v[36:39], v[170:173], v[234:237], v[36:39]
	v_mfma_f32_16x16x32_bf16 v[44:47], v[140:143], v[242:245], v[44:47]
	v_mfma_f32_16x16x32_bf16 v[40:43], v[170:173], v[242:245], v[40:43]
	v_mfma_f32_16x16x32_bf16 v[8:11], v[160:163], v[222:225], v[8:11]
	v_mfma_f32_16x16x32_bf16 v[12:15], v[198:201], v[222:225], v[12:15]
	v_mfma_f32_16x16x32_bf16 v[4:7], v[160:163], v[230:233], v[4:7]
	v_mfma_f32_16x16x32_bf16 v[0:3], v[198:201], v[230:233], v[0:3]
	v_mfma_f32_16x16x32_bf16 v[16:19], v[160:163], v[238:241], v[16:19]
	v_mfma_f32_16x16x32_bf16 v[36:39], v[198:201], v[238:241], v[36:39]
	v_mfma_f32_16x16x32_bf16 v[44:47], v[160:163], v[246:249], v[44:47]
	v_mfma_f32_16x16x32_bf16 v[40:43], v[198:201], v[246:249], v[40:43]
	s_setprio 0
	s_setprio 1
	v_mfma_f32_16x16x32_bf16 v[28:31], v[202:205], v[218:221], v[28:31]
	v_mfma_f32_16x16x32_bf16 v[32:35], v[210:213], v[218:221], v[32:35]
	v_mfma_f32_16x16x32_bf16 v[20:23], v[202:205], v[226:229], v[20:23]
	v_mfma_f32_16x16x32_bf16 v[24:27], v[210:213], v[226:229], v[24:27]
	v_mfma_f32_16x16x32_bf16 v[48:51], v[202:205], v[234:237], v[48:51]
	v_mfma_f32_16x16x32_bf16 v[56:59], v[210:213], v[234:237], v[56:59]
	v_mfma_f32_16x16x32_bf16 v[52:55], v[202:205], v[242:245], v[52:55]
	v_mfma_f32_16x16x32_bf16 v[76:79], v[210:213], v[242:245], v[76:79]
	v_mfma_f32_16x16x32_bf16 v[28:31], v[206:209], v[222:225], v[28:31]
	v_mfma_f32_16x16x32_bf16 v[32:35], v[214:217], v[222:225], v[32:35]
	v_mfma_f32_16x16x32_bf16 v[20:23], v[206:209], v[230:233], v[20:23]
	v_mfma_f32_16x16x32_bf16 v[24:27], v[214:217], v[230:233], v[24:27]
	v_mfma_f32_16x16x32_bf16 v[48:51], v[206:209], v[238:241], v[48:51]
	v_mfma_f32_16x16x32_bf16 v[56:59], v[214:217], v[238:241], v[56:59]
	v_mfma_f32_16x16x32_bf16 v[52:55], v[206:209], v[246:249], v[52:55]
	v_mfma_f32_16x16x32_bf16 v[76:79], v[214:217], v[246:249], v[76:79]
	s_setprio 0
	s_barrier
	s_add_i32 s41, s41, s44
	v_lshl_add_u64 v[174:175], s[6:7], 0, v[130:131]
	s_mov_b32 m0, s41
	ds_read_b128 v[218:221], v168 offset:16384
	ds_read_b128 v[222:225], v168 offset:17408
	ds_read_b128 v[226:229], v168 offset:18432
	ds_read_b128 v[230:233], v168 offset:19456
	ds_read_b128 v[234:237], v168 offset:20480
	ds_read_b128 v[238:241], v168 offset:21504
	ds_read_b128 v[242:245], v168 offset:22528
	ds_read_b128 v[246:249], v168 offset:23552
	global_load_lds_dwordx4 v[174:175], off
	s_add_i32 m0, s41, 0x2000
	s_add_u32 s60, s6, 0x4000
	v_lshl_add_u64 v[174:175], s[6:7], 0, v[134:135]
	s_addc_u32 s61, s7, 0
	s_add_i32 s41, s43, s44
	global_load_lds_dwordx4 v[174:175], off
	v_lshl_add_u64 v[174:175], s[60:61], 0, v[130:131]
	s_mov_b32 m0, s41
	v_lshl_add_u64 v[178:179], s[8:9], 0, v[132:133]
	global_load_lds_dwordx4 v[174:175], off
	v_lshl_add_u64 v[174:175], s[60:61], 0, v[134:135]
	s_add_i32 m0, s41, 0x2000
	s_nop 0
	global_load_lds_dwordx4 v[174:175], off
	v_lshl_add_u64 v[174:175], s[8:9], 0, v[128:129]
	s_mov_b32 m0, s53
	s_nop 0
	global_load_lds_dwordx4 v[174:175], off
	s_mov_b32 m0, s54
	s_nop 0
	global_load_lds_dwordx4 v[178:179], off
	s_waitcnt vmcnt(8)
	s_waitcnt lgkmcnt(0)
	s_barrier
; #define PG8_STAGE(bufoff, gbase, voff) do { _Pragma("unroll") for (int _i = 0; _i < 2; ++_i) \
;         __builtin_amdgcn_global_load_lds((const unsigned*)((const char*)(gbase) + (voff)[_i]), (PG8_LAS unsigned*)(lds + (bufoff) + ldsw + _i * 8192), 16, 0, 0); } while (0)
; #define PG8_LDA(dst, b, h) do { _Pragma("unroll") for (int m = 0; m < 4; ++m) _Pragma("unroll") for (int k = 0; k < 2; ++k) dst[m][k] = *(const PG8_LAS bf16x8*)(lds + PG8_SA(b, h) + aoff + m * 2048 + k * 1024); } while (0)
; #define PG8_LDB(dst, b, h) do { _Pragma("unroll") for (int n = 0; n < 2; ++n) _Pragma("unroll") for (int k = 0; k < 2; ++k) dst[n][k] = *(const PG8_LAS bf16x8*)(lds + PG8_SB(b, h) + boff + n * 2048 + k * 1024); } while (0)
; #define PG8_MMA(ai, bj, At, Bt) do { __builtin_amdgcn_s_setprio(1); _Pragma("unroll") for (int m = 0; m < 4; ++m) _Pragma("unroll") for (int n = 0; n < 2; ++n) _Pragma("unroll") for (int k = 0; k < 2; ++k) \
;         acc[ai][bj][m][n] = __builtin_amdgcn_mfma_f32_16x16x32_bf16(Bt[n][k], At[m][k], acc[ai][bj][m][n], 0, 0, 0); __builtin_amdgcn_s_setprio(0); } while (0)
; #define PG8_WAIT_V(n) asm volatile("s_waitcnt vmcnt(" #n ")" ::: "memory")
; template <class Epi, class Sched, bool ALIGN_EPI = false, bool SP2 = false>
; __device__ __forceinline__ void gemm_phase(PG8_LAS unsigned char* lds, const Gemm g, const Sched& S, const Epi& E) {
;     ...
;             PG8_LDB(B0, 0, 0); PG8_LDB(B1, 0, 1); PG8_SCHED; PG8_LDA(At, 0, 0); PG8_STAGE(PG8_SA(1, 1), a1 + hstepA, voffA);
;             PG8_WAIT_V(8); PG8_WAIT_L(0); PG8_BAR; PG8_MMA(0, 0, At, B0); PG8_MMA(0, 1, At, B1); PG8_BAR; PG8_SCHED;
;             PG8_LDA(At, 0, 1); PG8_STAGE(PG8_SB(0, 0), b2, voffB); PG8_STAGE(PG8_SB(0, 1), b2 + hstepB, voffB); PG8_STAGE(PG8_SA(0, 0), a2, voffA);
;             PG8_WAIT_V(8); PG8_WAIT_L(0); PG8_BAR; PG8_MMA(1, 0, At, B0); PG8_MMA(1, 1, At, B1); PG8_BAR; PG8_SCHED;
;             PG8_LDB(B0, 1, 0); PG8_LDB(B1, 1, 1); PG8_SCHED; PG8_LDA(At, 1, 0); PG8_STAGE(PG8_SA(0, 1), a2 + hstepA, voffA);
;             PG8_WAIT_V(8); PG8_WAIT_L(0); PG8_BAR; PG8_MMA(0, 0, At, B0); PG8_MMA(0, 1, At, B1); PG8_BAR; PG8_SCHED;
;             PG8_LDA(At, 1, 1); PG8_STAGE(PG8_SB(1, 0), b3, voffB); PG8_STAGE(PG8_SB(1, 1), b3 + hstepB, voffB); PG8_STAGE(PG8_SA(1, 0), a3, voffA);
;             PG8_WAIT_V(8); PG8_WAIT_L(0); PG8_BAR; PG8_MMA(1, 0, At, B0); PG8_MMA(1, 1, At, B1); PG8_BAR; PG8_SCHED;
	s_setprio 1
	s_waitcnt lgkmcnt(0)
	v_mfma_f32_16x16x32_bf16 v[64:67], v[140:143], v[218:221], v[64:67]
	v_mfma_f32_16x16x32_bf16 v[84:87], v[170:173], v[218:221], v[84:87]
	v_mfma_f32_16x16x32_bf16 v[60:63], v[140:143], v[226:229], v[60:63]
	v_mfma_f32_16x16x32_bf16 v[80:83], v[170:173], v[226:229], v[80:83]
	v_mfma_f32_16x16x32_bf16 v[68:71], v[140:143], v[234:237], v[68:71]
	v_mfma_f32_16x16x32_bf16 v[88:91], v[170:173], v[234:237], v[88:91]
	v_mfma_f32_16x16x32_bf16 v[72:75], v[140:143], v[242:245], v[72:75]
	v_mfma_f32_16x16x32_bf16 v[92:95], v[170:173], v[242:245], v[92:95]
	v_mfma_f32_16x16x32_bf16 v[64:67], v[160:163], v[222:225], v[64:67]
	v_mfma_f32_16x16x32_bf16 v[84:87], v[198:201], v[222:225], v[84:87]
	v_mfma_f32_16x16x32_bf16 v[60:63], v[160:163], v[230:233], v[60:63]
	v_mfma_f32_16x16x32_bf16 v[80:83], v[198:201], v[230:233], v[80:83]
	v_mfma_f32_16x16x32_bf16 v[68:71], v[160:163], v[238:241], v[68:71]
	v_mfma_f32_16x16x32_bf16 v[88:91], v[198:201], v[238:241], v[88:91]
	v_mfma_f32_16x16x32_bf16 v[72:75], v[160:163], v[246:249], v[72:75]
	v_mfma_f32_16x16x32_bf16 v[92:95], v[198:201], v[246:249], v[92:95]
	s_setprio 0
	s_setprio 1
	v_mfma_f32_16x16x32_bf16 v[100:103], v[202:205], v[218:221], v[100:103]
	v_mfma_f32_16x16x32_bf16 v[120:123], v[210:213], v[218:221], v[120:123]
	v_mfma_f32_16x16x32_bf16 v[96:99], v[202:205], v[226:229], v[96:99]
	v_mfma_f32_16x16x32_bf16 v[112:115], v[210:213], v[226:229], v[112:115]
	v_mfma_f32_16x16x32_bf16 v[104:107], v[202:205], v[234:237], v[104:107]
	v_mfma_f32_16x16x32_bf16 v[116:119], v[210:213], v[234:237], v[116:119]
	v_mfma_f32_16x16x32_bf16 v[108:111], v[202:205], v[242:245], v[108:111]
	v_mfma_f32_16x16x32_bf16 v[124:127], v[210:213], v[242:245], v[124:127]
	v_mfma_f32_16x16x32_bf16 v[100:103], v[206:209], v[222:225], v[100:103]
	v_mfma_f32_16x16x32_bf16 v[120:123], v[214:217], v[222:225], v[120:123]
	v_mfma_f32_16x16x32_bf16 v[96:99], v[206:209], v[230:233], v[96:99]
	v_mfma_f32_16x16x32_bf16 v[112:115], v[214:217], v[230:233], v[112:115]
	v_mfma_f32_16x16x32_bf16 v[104:107], v[206:209], v[238:241], v[104:107]
	v_mfma_f32_16x16x32_bf16 v[116:119], v[214:217], v[238:241], v[116:119]
	v_mfma_f32_16x16x32_bf16 v[108:111], v[206:209], v[246:249], v[108:111]
	v_mfma_f32_16x16x32_bf16 v[124:127], v[214:217], v[246:249], v[124:127]
	s_setprio 0
	s_barrier
	s_add_i32 s41, 0, 0x18000
	v_add_u32_e32 v144, s41, v166
	s_add_i32 s43, 0, 0x1c000
	ds_read_b128 v[140:143], v144
	ds_read_b128 v[160:163], v144 offset:1024
	ds_read_b128 v[170:173], v144 offset:2048
	ds_read_b128 v[198:201], v144 offset:3072
	v_add_u32_e32 v144, s43, v166
	ds_read_b128 v[202:205], v144
	ds_read_b128 v[206:209], v144 offset:1024
	ds_read_b128 v[210:213], v144 offset:2048
	ds_read_b128 v[214:217], v144 offset:3072
	s_add_u32 s8, s8, 0x80000
	s_addc_u32 s9, s9, 0
	s_mov_b32 m0, s55
	v_lshl_add_u64 v[180:181], s[8:9], 0, v[128:129]
	ds_read_b128 v[218:221], v168 offset:32768
	ds_read_b128 v[222:225], v168 offset:33792
	ds_read_b128 v[226:229], v168 offset:34816
	ds_read_b128 v[230:233], v168 offset:35840
	ds_read_b128 v[234:237], v168 offset:36864
	ds_read_b128 v[238:241], v168 offset:37888
	ds_read_b128 v[242:245], v168 offset:38912
	ds_read_b128 v[246:249], v168 offset:39936
	global_load_lds_dwordx4 v[180:181], off
	v_lshl_add_u64 v[180:181], s[8:9], 0, v[132:133]
	s_mov_b32 m0, s66
	s_nop 0
	global_load_lds_dwordx4 v[180:181], off
	s_waitcnt vmcnt(8)
	s_waitcnt lgkmcnt(0)
	s_barrier
	s_setprio 1
	s_waitcnt lgkmcnt(0)
	v_mfma_f32_16x16x32_bf16 v[8:11], v[140:143], v[218:221], v[8:11]
	v_mfma_f32_16x16x32_bf16 v[12:15], v[170:173], v[218:221], v[12:15]
	v_mfma_f32_16x16x32_bf16 v[4:7], v[140:143], v[226:229], v[4:7]
	v_mfma_f32_16x16x32_bf16 v[0:3], v[170:173], v[226:229], v[0:3]
	v_mfma_f32_16x16x32_bf16 v[16:19], v[140:143], v[234:237], v[16:19]
	v_mfma_f32_16x16x32_bf16 v[36:39], v[170:173], v[234:237], v[36:39]
	v_mfma_f32_16x16x32_bf16 v[44:47], v[140:143], v[242:245], v[44:47]
	v_mfma_f32_16x16x32_bf16 v[40:43], v[170:173], v[242:245], v[40:43]
	v_mfma_f32_16x16x32_bf16 v[8:11], v[160:163], v[222:225], v[8:11]
	v_mfma_f32_16x16x32_bf16 v[12:15], v[198:201], v[222:225], v[12:15]
	v_mfma_f32_16x16x32_bf16 v[4:7], v[160:163], v[230:233], v[4:7]
	v_mfma_f32_16x16x32_bf16 v[0:3], v[198:201], v[230:233], v[0:3]
	v_mfma_f32_16x16x32_bf16 v[16:19], v[160:163], v[238:241], v[16:19]
	v_mfma_f32_16x16x32_bf16 v[36:39], v[198:201], v[238:241], v[36:39]
	v_mfma_f32_16x16x32_bf16 v[44:47], v[160:163], v[246:249], v[44:47]
	v_mfma_f32_16x16x32_bf16 v[40:43], v[198:201], v[246:249], v[40:43]
	s_setprio 0
	s_setprio 1
	v_mfma_f32_16x16x32_bf16 v[28:31], v[202:205], v[218:221], v[28:31]
	v_mfma_f32_16x16x32_bf16 v[32:35], v[210:213], v[218:221], v[32:35]
	v_mfma_f32_16x16x32_bf16 v[20:23], v[202:205], v[226:229], v[20:23]
	v_mfma_f32_16x16x32_bf16 v[24:27], v[210:213], v[226:229], v[24:27]
	v_mfma_f32_16x16x32_bf16 v[48:51], v[202:205], v[234:237], v[48:51]
	v_mfma_f32_16x16x32_bf16 v[56:59], v[210:213], v[234:237], v[56:59]
	v_mfma_f32_16x16x32_bf16 v[52:55], v[202:205], v[242:245], v[52:55]
	v_mfma_f32_16x16x32_bf16 v[76:79], v[210:213], v[242:245], v[76:79]
	v_mfma_f32_16x16x32_bf16 v[28:31], v[206:209], v[222:225], v[28:31]
	v_mfma_f32_16x16x32_bf16 v[32:35], v[214:217], v[222:225], v[32:35]
	v_mfma_f32_16x16x32_bf16 v[20:23], v[206:209], v[230:233], v[20:23]
	v_mfma_f32_16x16x32_bf16 v[24:27], v[214:217], v[230:233], v[24:27]
	v_mfma_f32_16x16x32_bf16 v[48:51], v[206:209], v[238:241], v[48:51]
	v_mfma_f32_16x16x32_bf16 v[56:59], v[214:217], v[238:241], v[56:59]
	v_mfma_f32_16x16x32_bf16 v[52:55], v[206:209], v[246:249], v[52:55]
	v_mfma_f32_16x16x32_bf16 v[76:79], v[214:217], v[246:249], v[76:79]
	s_setprio 0
	s_barrier
; #define PG8_WAIT_V(n) asm volatile("s_waitcnt vmcnt(" #n ")" ::: "memory")
;     __device__ __forceinline__ void operator()(const f32x4 (&acc)[2][2][4][2], const State&, const Unit& u, int wr, int wc, int fr, int fq) const {
;     ...
; #pragma unroll
;             for (int ai = 0; ai < 2; ++ai)
; #pragma unroll
;                 for (int m = 0; m < 4; ++m) { const int row = row0 + ai * HALF + m * 16; const size_t off = (size_t)row * ldc + col0; float ss = 0.f;
; #pragma unroll
;                     for (int bj = 0; bj < 2; ++bj) { const f32x4 v0 = acc[ai][bj][m][0], v1 = acc[ai][bj][m][1];
;                         u32x4 w; w.x = cvt_pk_bf16(v0[0], v0[1]); w.y = cvt_pk_bf16(v0[2], v0[3]); w.z = cvt_pk_bf16(v1[0], v1[1]); w.w = cvt_pk_bf16(v1[2], v1[3]);
;                         *(u32x4*)(xb + xb_off(row, col0 + bj * HALF)) = w;
;                         ss += ((v0[0] * v0[0] + v0[1] * v0[1]) + (v0[2] * v0[2] + v0[3] * v0[3])) + ((v1[0] * v1[0] + v1[1] * v1[1]) + (v1[2] * v1[2] + v1[3] * v1[3])); }
;                     ss += __shfl_xor(ss, 16); ss += __shfl_xor(ss, 32);
;                     if (fq == 0) ssq[(size_t)row * 32 + u.pn * 4 + wc] = ss; }
; template <class Epi, class Sched, bool ALIGN_EPI = false, bool SP2 = false>
; __device__ __forceinline__ void gemm_phase(PG8_LAS unsigned char* lds, const Gemm g, const Sched& S, const Epi& E) {
;     ...
;             PG8_LDB(B0, 0, 0); PG8_LDB(B1, 0, 1); PG8_SCHED; PG8_LDA(At, 0, 0); PG8_STAGE(PG8_SA(1, 1), a1 + hstepA, voffA);
;             PG8_WAIT_V(8); PG8_WAIT_L(0); PG8_BAR; PG8_MMA(0, 0, At, B0); PG8_MMA(0, 1, At, B1); PG8_BAR; PG8_SCHED;
;             PG8_LDA(At, 0, 1); PG8_STAGE(PG8_SB(0, 0), b2, voffB); PG8_STAGE(PG8_SB(0, 1), b2 + hstepB, voffB); PG8_STAGE(PG8_SA(0, 0), a2, voffA);
;             PG8_WAIT_V(8); PG8_WAIT_L(0); PG8_BAR; PG8_MMA(1, 0, At, B0); PG8_MMA(1, 1, At, B1); PG8_BAR; PG8_SCHED;
;             PG8_LDB(B0, 1, 0); PG8_LDB(B1, 1, 1); PG8_SCHED; PG8_LDA(At, 1, 0); PG8_STAGE(PG8_SA(0, 1), a2 + hstepA, voffA);
;             PG8_WAIT_V(8); PG8_WAIT_L(0); PG8_BAR; PG8_MMA(0, 0, At, B0); PG8_MMA(0, 1, At, B1); PG8_BAR; PG8_SCHED;
;             PG8_LDA(At, 1, 1); PG8_STAGE(PG8_SB(1, 0), b3, voffB); PG8_STAGE(PG8_SB(1, 1), b3 + hstepB, voffB); PG8_STAGE(PG8_SA(1, 0), a3, voffA);
;             PG8_WAIT_V(8); PG8_WAIT_L(0); PG8_BAR; PG8_MMA(1, 0, At, B0); PG8_MMA(1, 1, At, B1); PG8_BAR; PG8_SCHED;
	s_add_u32 s8, s6, 0x8000
	s_addc_u32 s9, s7, 0
	s_add_i32 s41, s41, s44
	v_lshl_add_u64 v[180:181], s[8:9], 0, v[130:131]
	s_mov_b32 m0, s41
	ds_read_b128 v[218:221], v168 offset:49152
	ds_read_b128 v[222:225], v168 offset:50176
	ds_read_b128 v[226:229], v168 offset:51200
	ds_read_b128 v[230:233], v168 offset:52224
	ds_read_b128 v[234:237], v168 offset:53248
	ds_read_b128 v[238:241], v168 offset:54272
	ds_read_b128 v[242:245], v168 offset:55296
	ds_read_b128 v[246:249], v168 offset:56320
	global_load_lds_dwordx4 v[180:181], off
	s_add_i32 m0, s41, 0x2000
	s_add_u32 s6, s6, 0xc000
	v_lshl_add_u64 v[180:181], s[8:9], 0, v[134:135]
	s_addc_u32 s7, s7, 0
	s_add_i32 s8, s43, s44
	global_load_lds_dwordx4 v[180:181], off
	v_lshl_add_u64 v[180:181], s[6:7], 0, v[130:131]
	s_mov_b32 m0, s8
	v_lshl_add_u64 v[174:175], v[174:175], 0, s[94:95]
	global_load_lds_dwordx4 v[180:181], off
	v_lshl_add_u64 v[180:181], s[6:7], 0, v[134:135]
	s_add_i32 m0, s8, 0x2000
	s_nop 0
	global_load_lds_dwordx4 v[180:181], off
	s_mov_b32 m0, s67
	s_nop 0
	global_load_lds_dwordx4 v[174:175], off
	v_lshl_add_u64 v[174:175], v[178:179], 0, s[94:95]
	s_mov_b32 m0, s68
	s_nop 0
	global_load_lds_dwordx4 v[174:175], off
	s_waitcnt vmcnt(8)
	s_waitcnt lgkmcnt(0)
	s_barrier
	s_setprio 1
	s_waitcnt lgkmcnt(0)
	v_mfma_f32_16x16x32_bf16 v[64:67], v[140:143], v[218:221], v[64:67]
	v_mfma_f32_16x16x32_bf16 v[84:87], v[170:173], v[218:221], v[84:87]
	v_mfma_f32_16x16x32_bf16 v[60:63], v[140:143], v[226:229], v[60:63]
	v_mfma_f32_16x16x32_bf16 v[80:83], v[170:173], v[226:229], v[80:83]
	v_mfma_f32_16x16x32_bf16 v[68:71], v[140:143], v[234:237], v[68:71]
	v_mfma_f32_16x16x32_bf16 v[88:91], v[170:173], v[234:237], v[88:91]
	v_mfma_f32_16x16x32_bf16 v[72:75], v[140:143], v[242:245], v[72:75]
	v_mfma_f32_16x16x32_bf16 v[92:95], v[170:173], v[242:245], v[92:95]
	v_mfma_f32_16x16x32_bf16 v[64:67], v[160:163], v[222:225], v[64:67]
	v_mfma_f32_16x16x32_bf16 v[84:87], v[198:201], v[222:225], v[84:87]
	v_mfma_f32_16x16x32_bf16 v[60:63], v[160:163], v[230:233], v[60:63]
	v_mfma_f32_16x16x32_bf16 v[80:83], v[198:201], v[230:233], v[80:83]
	v_mfma_f32_16x16x32_bf16 v[68:71], v[160:163], v[238:241], v[68:71]
	v_mfma_f32_16x16x32_bf16 v[88:91], v[198:201], v[238:241], v[88:91]
	v_mfma_f32_16x16x32_bf16 v[72:75], v[160:163], v[246:249], v[72:75]
	v_mfma_f32_16x16x32_bf16 v[92:95], v[198:201], v[246:249], v[92:95]
	s_setprio 0
	s_setprio 1
	v_mfma_f32_16x16x32_bf16 v[100:103], v[202:205], v[218:221], v[100:103]
	v_mfma_f32_16x16x32_bf16 v[120:123], v[210:213], v[218:221], v[120:123]
	v_mfma_f32_16x16x32_bf16 v[96:99], v[202:205], v[226:229], v[96:99]
	v_mfma_f32_16x16x32_bf16 v[112:115], v[210:213], v[226:229], v[112:115]
	v_mfma_f32_16x16x32_bf16 v[104:107], v[202:205], v[234:237], v[104:107]
	v_mfma_f32_16x16x32_bf16 v[116:119], v[210:213], v[234:237], v[116:119]
	v_mfma_f32_16x16x32_bf16 v[108:111], v[202:205], v[242:245], v[108:111]
	v_mfma_f32_16x16x32_bf16 v[124:127], v[210:213], v[242:245], v[124:127]
	v_mfma_f32_16x16x32_bf16 v[100:103], v[206:209], v[222:225], v[100:103]
	v_mfma_f32_16x16x32_bf16 v[120:123], v[214:217], v[222:225], v[120:123]
	v_mfma_f32_16x16x32_bf16 v[96:99], v[206:209], v[230:233], v[96:99]
	v_mfma_f32_16x16x32_bf16 v[112:115], v[214:217], v[230:233], v[112:115]
	v_mfma_f32_16x16x32_bf16 v[104:107], v[206:209], v[238:241], v[104:107]
	v_mfma_f32_16x16x32_bf16 v[116:119], v[214:217], v[238:241], v[116:119]
	v_mfma_f32_16x16x32_bf16 v[108:111], v[206:209], v[246:249], v[108:111]
	v_mfma_f32_16x16x32_bf16 v[124:127], v[214:217], v[246:249], v[124:127]
	s_setprio 0
	s_barrier
	s_add_i32 s40, s40, 2
	s_add_u32 s0, s0, 0x100
	s_addc_u32 s1, s1, 0
	s_add_u32 s22, s22, 0x10000
	s_addc_u32 s23, s23, 0
	s_cmp_gt_u32 s40, 29
	s_cbranch_scc0 .LBB0_458
	v_cvt_pk_bf16_f32 v160, v8, v9
	v_mul_f32_e32 v9, v9, v9
	v_fmac_f32_e32 v9, v8, v8
	v_mul_f32_e32 v8, v11, v11
	v_fmac_f32_e32 v8, v10, v10
	v_cvt_pk_bf16_f32 v161, v10, v11
	v_add_f32_e32 v8, v9, v8
	v_mul_f32_e32 v9, v13, v13
	v_mul_f32_e32 v10, v15, v15
	v_fmac_f32_e32 v9, v12, v12
	v_fmac_f32_e32 v10, v14, v14
	v_add_f32_e32 v9, v9, v10
	v_add_f32_e32 v8, v8, v9
	v_mul_f32_e32 v9, v29, v29
	v_mul_f32_e32 v10, v31, v31
	v_fmac_f32_e32 v9, v28, v28
	v_fmac_f32_e32 v10, v30, v30
	v_add_f32_e32 v9, v9, v10
	v_mul_f32_e32 v10, v33, v33
	v_mul_f32_e32 v11, v35, v35
	s_lshl_b32 s0, s14, 8
	v_fmac_f32_e32 v10, v32, v32
	v_fmac_f32_e32 v11, v34, v34
	s_add_i32 s8, s0, s29
	v_add_f32_e32 v10, v10, v11
	s_lshl_b32 s0, s24, 8
	s_ashr_i32 s6, s8, 8
	v_add_f32_e32 v9, v9, v10
	v_cmp_lt_i32_e64 s[40:41], v191, v192
	v_or_b32_e32 v140, s8, v164
	s_or_b32 s9, s0, s34
	s_ashr_i32 s7, s6, 31
	v_add_f32_e32 v8, v8, v9
	v_cndmask_b32_e64 v9, v190, v191, s[40:41]
	s_lshl_b32 s0, s24, 2
	s_lshl_b32 s8, s8, 6
	v_lshlrev_b32_e32 v141, 5, v140
	s_lshl_b64 s[24:25], s[6:7], 5
	s_ashr_i32 s6, s9, 6
	v_lshlrev_b32_e32 v10, 2, v9
	s_ashr_i32 s1, s0, 31
	s_and_b32 s8, s8, 0x2000
	v_and_b32_e32 v142, 0x1e0, v141
	s_ashr_i32 s7, s6, 31
	ds_bpermute_b32 v9, v10, v8
	v_or3_b32 v141, s8, v142, v167
	s_add_u32 s8, s24, s6
	s_addc_u32 s9, s25, s7
	s_lshl_b64 s[8:9], s[8:9], 15
	s_add_u32 s22, s16, s8
	v_cmp_lt_i32_e64 s[40:41], v193, v192
	s_addc_u32 s23, s17, s9
	s_or_b32 s8, s6, 2
	s_waitcnt lgkmcnt(0)
	v_add_f32_e32 v8, v8, v9
	v_cndmask_b32_e64 v9, v190, v193, s[40:41]
	s_ashr_i32 s9, s8, 31
	v_lshlrev_b32_e32 v11, 2, v9
	s_add_u32 s24, s24, s8
	ds_bpermute_b32 v9, v11, v8
	s_addc_u32 s25, s25, s9
	s_lshl_b64 s[24:25], s[24:25], 15
	s_add_u32 s24, s16, s24
	v_lshlrev_b32_e32 v141, 1, v141
	s_addc_u32 s25, s17, s25
	v_cvt_pk_bf16_f32 v162, v12, v13
	v_cvt_pk_bf16_f32 v163, v14, v15
	global_store_dwordx4 v141, v[160:163], s[22:23] sc1
	v_cvt_pk_bf16_f32 v12, v28, v29
	v_cvt_pk_bf16_f32 v13, v30, v31
	v_cvt_pk_bf16_f32 v14, v32, v33
	v_cvt_pk_bf16_f32 v15, v34, v35
	global_store_dwordx4 v141, v[12:15], s[24:25] sc1
	s_and_saveexec_b64 s[26:27], s[38:39]
	s_cbranch_execz .LBB0_461
	v_ashrrev_i32_e32 v141, 31, v140
	v_lshlrev_b64 v[12:13], 7, v[140:141]
	v_lshl_add_u64 v[12:13], s[20:21], 0, v[12:13]
	v_lshl_add_u64 v[12:13], s[0:1], 2, v[12:13]
	s_lshl_b32 s14, s28, 2
	v_lshl_add_u64 v[12:13], v[12:13], 0, s[14:15]
	s_waitcnt lgkmcnt(0)
	v_add_f32_e32 v8, v8, v9
	global_store_dword v[12:13], v8, off
; __device__ __forceinline__ unsigned cvt_pk_bf16(float lo, float hi) { unsigned r; asm volatile("v_cvt_pk_bf16_f32 %0, %1, %2" : "=v"(r) : "v"(lo), "v"(hi)); return r; }
;     __device__ __forceinline__ size_t xb_off(int row, int col) const { return ((size_t)(row >> 8) * (ldc >> 6) + (col >> 6)) * (256 * 64) + blk_off(row & 255, col & 63); }
;     __device__ __forceinline__ void operator()(const f32x4 (&acc)[2][2][4][2], const State&, const Unit& u, int wr, int wc, int fr, int fq) const {
;     ...
;             for (int ai = 0; ai < 2; ++ai)
; #pragma unroll
;                 for (int m = 0; m < 4; ++m) { const int row = row0 + ai * HALF + m * 16; const size_t off = (size_t)row * ldc + col0; float ss = 0.f;
; #pragma unroll
;                     for (int bj = 0; bj < 2; ++bj) { const f32x4 v0 = acc[ai][bj][m][0], v1 = acc[ai][bj][m][1];
;                         u32x4 w; w.x = cvt_pk_bf16(v0[0], v0[1]); w.y = cvt_pk_bf16(v0[2], v0[3]); w.z = cvt_pk_bf16(v1[0], v1[1]); w.w = cvt_pk_bf16(v1[2], v1[3]);
;                         *(u32x4*)(xb + xb_off(row, col0 + bj * HALF)) = w;
;                         ss += ((v0[0] * v0[0] + v0[1] * v0[1]) + (v0[2] * v0[2] + v0[3] * v0[3])) + ((v1[0] * v1[0] + v1[1] * v1[1]) + (v1[2] * v1[2] + v1[3] * v1[3])); }
;                     ss += __shfl_xor(ss, 16); ss += __shfl_xor(ss, 32);
;                     if (fq == 0) ssq[(size_t)row * 32 + u.pn * 4 + wc] = ss; }
.LBB0_461:
	s_or_b64 exec, exec, s[26:27]
	v_cvt_pk_bf16_f32 v28, v4, v5
	v_cvt_pk_bf16_f32 v29, v6, v7
	v_cvt_pk_bf16_f32 v30, v0, v1
	v_mul_f32_e32 v5, v5, v5
	v_mul_f32_e32 v1, v1, v1
	v_fmac_f32_e32 v5, v4, v4
	v_mul_f32_e32 v4, v7, v7
	v_fmac_f32_e32 v1, v0, v0
	v_mul_f32_e32 v0, v3, v3
	v_fmac_f32_e32 v4, v6, v6
	v_fmac_f32_e32 v0, v2, v2
	v_add_f32_e32 v4, v5, v4
	v_add_f32_e32 v0, v1, v0
	v_add_f32_e32 v0, v4, v0
	v_mul_f32_e32 v1, v21, v21
	v_mul_f32_e32 v4, v23, v23
	v_fmac_f32_e32 v1, v20, v20
	v_fmac_f32_e32 v4, v22, v22
	v_add_f32_e32 v1, v1, v4
	v_mul_f32_e32 v4, v25, v25
	v_mul_f32_e32 v5, v27, v27
	v_fmac_f32_e32 v4, v24, v24
	v_fmac_f32_e32 v5, v26, v26
	v_add_f32_e32 v4, v4, v5
	v_add_f32_e32 v1, v1, v4
	v_add_f32_e32 v0, v0, v1
	ds_bpermute_b32 v1, v10, v0
	v_or_b32_e32 v8, 16, v140
	s_waitcnt lgkmcnt(0)
	v_lshlrev_b32_e32 v9, 6, v140
	v_and_b32_e32 v12, 0x2000, v9
	v_lshrrev_b32_e32 v9, 3, v8
	v_add_f32_e32 v0, v0, v1
	ds_bpermute_b32 v1, v11, v0
	v_and_or_b32 v9, v9, 10, s69
	v_lshl_or_b32 v9, v9, 9, v12
	v_or3_b32 v9, v9, v142, v165
	v_lshlrev_b32_e32 v6, 1, v9
	v_cvt_pk_bf16_f32 v31, v2, v3
	global_store_dwordx4 v6, v[28:31], s[22:23] sc1
	v_cvt_pk_bf16_f32 v2, v20, v21
	v_cvt_pk_bf16_f32 v3, v22, v23
	v_cvt_pk_bf16_f32 v4, v24, v25
	v_cvt_pk_bf16_f32 v5, v26, v27
	global_store_dwordx4 v6, v[2:5], s[24:25] sc1
	s_and_saveexec_b64 s[26:27], s[38:39]
	s_cbranch_execz .LBB0_463
	v_ashrrev_i32_e32 v9, 31, v8
	v_lshlrev_b64 v[2:3], 7, v[8:9]
	v_lshl_add_u64 v[2:3], s[20:21], 0, v[2:3]
	v_lshl_add_u64 v[2:3], s[0:1], 2, v[2:3]
	s_lshl_b32 s14, s28, 2
	v_lshl_add_u64 v[2:3], v[2:3], 0, s[14:15]
	s_waitcnt lgkmcnt(0)
	v_add_f32_e32 v0, v0, v1
	global_store_dword v[2:3], v0, off
.LBB0_463:
	s_or_b64 exec, exec, s[26:27]
	v_mul_f32_e32 v5, v17, v17
	v_mul_f32_e32 v6, v19, v19
	v_fmac_f32_e32 v5, v16, v16
	v_fmac_f32_e32 v6, v18, v18
	v_add_f32_e32 v5, v5, v6
	v_mul_f32_e32 v6, v37, v37
	v_mul_f32_e32 v7, v39, v39
	v_fmac_f32_e32 v6, v36, v36
	v_fmac_f32_e32 v7, v38, v38
	v_add_f32_e32 v6, v6, v7
	v_add_f32_e32 v5, v5, v6
	v_mul_f32_e32 v6, v49, v49
	v_mul_f32_e32 v7, v51, v51
	v_fmac_f32_e32 v6, v48, v48
	v_fmac_f32_e32 v7, v50, v50
	v_add_f32_e32 v6, v6, v7
	v_mul_f32_e32 v7, v57, v57
	v_mul_f32_e32 v8, v59, v59
	v_fmac_f32_e32 v7, v56, v56
	v_fmac_f32_e32 v8, v58, v58
	v_add_f32_e32 v7, v7, v8
	v_add_f32_e32 v6, v6, v7
	v_or_b32_e32 v0, 32, v140
	v_add_f32_e32 v6, v5, v6
	s_waitcnt lgkmcnt(0)
	v_lshrrev_b32_e32 v1, 3, v0
	ds_bpermute_b32 v7, v10, v6
	v_and_or_b32 v1, v1, 12, s69
	v_lshl_or_b32 v1, v1, 9, v12
	v_or3_b32 v1, v1, v142, v165
	v_cvt_pk_bf16_f32 v2, v16, v17
	v_lshlrev_b32_e32 v1, 1, v1
	v_cvt_pk_bf16_f32 v3, v18, v19
	v_cvt_pk_bf16_f32 v4, v36, v37
	v_cvt_pk_bf16_f32 v5, v38, v39
	global_store_dwordx4 v1, v[2:5], s[22:23] sc1
	s_waitcnt lgkmcnt(0)
	s_nop 0
	v_add_f32_e32 v2, v6, v7
	ds_bpermute_b32 v3, v11, v2
	v_cvt_pk_bf16_f32 v4, v48, v49
	v_cvt_pk_bf16_f32 v5, v50, v51
	v_cvt_pk_bf16_f32 v6, v56, v57
	v_cvt_pk_bf16_f32 v7, v58, v59
	global_store_dwordx4 v1, v[4:7], s[24:25] sc1
	s_and_saveexec_b64 s[26:27], s[38:39]
	s_cbranch_execz .LBB0_465
	v_ashrrev_i32_e32 v1, 31, v0
	v_lshlrev_b64 v[0:1], 7, v[0:1]
	v_lshl_add_u64 v[0:1], s[20:21], 0, v[0:1]
	v_lshl_add_u64 v[0:1], s[0:1], 2, v[0:1]
	s_lshl_b32 s14, s28, 2
	v_lshl_add_u64 v[0:1], v[0:1], 0, s[14:15]
	s_waitcnt lgkmcnt(0)
	v_add_f32_e32 v2, v2, v3
	global_store_dword v[0:1], v2, off
.LBB0_465:
	s_or_b64 exec, exec, s[26:27]
	v_mul_f32_e32 v5, v45, v45
	v_mul_f32_e32 v6, v47, v47
	v_fmac_f32_e32 v5, v44, v44
	v_fmac_f32_e32 v6, v46, v46
	v_add_f32_e32 v5, v5, v6
	v_mul_f32_e32 v6, v41, v41
	v_mul_f32_e32 v7, v43, v43
	v_fmac_f32_e32 v6, v40, v40
	v_fmac_f32_e32 v7, v42, v42
	v_add_f32_e32 v6, v6, v7
	v_add_f32_e32 v5, v5, v6
	v_mul_f32_e32 v6, v53, v53
	v_mul_f32_e32 v7, v55, v55
	v_fmac_f32_e32 v6, v52, v52
	v_fmac_f32_e32 v7, v54, v54
	v_add_f32_e32 v6, v6, v7
	v_mul_f32_e32 v7, v77, v77
	v_mul_f32_e32 v8, v79, v79
	v_fmac_f32_e32 v7, v76, v76
	v_fmac_f32_e32 v8, v78, v78
	v_add_f32_e32 v7, v7, v8
	v_add_f32_e32 v6, v6, v7
	v_or_b32_e32 v0, 48, v140
	v_add_f32_e32 v6, v5, v6
	v_lshrrev_b32_e32 v1, 3, v0
	ds_bpermute_b32 v7, v10, v6
	v_and_or_b32 v1, v1, 14, s69
	v_lshl_or_b32 v1, v1, 9, v12
	v_or3_b32 v1, v1, v142, v165
	v_cvt_pk_bf16_f32 v2, v44, v45
	v_lshlrev_b32_e32 v1, 1, v1
	s_waitcnt lgkmcnt(0)
	v_cvt_pk_bf16_f32 v3, v46, v47
	v_cvt_pk_bf16_f32 v4, v40, v41
	v_cvt_pk_bf16_f32 v5, v42, v43
	global_store_dwordx4 v1, v[2:5], s[22:23] sc1
	s_nop 1
	v_add_f32_e32 v2, v6, v7
	ds_bpermute_b32 v3, v11, v2
	v_cvt_pk_bf16_f32 v4, v52, v53
	v_cvt_pk_bf16_f32 v5, v54, v55
	v_cvt_pk_bf16_f32 v6, v76, v77
	v_cvt_pk_bf16_f32 v7, v78, v79
	global_store_dwordx4 v1, v[4:7], s[24:25] sc1
	s_and_saveexec_b64 s[22:23], s[38:39]
	s_cbranch_execz .LBB0_467
	v_ashrrev_i32_e32 v1, 31, v0
	v_lshlrev_b64 v[0:1], 7, v[0:1]
	v_lshl_add_u64 v[0:1], s[20:21], 0, v[0:1]
	v_lshl_add_u64 v[0:1], s[0:1], 2, v[0:1]
	s_lshl_b32 s14, s28, 2
	v_lshl_add_u64 v[0:1], v[0:1], 0, s[14:15]
	s_waitcnt lgkmcnt(0)
	v_add_f32_e32 v2, v2, v3
	global_store_dword v[0:1], v2, off
; __device__ __forceinline__ unsigned cvt_pk_bf16(float lo, float hi) { unsigned r; asm volatile("v_cvt_pk_bf16_f32 %0, %1, %2" : "=v"(r) : "v"(lo), "v"(hi)); return r; }
;     __device__ __forceinline__ size_t xb_off(int row, int col) const { return ((size_t)(row >> 8) * (ldc >> 6) + (col >> 6)) * (256 * 64) + blk_off(row & 255, col & 63); }
;     __device__ __forceinline__ void operator()(const f32x4 (&acc)[2][2][4][2], const State&, const Unit& u, int wr, int wc, int fr, int fq) const {
;     ...
;             for (int ai = 0; ai < 2; ++ai)
; #pragma unroll
;                 for (int m = 0; m < 4; ++m) { const int row = row0 + ai * HALF + m * 16; const size_t off = (size_t)row * ldc + col0; float ss = 0.f;
; #pragma unroll
;                     for (int bj = 0; bj < 2; ++bj) { const f32x4 v0 = acc[ai][bj][m][0], v1 = acc[ai][bj][m][1];
;                         u32x4 w; w.x = cvt_pk_bf16(v0[0], v0[1]); w.y = cvt_pk_bf16(v0[2], v0[3]); w.z = cvt_pk_bf16(v1[0], v1[1]); w.w = cvt_pk_bf16(v1[2], v1[3]);
;                         *(u32x4*)(xb + xb_off(row, col0 + bj * HALF)) = w;
;                         ss += ((v0[0] * v0[0] + v0[1] * v0[1]) + (v0[2] * v0[2] + v0[3] * v0[3])) + ((v1[0] * v1[0] + v1[1] * v1[1]) + (v1[2] * v1[2] + v1[3] * v1[3])); }
;                     ss += __shfl_xor(ss, 16); ss += __shfl_xor(ss, 32);
;                     if (fq == 0) ssq[(size_t)row * 32 + u.pn * 4 + wc] = ss; }
.LBB0_467:
	s_or_b64 exec, exec, s[22:23]
	v_add_u32_e32 v4, 0x80, v140
	v_ashrrev_i32_e32 v0, 8, v4
	v_lshlrev_b32_e32 v2, 6, v4
	s_waitcnt lgkmcnt(0)
	v_lshlrev_b32_e32 v3, 5, v4
	v_ashrrev_i32_e32 v1, 31, v0
	v_and_b32_e32 v2, 0x2000, v2
	v_and_b32_e32 v3, 0x1e0, v3
	v_or3_b32 v5, v2, v3, v167
	v_lshlrev_b64 v[2:3], 5, v[0:1]
	v_lshl_add_u64 v[0:1], v[2:3], 0, s[6:7]
	v_lshlrev_b64 v[0:1], 15, v[0:1]
	v_lshl_add_u64 v[0:1], s[16:17], 0, v[0:1]
	v_lshlrev_b32_e32 v144, 1, v5
	v_cvt_pk_bf16_f32 v6, v64, v65
	v_lshl_add_u64 v[12:13], v[0:1], 0, v[144:145]
	v_cvt_pk_bf16_f32 v7, v66, v67
	v_cvt_pk_bf16_f32 v8, v84, v85
	v_cvt_pk_bf16_f32 v9, v86, v87
	global_store_dwordx4 v[12:13], v[6:9], off sc1
	v_mul_f32_e32 v5, v65, v65
	v_fmac_f32_e32 v5, v64, v64
	v_mul_f32_e32 v6, v67, v67
	v_fmac_f32_e32 v6, v66, v66
	v_add_f32_e32 v5, v5, v6
	v_mul_f32_e32 v6, v85, v85
	v_mul_f32_e32 v7, v87, v87
	v_fmac_f32_e32 v6, v84, v84
	v_fmac_f32_e32 v7, v86, v86
	v_add_f32_e32 v6, v6, v7
	v_add_f32_e32 v5, v5, v6
	v_mul_f32_e32 v6, v101, v101
	v_mul_f32_e32 v7, v103, v103
	v_fmac_f32_e32 v6, v100, v100
	v_fmac_f32_e32 v7, v102, v102
	v_add_f32_e32 v6, v6, v7
	v_mul_f32_e32 v7, v121, v121
	v_mul_f32_e32 v8, v123, v123
	v_fmac_f32_e32 v7, v120, v120
	v_fmac_f32_e32 v8, v122, v122
	v_add_f32_e32 v7, v7, v8
	v_add_f32_e32 v6, v6, v7
	v_add_f32_e32 v5, v5, v6
	ds_bpermute_b32 v6, v10, v5
	v_lshl_add_u64 v[2:3], v[2:3], 0, s[8:9]
	v_lshlrev_b64 v[2:3], 15, v[2:3]
	v_lshl_add_u64 v[2:3], s[16:17], 0, v[2:3]
	v_lshl_add_u64 v[8:9], v[2:3], 0, v[144:145]
	s_waitcnt lgkmcnt(0)
	v_add_f32_e32 v6, v5, v6
	ds_bpermute_b32 v7, v11, v6
	v_cvt_pk_bf16_f32 v12, v100, v101
	v_cvt_pk_bf16_f32 v13, v102, v103
	v_cvt_pk_bf16_f32 v14, v120, v121
	v_cvt_pk_bf16_f32 v15, v122, v123
	global_store_dwordx4 v[8:9], v[12:15], off sc1
	s_and_saveexec_b64 s[6:7], s[38:39]
	s_cbranch_execz .LBB0_469
	v_ashrrev_i32_e32 v5, 31, v4
	v_lshlrev_b64 v[4:5], 7, v[4:5]
	v_lshl_add_u64 v[4:5], s[20:21], 0, v[4:5]
	v_lshl_add_u64 v[4:5], s[0:1], 2, v[4:5]
	s_lshl_b32 s14, s28, 2
	v_lshl_add_u64 v[4:5], v[4:5], 0, s[14:15]
	s_waitcnt lgkmcnt(0)
	v_add_f32_e32 v6, v6, v7
	global_store_dword v[4:5], v6, off
.LBB0_469:
	s_or_b64 exec, exec, s[6:7]
	v_add_u32_e32 v4, 0x90, v140
	v_lshlrev_b32_e32 v5, 6, v4
	v_lshrrev_b32_e32 v6, 3, v4
	v_and_b32_e32 v5, 0x2000, v5
	v_and_or_b32 v6, v6, 10, s69
	v_lshl_or_b32 v5, v6, 9, v5
	v_lshlrev_b32_e32 v6, 5, v4
	v_and_b32_e32 v6, 0x1e0, v6
	v_or3_b32 v5, v5, v6, v165
	v_lshlrev_b32_e32 v144, 1, v5
	v_mul_f32_e32 v5, v61, v61
	v_mul_f32_e32 v12, v63, v63
	v_fmac_f32_e32 v5, v60, v60
	v_fmac_f32_e32 v12, v62, v62
	v_add_f32_e32 v5, v5, v12
	v_mul_f32_e32 v12, v81, v81
	v_mul_f32_e32 v13, v83, v83
	v_fmac_f32_e32 v12, v80, v80
	v_fmac_f32_e32 v13, v82, v82
	v_add_f32_e32 v12, v12, v13
	v_add_f32_e32 v5, v5, v12
	v_mul_f32_e32 v12, v97, v97
	v_mul_f32_e32 v13, v99, v99
	v_fmac_f32_e32 v12, v96, v96
	v_fmac_f32_e32 v13, v98, v98
	v_add_f32_e32 v12, v12, v13
	v_mul_f32_e32 v13, v113, v113
	v_mul_f32_e32 v14, v115, v115
	v_fmac_f32_e32 v13, v112, v112
	v_fmac_f32_e32 v14, v114, v114
	v_add_f32_e32 v13, v13, v14
	v_add_f32_e32 v12, v12, v13
	v_add_f32_e32 v5, v5, v12
	ds_bpermute_b32 v14, v10, v5
	v_cvt_pk_bf16_f32 v6, v60, v61
	v_lshl_add_u64 v[12:13], v[0:1], 0, v[144:145]
	s_waitcnt lgkmcnt(0)
	v_cvt_pk_bf16_f32 v7, v62, v63
	v_cvt_pk_bf16_f32 v8, v80, v81
	v_cvt_pk_bf16_f32 v9, v82, v83
	global_store_dwordx4 v[12:13], v[6:9], off sc1
	v_cvt_pk_bf16_f32 v12, v96, v97
	v_cvt_pk_bf16_f32 v13, v98, v99
	s_nop 1
	v_add_f32_e32 v6, v5, v14
	ds_bpermute_b32 v7, v11, v6
	v_lshl_add_u64 v[8:9], v[2:3], 0, v[144:145]
	v_cvt_pk_bf16_f32 v14, v112, v113
	v_cvt_pk_bf16_f32 v15, v114, v115
	global_store_dwordx4 v[8:9], v[12:15], off sc1
	s_and_saveexec_b64 s[6:7], s[38:39]
	s_cbranch_execz .LBB0_471
	v_ashrrev_i32_e32 v5, 31, v4
	v_lshlrev_b64 v[4:5], 7, v[4:5]
	v_lshl_add_u64 v[4:5], s[20:21], 0, v[4:5]
	v_lshl_add_u64 v[4:5], s[0:1], 2, v[4:5]
	s_lshl_b32 s14, s28, 2
	v_lshl_add_u64 v[4:5], v[4:5], 0, s[14:15]
	s_waitcnt lgkmcnt(0)
	v_add_f32_e32 v6, v6, v7
	global_store_dword v[4:5], v6, off
; __device__ __forceinline__ unsigned cvt_pk_bf16(float lo, float hi) { unsigned r; asm volatile("v_cvt_pk_bf16_f32 %0, %1, %2" : "=v"(r) : "v"(lo), "v"(hi)); return r; }
;     __device__ __forceinline__ size_t xb_off(int row, int col) const { return ((size_t)(row >> 8) * (ldc >> 6) + (col >> 6)) * (256 * 64) + blk_off(row & 255, col & 63); }
;     __device__ __forceinline__ void operator()(const f32x4 (&acc)[2][2][4][2], const State&, const Unit& u, int wr, int wc, int fr, int fq) const {
;     ...
;             for (int ai = 0; ai < 2; ++ai)
; #pragma unroll
;                 for (int m = 0; m < 4; ++m) { const int row = row0 + ai * HALF + m * 16; const size_t off = (size_t)row * ldc + col0; float ss = 0.f;
; #pragma unroll
;                     for (int bj = 0; bj < 2; ++bj) { const f32x4 v0 = acc[ai][bj][m][0], v1 = acc[ai][bj][m][1];
;                         u32x4 w; w.x = cvt_pk_bf16(v0[0], v0[1]); w.y = cvt_pk_bf16(v0[2], v0[3]); w.z = cvt_pk_bf16(v1[0], v1[1]); w.w = cvt_pk_bf16(v1[2], v1[3]);
;                         *(u32x4*)(xb + xb_off(row, col0 + bj * HALF)) = w;
;                         ss += ((v0[0] * v0[0] + v0[1] * v0[1]) + (v0[2] * v0[2] + v0[3] * v0[3])) + ((v1[0] * v1[0] + v1[1] * v1[1]) + (v1[2] * v1[2] + v1[3] * v1[3])); }
;                     ss += __shfl_xor(ss, 16); ss += __shfl_xor(ss, 32);
;                     if (fq == 0) ssq[(size_t)row * 32 + u.pn * 4 + wc] = ss; }
.LBB0_471:
	s_or_b64 exec, exec, s[6:7]
	v_add_u32_e32 v4, 0xa0, v140
	v_lshlrev_b32_e32 v5, 6, v4
	v_lshrrev_b32_e32 v6, 3, v4
	v_and_b32_e32 v5, 0x2000, v5
	v_and_or_b32 v6, v6, 12, s69
	v_lshl_or_b32 v5, v6, 9, v5
	v_lshlrev_b32_e32 v6, 5, v4
	v_and_b32_e32 v6, 0x1e0, v6
	v_or3_b32 v5, v5, v6, v165
	v_lshlrev_b32_e32 v144, 1, v5
	v_mul_f32_e32 v5, v69, v69
	v_mul_f32_e32 v12, v71, v71
	v_fmac_f32_e32 v5, v68, v68
	v_fmac_f32_e32 v12, v70, v70
	v_add_f32_e32 v5, v5, v12
	v_mul_f32_e32 v12, v89, v89
	v_mul_f32_e32 v13, v91, v91
	v_fmac_f32_e32 v12, v88, v88
	v_fmac_f32_e32 v13, v90, v90
	v_add_f32_e32 v12, v12, v13
	v_add_f32_e32 v5, v5, v12
	v_mul_f32_e32 v12, v105, v105
	v_mul_f32_e32 v13, v107, v107
	v_fmac_f32_e32 v12, v104, v104
	v_fmac_f32_e32 v13, v106, v106
	v_add_f32_e32 v12, v12, v13
	v_mul_f32_e32 v13, v117, v117
	v_mul_f32_e32 v14, v119, v119
	v_fmac_f32_e32 v13, v116, v116
	v_fmac_f32_e32 v14, v118, v118
	v_add_f32_e32 v13, v13, v14
	v_add_f32_e32 v12, v12, v13
	v_add_f32_e32 v5, v5, v12
	ds_bpermute_b32 v14, v10, v5
	v_cvt_pk_bf16_f32 v6, v68, v69
	v_lshl_add_u64 v[12:13], v[0:1], 0, v[144:145]
	s_waitcnt lgkmcnt(0)
	v_cvt_pk_bf16_f32 v7, v70, v71
	v_cvt_pk_bf16_f32 v8, v88, v89
	v_cvt_pk_bf16_f32 v9, v90, v91
	global_store_dwordx4 v[12:13], v[6:9], off sc1
	v_cvt_pk_bf16_f32 v12, v104, v105
	v_cvt_pk_bf16_f32 v13, v106, v107
	s_nop 1
	v_add_f32_e32 v6, v5, v14
	ds_bpermute_b32 v7, v11, v6
	v_lshl_add_u64 v[8:9], v[2:3], 0, v[144:145]
	v_cvt_pk_bf16_f32 v14, v116, v117
	v_cvt_pk_bf16_f32 v15, v118, v119
	global_store_dwordx4 v[8:9], v[12:15], off sc1
	s_and_saveexec_b64 s[6:7], s[38:39]
	s_cbranch_execz .LBB0_473
	v_ashrrev_i32_e32 v5, 31, v4
	v_lshlrev_b64 v[4:5], 7, v[4:5]
	v_lshl_add_u64 v[4:5], s[20:21], 0, v[4:5]
	v_lshl_add_u64 v[4:5], s[0:1], 2, v[4:5]
	s_lshl_b32 s14, s28, 2
	v_lshl_add_u64 v[4:5], v[4:5], 0, s[14:15]
	s_waitcnt lgkmcnt(0)
	v_add_f32_e32 v6, v6, v7
	global_store_dword v[4:5], v6, off
.LBB0_473:
	s_or_b64 exec, exec, s[6:7]
	v_add_u32_e32 v4, 0xb0, v140
	v_lshlrev_b32_e32 v5, 6, v4
	v_lshrrev_b32_e32 v6, 3, v4
	v_and_b32_e32 v5, 0x2000, v5
	v_and_or_b32 v6, v6, 14, s69
	v_lshl_or_b32 v5, v6, 9, v5
	v_lshlrev_b32_e32 v6, 5, v4
	v_and_b32_e32 v6, 0x1e0, v6
	v_or3_b32 v5, v5, v6, v165
	v_lshlrev_b32_e32 v144, 1, v5
	v_mul_f32_e32 v5, v73, v73
	v_mul_f32_e32 v12, v75, v75
	v_fmac_f32_e32 v5, v72, v72
	v_fmac_f32_e32 v12, v74, v74
	v_add_f32_e32 v5, v5, v12
	v_mul_f32_e32 v12, v93, v93
	v_mul_f32_e32 v13, v95, v95
	v_fmac_f32_e32 v12, v92, v92
	v_fmac_f32_e32 v13, v94, v94
	v_add_f32_e32 v12, v12, v13
	v_add_f32_e32 v5, v5, v12
	v_mul_f32_e32 v12, v109, v109
	v_mul_f32_e32 v13, v111, v111
	v_fmac_f32_e32 v12, v108, v108
	v_fmac_f32_e32 v13, v110, v110
	v_add_f32_e32 v12, v12, v13
	v_mul_f32_e32 v13, v125, v125
	v_mul_f32_e32 v14, v127, v127
	v_fmac_f32_e32 v13, v124, v124
	v_fmac_f32_e32 v14, v126, v126
	v_add_f32_e32 v13, v13, v14
	v_add_f32_e32 v12, v12, v13
	v_add_f32_e32 v5, v5, v12
	ds_bpermute_b32 v10, v10, v5
	v_lshl_add_u64 v[0:1], v[0:1], 0, v[144:145]
	v_cvt_pk_bf16_f32 v6, v72, v73
	s_waitcnt lgkmcnt(0)
	v_cvt_pk_bf16_f32 v7, v74, v75
	v_cvt_pk_bf16_f32 v8, v92, v93
	v_cvt_pk_bf16_f32 v9, v94, v95
	global_store_dwordx4 v[0:1], v[6:9], off sc1
	v_add_f32_e32 v0, v5, v10
	ds_bpermute_b32 v1, v11, v0
	v_lshl_add_u64 v[2:3], v[2:3], 0, v[144:145]
	v_cvt_pk_bf16_f32 v6, v108, v109
	v_cvt_pk_bf16_f32 v7, v110, v111
	v_cvt_pk_bf16_f32 v8, v124, v125
	v_cvt_pk_bf16_f32 v9, v126, v127
	global_store_dwordx4 v[2:3], v[6:9], off sc1
	s_and_saveexec_b64 s[6:7], s[38:39]
	s_cbranch_execz .LBB0_475
	v_ashrrev_i32_e32 v5, 31, v4
	v_lshlrev_b64 v[2:3], 7, v[4:5]
	v_lshl_add_u64 v[2:3], s[20:21], 0, v[2:3]
	v_lshl_add_u64 v[2:3], s[0:1], 2, v[2:3]
	s_lshl_b32 s14, s28, 2
	v_lshl_add_u64 v[2:3], v[2:3], 0, s[14:15]
	s_waitcnt lgkmcnt(0)
	v_add_f32_e32 v0, v0, v1
	global_store_dword v[2:3], v0, off

; __host__ __device__ __forceinline__ int blk_off(int r, int c) { const int rr = r & 127; return (r >> 7) * 8192 + (((rr >> 4) * 2 + (c >> 5)) * 512) + (rr & 15) * 32 + (c & 31); }
; __device__ __forceinline__ unsigned cvt_pk_bf16(float lo, float hi) { unsigned r; asm volatile("v_cvt_pk_bf16_f32 %0, %1, %2" : "=v"(r) : "v"(lo), "v"(hi)); return r; }
;     __device__ __forceinline__ void operator()(const f32x4 (&acc)[2][2][4][2], const State& st, const Unit& u, int wr, int wc, int fr, int fq) const {
;     ...
;         for (int ai = 0; ai < 2; ++ai)
; #pragma unroll
;             for (int m = 0; m < 4; ++m) { const int row = row0 + ai * HALF + m * 16;
;                 const float rs = rsv[ai][m];
;                 bf16_t* rowp = O + (size_t)(row >> 8) * (ldc >> 6) * (256 * 64);
; #pragma unroll
;                 for (int bj = 0; bj < 2; ++bj) { f32x4 v0 = acc[ai][bj][m][0] * rs, v1 = acc[ai][bj][m][1] * rs;
; #pragma unroll
;                     for (int e = 0; e < 4; ++e) { const float a = fmaxf(v0[e], 0.f), b = fmaxf(v1[e], 0.f); v0[e] = a * a; v1[e] = b * b; }
;                     u32x4 w; w.x = cvt_pk_bf16(v0[0], v0[1]); w.y = cvt_pk_bf16(v0[2], v0[3]); w.z = cvt_pk_bf16(v1[0], v1[1]); w.w = cvt_pk_bf16(v1[2], v1[3]);
;                     { const int col = col0 + bj * HALF; *(u32x4*)(rowp + (size_t)(col >> 6) * (256 * 64) + blk_off(row & 255, col & 63)) = w; } } }
.LBB0_556:
	s_lshl_b32 s0, s60, 8
	s_add_i32 s6, s0, s14
	v_or_b32_e32 v165, s6, v129
	s_lshl_b32 s0, s66, 8
	s_or_b32 s7, s0, s50
	s_ashr_i32 s0, s6, 8
	s_lshl_b32 s6, s6, 6
	v_lshlrev_b32_e32 v144, 5, v165
	s_ashr_i32 s1, s0, 31
	s_and_b32 s6, s6, 0x2000
	v_and_b32_e32 v144, 0x1e0, v144
	v_or3_b32 v167, s6, v144, v131
	s_lshl_b64 s[0:1], s[0:1], 22
	s_add_u32 s8, s18, s0
	v_or_b32_e32 v144, s53, v167
	v_pk_mul_f32 v[122:123], v[128:129], v[122:123] op_sel_hi:[0,1]
	v_pk_mul_f32 v[120:121], v[128:129], v[120:121] op_sel_hi:[0,1]
	s_addc_u32 s9, s19, s1
	v_lshlrev_b32_e32 v144, 1, v144
	v_pk_mul_f32 v[126:127], v[128:129], v[126:127] op_sel_hi:[0,1]
	v_pk_mul_f32 v[124:125], v[128:129], v[124:125] op_sel_hi:[0,1]
	v_max_f32_e32 v120, 0, v120
	v_max_f32_e32 v121, 0, v121
	v_max_f32_e32 v122, 0, v122
	s_ashr_i32 s6, s7, 6
	v_lshl_add_u64 v[170:171], s[8:9], 0, v[144:145]
	v_max_f32_e32 v124, 0, v124
	v_mul_f32_e32 v144, v120, v120
	v_max_f32_e32 v120, 0, v125
	v_mul_f32_e32 v125, v121, v121
	v_max_f32_e32 v121, 0, v126
	v_mul_f32_e32 v126, v122, v122
	v_max_f32_e32 v122, 0, v127
	s_ashr_i32 s7, s6, 31
	v_mul_f32_e32 v124, v124, v124
	v_mul_f32_e32 v120, v120, v120
	v_mul_f32_e32 v121, v121, v121
	v_max_f32_e32 v123, 0, v123
	v_mul_f32_e32 v122, v122, v122
	s_lshl_b64 s[0:1], s[6:7], 15
	v_pk_mul_f32 v[114:115], v[128:129], v[114:115] op_sel_hi:[0,1]
	v_pk_mul_f32 v[112:113], v[128:129], v[112:113] op_sel_hi:[0,1]
	v_mul_f32_e32 v123, v123, v123
	v_cvt_pk_bf16_f32 v120, v124, v120
	v_cvt_pk_bf16_f32 v121, v121, v122
	v_cvt_pk_bf16_f32 v122, v144, v125
	v_lshl_add_u64 v[124:125], v[170:171], 0, s[0:1]
	v_pk_mul_f32 v[118:119], v[128:129], v[118:119] op_sel_hi:[0,1]
	v_pk_mul_f32 v[116:117], v[128:129], v[116:117] op_sel_hi:[0,1]
	v_max_f32_e32 v112, 0, v112
	v_max_f32_e32 v113, 0, v113
	v_max_f32_e32 v114, 0, v114
	s_or_b32 s6, s6, 2
	v_cvt_pk_bf16_f32 v123, v126, v123
	global_store_dwordx4 v[124:125], v[120:123], off sc1
	v_max_f32_e32 v116, 0, v116
	s_ashr_i32 s7, s6, 31
	v_mul_f32_e32 v120, v112, v112
	v_max_f32_e32 v112, 0, v117
	v_mul_f32_e32 v117, v113, v113
	v_max_f32_e32 v113, 0, v118
	v_mul_f32_e32 v118, v114, v114
	v_max_f32_e32 v114, 0, v119
	v_mul_f32_e32 v116, v116, v116
	v_mul_f32_e32 v112, v112, v112
	v_mul_f32_e32 v113, v113, v113
	v_max_f32_e32 v115, 0, v115
	v_mul_f32_e32 v114, v114, v114
	s_lshl_b64 s[6:7], s[6:7], 15
	v_mul_f32_e32 v115, v115, v115
	v_cvt_pk_bf16_f32 v112, v116, v112
	v_cvt_pk_bf16_f32 v113, v113, v114
	v_cvt_pk_bf16_f32 v114, v120, v117
	v_lshl_add_u64 v[116:117], v[170:171], 0, s[6:7]
	v_cvt_pk_bf16_f32 v115, v118, v115
	global_store_dwordx4 v[116:117], v[112:115], off sc1
	v_pk_mul_f32 v[106:107], v[130:131], v[106:107] op_sel_hi:[0,1]
	v_pk_mul_f32 v[104:105], v[130:131], v[104:105] op_sel_hi:[0,1]
	v_or_b32_e32 v112, s54, v167
	v_lshlrev_b32_e32 v114, 1, v112
	v_pk_mul_f32 v[110:111], v[130:131], v[110:111] op_sel_hi:[0,1]
	v_pk_mul_f32 v[108:109], v[130:131], v[108:109] op_sel_hi:[0,1]
	v_max_f32_e32 v104, 0, v104
	v_max_f32_e32 v105, 0, v105
	v_max_f32_e32 v106, 0, v106
	v_or_b32_e32 v144, 0x800, v114
	v_max_f32_e32 v108, 0, v108
	v_mul_f32_e32 v115, v104, v104
	v_max_f32_e32 v104, 0, v109
	v_mul_f32_e32 v109, v105, v105
	v_max_f32_e32 v105, 0, v110
	v_mul_f32_e32 v110, v106, v106
	v_max_f32_e32 v106, 0, v111
	v_lshl_add_u64 v[112:113], s[8:9], 0, v[144:145]
	v_mul_f32_e32 v108, v108, v108
	v_mul_f32_e32 v104, v104, v104
	v_mul_f32_e32 v105, v105, v105
	v_max_f32_e32 v107, 0, v107
	v_mul_f32_e32 v106, v106, v106
	v_pk_mul_f32 v[98:99], v[130:131], v[98:99] op_sel_hi:[0,1]
	v_pk_mul_f32 v[96:97], v[130:131], v[96:97] op_sel_hi:[0,1]
	v_mul_f32_e32 v107, v107, v107
	v_cvt_pk_bf16_f32 v104, v108, v104
	v_cvt_pk_bf16_f32 v105, v105, v106
	v_cvt_pk_bf16_f32 v106, v115, v109
	v_lshl_add_u64 v[108:109], v[112:113], 0, s[0:1]
	v_pk_mul_f32 v[102:103], v[130:131], v[102:103] op_sel_hi:[0,1]
	v_pk_mul_f32 v[100:101], v[130:131], v[100:101] op_sel_hi:[0,1]
	v_max_f32_e32 v96, 0, v96
	v_max_f32_e32 v97, 0, v97
	v_max_f32_e32 v98, 0, v98
	v_cvt_pk_bf16_f32 v107, v110, v107
	global_store_dwordx4 v[108:109], v[104:107], off sc1
	v_max_f32_e32 v100, 0, v100
	v_mul_f32_e32 v100, v100, v100
	v_mul_f32_e32 v104, v96, v96
	v_max_f32_e32 v96, 0, v101
	v_mul_f32_e32 v101, v97, v97
	v_max_f32_e32 v97, 0, v102
	v_mul_f32_e32 v102, v98, v98
	v_max_f32_e32 v98, 0, v103
	v_mul_f32_e32 v96, v96, v96
	v_mul_f32_e32 v97, v97, v97
	v_max_f32_e32 v99, 0, v99
	v_mul_f32_e32 v98, v98, v98
	v_pk_mul_f32 v[90:91], v[142:143], v[90:91] op_sel_hi:[0,1]
	v_pk_mul_f32 v[88:89], v[142:143], v[88:89] op_sel_hi:[0,1]
	v_mul_f32_e32 v99, v99, v99
	v_cvt_pk_bf16_f32 v96, v100, v96
	v_cvt_pk_bf16_f32 v97, v97, v98
	v_cvt_pk_bf16_f32 v98, v104, v101
	v_lshl_add_u64 v[100:101], v[112:113], 0, s[6:7]
	v_pk_mul_f32 v[94:95], v[142:143], v[94:95] op_sel_hi:[0,1]
	v_pk_mul_f32 v[92:93], v[142:143], v[92:93] op_sel_hi:[0,1]
	v_max_f32_e32 v88, 0, v88
	v_max_f32_e32 v89, 0, v89
	v_max_f32_e32 v90, 0, v90
	v_cvt_pk_bf16_f32 v99, v102, v99
	global_store_dwordx4 v[100:101], v[96:99], off sc1
	v_max_f32_e32 v92, 0, v92
	v_mul_f32_e32 v92, v92, v92
	v_mul_f32_e32 v98, v88, v88
	v_max_f32_e32 v88, 0, v93
	v_mul_f32_e32 v93, v89, v89
	v_max_f32_e32 v89, 0, v94
	v_mul_f32_e32 v94, v90, v90
	v_max_f32_e32 v90, 0, v95
	v_lshl_add_u64 v[96:97], v[170:171], 0, s[12:13]
	v_mul_f32_e32 v88, v88, v88
	v_mul_f32_e32 v89, v89, v89
	v_max_f32_e32 v91, 0, v91
	v_mul_f32_e32 v90, v90, v90
	v_pk_mul_f32 v[82:83], v[142:143], v[82:83] op_sel_hi:[0,1]
	v_pk_mul_f32 v[80:81], v[142:143], v[80:81] op_sel_hi:[0,1]
	v_mul_f32_e32 v91, v91, v91
	v_cvt_pk_bf16_f32 v88, v92, v88
; __host__ __device__ __forceinline__ int blk_off(int r, int c) { const int rr = r & 127; return (r >> 7) * 8192 + (((rr >> 4) * 2 + (c >> 5)) * 512) + (rr & 15) * 32 + (c & 31); }
; __device__ __forceinline__ unsigned cvt_pk_bf16(float lo, float hi) { unsigned r; asm volatile("v_cvt_pk_bf16_f32 %0, %1, %2" : "=v"(r) : "v"(lo), "v"(hi)); return r; }
;     __device__ __forceinline__ void operator()(const f32x4 (&acc)[2][2][4][2], const State& st, const Unit& u, int wr, int wc, int fr, int fq) const {
;     ...
;         for (int ai = 0; ai < 2; ++ai)
; #pragma unroll
;             for (int m = 0; m < 4; ++m) { const int row = row0 + ai * HALF + m * 16;
;                 const float rs = rsv[ai][m];
;                 bf16_t* rowp = O + (size_t)(row >> 8) * (ldc >> 6) * (256 * 64);
; #pragma unroll
;                 for (int bj = 0; bj < 2; ++bj) { f32x4 v0 = acc[ai][bj][m][0] * rs, v1 = acc[ai][bj][m][1] * rs;
; #pragma unroll
;                     for (int e = 0; e < 4; ++e) { const float a = fmaxf(v0[e], 0.f), b = fmaxf(v1[e], 0.f); v0[e] = a * a; v1[e] = b * b; }
;                     u32x4 w; w.x = cvt_pk_bf16(v0[0], v0[1]); w.y = cvt_pk_bf16(v0[2], v0[3]); w.z = cvt_pk_bf16(v1[0], v1[1]); w.w = cvt_pk_bf16(v1[2], v1[3]);
;                     { const int col = col0 + bj * HALF; *(u32x4*)(rowp + (size_t)(col >> 6) * (256 * 64) + blk_off(row & 255, col & 63)) = w; } } }
	v_cvt_pk_bf16_f32 v89, v89, v90
	v_cvt_pk_bf16_f32 v90, v98, v93
	v_lshl_add_u64 v[92:93], v[96:97], 0, s[0:1]
	v_pk_mul_f32 v[86:87], v[142:143], v[86:87] op_sel_hi:[0,1]
	v_pk_mul_f32 v[84:85], v[142:143], v[84:85] op_sel_hi:[0,1]
	v_max_f32_e32 v80, 0, v80
	v_max_f32_e32 v81, 0, v81
	v_max_f32_e32 v82, 0, v82
	v_cvt_pk_bf16_f32 v91, v94, v91
	global_store_dwordx4 v[92:93], v[88:91], off sc1
	v_max_f32_e32 v84, 0, v84
	v_mul_f32_e32 v84, v84, v84
	v_mul_f32_e32 v88, v80, v80
	v_max_f32_e32 v80, 0, v85
	v_mul_f32_e32 v85, v81, v81
	v_max_f32_e32 v81, 0, v86
	v_mul_f32_e32 v86, v82, v82
	v_max_f32_e32 v82, 0, v87
	v_mul_f32_e32 v80, v80, v80
	v_mul_f32_e32 v81, v81, v81
	v_max_f32_e32 v83, 0, v83
	v_mul_f32_e32 v82, v82, v82
	v_pk_mul_f32 v[74:75], v[160:161], v[74:75] op_sel_hi:[0,1]
	v_pk_mul_f32 v[72:73], v[160:161], v[72:73] op_sel_hi:[0,1]
	v_mul_f32_e32 v83, v83, v83
	v_cvt_pk_bf16_f32 v80, v84, v80
	v_cvt_pk_bf16_f32 v81, v81, v82
	v_cvt_pk_bf16_f32 v82, v88, v85
	v_lshl_add_u64 v[84:85], v[96:97], 0, s[6:7]
	v_pk_mul_f32 v[78:79], v[160:161], v[78:79] op_sel_hi:[0,1]
	v_pk_mul_f32 v[76:77], v[160:161], v[76:77] op_sel_hi:[0,1]
	v_max_f32_e32 v72, 0, v72
	v_max_f32_e32 v73, 0, v73
	v_max_f32_e32 v74, 0, v74
	v_cvt_pk_bf16_f32 v83, v86, v83
	global_store_dwordx4 v[84:85], v[80:83], off sc1
	v_or_b32_e32 v144, 0x1800, v114
	v_max_f32_e32 v76, 0, v76
	v_mul_f32_e32 v82, v72, v72
	v_max_f32_e32 v72, 0, v77
	v_mul_f32_e32 v77, v73, v73
	v_max_f32_e32 v73, 0, v78
	v_mul_f32_e32 v78, v74, v74
	v_max_f32_e32 v74, 0, v79
	v_lshl_add_u64 v[80:81], s[8:9], 0, v[144:145]
	v_mul_f32_e32 v76, v76, v76
	v_mul_f32_e32 v72, v72, v72
	v_mul_f32_e32 v73, v73, v73
	v_max_f32_e32 v75, 0, v75
	v_mul_f32_e32 v74, v74, v74
	v_pk_mul_f32 v[66:67], v[160:161], v[66:67] op_sel_hi:[0,1]
	v_pk_mul_f32 v[64:65], v[160:161], v[64:65] op_sel_hi:[0,1]
	v_mul_f32_e32 v75, v75, v75
	v_cvt_pk_bf16_f32 v72, v76, v72
	v_cvt_pk_bf16_f32 v73, v73, v74
	v_cvt_pk_bf16_f32 v74, v82, v77
	v_lshl_add_u64 v[76:77], v[80:81], 0, s[0:1]
	v_pk_mul_f32 v[70:71], v[160:161], v[70:71] op_sel_hi:[0,1]
	v_pk_mul_f32 v[68:69], v[160:161], v[68:69] op_sel_hi:[0,1]
	v_max_f32_e32 v64, 0, v64
	v_max_f32_e32 v65, 0, v65
	v_max_f32_e32 v66, 0, v66
	v_cvt_pk_bf16_f32 v75, v78, v75
	global_store_dwordx4 v[76:77], v[72:75], off sc1
	v_max_f32_e32 v68, 0, v68
	v_mul_f32_e32 v68, v68, v68
	v_mul_f32_e32 v72, v64, v64
	v_max_f32_e32 v64, 0, v69
	v_mul_f32_e32 v69, v65, v65
	v_max_f32_e32 v65, 0, v70
	v_mul_f32_e32 v70, v66, v66
	v_max_f32_e32 v66, 0, v71
	v_mul_f32_e32 v64, v64, v64
	v_mul_f32_e32 v65, v65, v65
	v_max_f32_e32 v67, 0, v67
	v_mul_f32_e32 v66, v66, v66
	v_mul_f32_e32 v67, v67, v67
	v_cvt_pk_bf16_f32 v64, v68, v64
	v_cvt_pk_bf16_f32 v65, v65, v66
	v_cvt_pk_bf16_f32 v66, v72, v69
	v_lshl_add_u64 v[68:69], v[80:81], 0, s[6:7]
	v_cvt_pk_bf16_f32 v67, v70, v67
	global_store_dwordx4 v[68:69], v[64:67], off sc1
	v_pk_mul_f32 v[58:59], v[162:163], v[58:59] op_sel_hi:[0,1]
	v_pk_mul_f32 v[56:57], v[162:163], v[56:57] op_sel_hi:[0,1]
	v_add_u32_e32 v66, 0x80, v165
	v_ashrrev_i32_e32 v64, 8, v66
	v_lshlrev_b32_e32 v67, 6, v66
	v_lshlrev_b32_e32 v66, 5, v66
	v_and_b32_e32 v67, 0x2000, v67
	v_and_b32_e32 v66, 0x1e0, v66
	v_ashrrev_i32_e32 v65, 31, v64
	v_or3_b32 v68, v67, v66, v131
	v_lshlrev_b64 v[64:65], 22, v[64:65]
	v_or_b32_e32 v66, s53, v68
	v_pk_mul_f32 v[62:63], v[162:163], v[62:63] op_sel_hi:[0,1]
	v_pk_mul_f32 v[60:61], v[162:163], v[60:61] op_sel_hi:[0,1]
	v_max_f32_e32 v56, 0, v56
	v_max_f32_e32 v57, 0, v57
	v_max_f32_e32 v58, 0, v58
	v_lshl_add_u64 v[64:65], s[18:19], 0, v[64:65]
	v_lshlrev_b32_e32 v144, 1, v66
	v_max_f32_e32 v60, 0, v60
	v_mul_f32_e32 v69, v56, v56
	v_max_f32_e32 v56, 0, v61
	v_mul_f32_e32 v61, v57, v57
	v_max_f32_e32 v57, 0, v62
	v_mul_f32_e32 v62, v58, v58
	v_max_f32_e32 v58, 0, v63
	v_lshl_add_u64 v[66:67], v[64:65], 0, v[144:145]
	v_mul_f32_e32 v60, v60, v60
	v_mul_f32_e32 v56, v56, v56
	v_mul_f32_e32 v57, v57, v57
	v_max_f32_e32 v59, 0, v59
	v_mul_f32_e32 v58, v58, v58
	v_pk_mul_f32 v[50:51], v[162:163], v[50:51] op_sel_hi:[0,1]
	v_pk_mul_f32 v[48:49], v[162:163], v[48:49] op_sel_hi:[0,1]
	v_mul_f32_e32 v59, v59, v59
	v_cvt_pk_bf16_f32 v56, v60, v56
	v_cvt_pk_bf16_f32 v57, v57, v58
	v_cvt_pk_bf16_f32 v58, v69, v61
	v_lshl_add_u64 v[60:61], v[66:67], 0, s[0:1]
	v_pk_mul_f32 v[54:55], v[162:163], v[54:55] op_sel_hi:[0,1]
	v_pk_mul_f32 v[52:53], v[162:163], v[52:53] op_sel_hi:[0,1]
	v_max_f32_e32 v48, 0, v48
	v_max_f32_e32 v49, 0, v49
	v_max_f32_e32 v50, 0, v50
	v_cvt_pk_bf16_f32 v59, v62, v59
	global_store_dwordx4 v[60:61], v[56:59], off sc1
	v_max_f32_e32 v52, 0, v52
	v_mul_f32_e32 v52, v52, v52
	v_mul_f32_e32 v56, v48, v48
	v_max_f32_e32 v48, 0, v53
	v_mul_f32_e32 v53, v49, v49
	v_max_f32_e32 v49, 0, v54
	v_mul_f32_e32 v54, v50, v50
	v_max_f32_e32 v50, 0, v55
	v_mul_f32_e32 v48, v48, v48
	v_mul_f32_e32 v49, v49, v49
	v_max_f32_e32 v51, 0, v51
	v_mul_f32_e32 v50, v50, v50
	v_mul_f32_e32 v51, v51, v51
	v_cvt_pk_bf16_f32 v48, v52, v48
	v_cvt_pk_bf16_f32 v49, v49, v50
	v_cvt_pk_bf16_f32 v50, v56, v53
	v_lshl_add_u64 v[52:53], v[66:67], 0, s[6:7]
	v_cvt_pk_bf16_f32 v51, v54, v51
	global_store_dwordx4 v[52:53], v[48:51], off sc1
	v_pk_mul_f32 v[42:43], v[164:165], v[42:43] op_sel_hi:[0,1]
	v_pk_mul_f32 v[40:41], v[164:165], v[40:41] op_sel_hi:[0,1]
	v_or_b32_e32 v48, s54, v68
	v_lshlrev_b32_e32 v50, 1, v48
	v_pk_mul_f32 v[46:47], v[164:165], v[46:47] op_sel_hi:[0,1]
	v_pk_mul_f32 v[44:45], v[164:165], v[44:45] op_sel_hi:[0,1]
	v_max_f32_e32 v40, 0, v40
	v_max_f32_e32 v41, 0, v41
	v_max_f32_e32 v42, 0, v42
	v_or_b32_e32 v144, 0x800, v50
	v_max_f32_e32 v44, 0, v44
; __host__ __device__ __forceinline__ int blk_off(int r, int c) { const int rr = r & 127; return (r >> 7) * 8192 + (((rr >> 4) * 2 + (c >> 5)) * 512) + (rr & 15) * 32 + (c & 31); }
; __device__ __forceinline__ unsigned cvt_pk_bf16(float lo, float hi) { unsigned r; asm volatile("v_cvt_pk_bf16_f32 %0, %1, %2" : "=v"(r) : "v"(lo), "v"(hi)); return r; }
;     __device__ __forceinline__ void operator()(const f32x4 (&acc)[2][2][4][2], const State& st, const Unit& u, int wr, int wc, int fr, int fq) const {
;     ...
;         for (int ai = 0; ai < 2; ++ai)
; #pragma unroll
;             for (int m = 0; m < 4; ++m) { const int row = row0 + ai * HALF + m * 16;
;                 const float rs = rsv[ai][m];
;                 bf16_t* rowp = O + (size_t)(row >> 8) * (ldc >> 6) * (256 * 64);
; #pragma unroll
;                 for (int bj = 0; bj < 2; ++bj) { f32x4 v0 = acc[ai][bj][m][0] * rs, v1 = acc[ai][bj][m][1] * rs;
; #pragma unroll
;                     for (int e = 0; e < 4; ++e) { const float a = fmaxf(v0[e], 0.f), b = fmaxf(v1[e], 0.f); v0[e] = a * a; v1[e] = b * b; }
;                     u32x4 w; w.x = cvt_pk_bf16(v0[0], v0[1]); w.y = cvt_pk_bf16(v0[2], v0[3]); w.z = cvt_pk_bf16(v1[0], v1[1]); w.w = cvt_pk_bf16(v1[2], v1[3]);
;                     { const int col = col0 + bj * HALF; *(u32x4*)(rowp + (size_t)(col >> 6) * (256 * 64) + blk_off(row & 255, col & 63)) = w; } } }
	v_mul_f32_e32 v51, v40, v40
	v_max_f32_e32 v40, 0, v45
	v_mul_f32_e32 v45, v41, v41
	v_max_f32_e32 v41, 0, v46
	v_mul_f32_e32 v46, v42, v42
	v_max_f32_e32 v42, 0, v47
	v_lshl_add_u64 v[48:49], v[64:65], 0, v[144:145]
	v_mul_f32_e32 v44, v44, v44
	v_mul_f32_e32 v40, v40, v40
	v_mul_f32_e32 v41, v41, v41
	v_max_f32_e32 v43, 0, v43
	v_mul_f32_e32 v42, v42, v42
	v_pk_mul_f32 v[34:35], v[164:165], v[34:35] op_sel_hi:[0,1]
	v_pk_mul_f32 v[32:33], v[164:165], v[32:33] op_sel_hi:[0,1]
	v_mul_f32_e32 v43, v43, v43
	v_cvt_pk_bf16_f32 v40, v44, v40
	v_cvt_pk_bf16_f32 v41, v41, v42
	v_cvt_pk_bf16_f32 v42, v51, v45
	v_lshl_add_u64 v[44:45], v[48:49], 0, s[0:1]
	v_pk_mul_f32 v[38:39], v[164:165], v[38:39] op_sel_hi:[0,1]
	v_pk_mul_f32 v[36:37], v[164:165], v[36:37] op_sel_hi:[0,1]
	v_max_f32_e32 v32, 0, v32
	v_max_f32_e32 v33, 0, v33
	v_max_f32_e32 v34, 0, v34
	v_cvt_pk_bf16_f32 v43, v46, v43
	global_store_dwordx4 v[44:45], v[40:43], off sc1
	v_max_f32_e32 v36, 0, v36
	v_mul_f32_e32 v36, v36, v36
	v_mul_f32_e32 v40, v32, v32
	v_max_f32_e32 v32, 0, v37
	v_mul_f32_e32 v37, v33, v33
	v_max_f32_e32 v33, 0, v38
	v_mul_f32_e32 v38, v34, v34
	v_max_f32_e32 v34, 0, v39
	v_mul_f32_e32 v32, v32, v32
	v_mul_f32_e32 v33, v33, v33
	v_max_f32_e32 v35, 0, v35
	v_mul_f32_e32 v34, v34, v34
	v_pk_mul_f32 v[26:27], v[166:167], v[26:27] op_sel_hi:[0,1]
	v_pk_mul_f32 v[24:25], v[166:167], v[24:25] op_sel_hi:[0,1]
	v_mul_f32_e32 v35, v35, v35
	v_cvt_pk_bf16_f32 v32, v36, v32
	v_cvt_pk_bf16_f32 v33, v33, v34
	v_cvt_pk_bf16_f32 v34, v40, v37
	v_lshl_add_u64 v[36:37], v[48:49], 0, s[6:7]
	v_pk_mul_f32 v[30:31], v[166:167], v[30:31] op_sel_hi:[0,1]
	v_pk_mul_f32 v[28:29], v[166:167], v[28:29] op_sel_hi:[0,1]
	v_max_f32_e32 v24, 0, v24
	v_max_f32_e32 v25, 0, v25
	v_max_f32_e32 v26, 0, v26
	v_cvt_pk_bf16_f32 v35, v38, v35
	global_store_dwordx4 v[36:37], v[32:35], off sc1
	v_max_f32_e32 v28, 0, v28
	v_mul_f32_e32 v28, v28, v28
	v_mul_f32_e32 v34, v24, v24
	v_max_f32_e32 v24, 0, v29
	v_mul_f32_e32 v29, v25, v25
	v_max_f32_e32 v25, 0, v30
	v_mul_f32_e32 v30, v26, v26
	v_max_f32_e32 v26, 0, v31
	v_lshl_add_u64 v[32:33], v[66:67], 0, s[12:13]
	v_mul_f32_e32 v24, v24, v24
	v_mul_f32_e32 v25, v25, v25
	v_max_f32_e32 v27, 0, v27
	v_mul_f32_e32 v26, v26, v26
	v_pk_mul_f32 v[18:19], v[166:167], v[18:19] op_sel_hi:[0,1]
	v_pk_mul_f32 v[16:17], v[166:167], v[16:17] op_sel_hi:[0,1]
	v_mul_f32_e32 v27, v27, v27
	v_cvt_pk_bf16_f32 v24, v28, v24
	v_cvt_pk_bf16_f32 v25, v25, v26
	v_cvt_pk_bf16_f32 v26, v34, v29
	v_lshl_add_u64 v[28:29], v[32:33], 0, s[0:1]
	v_pk_mul_f32 v[22:23], v[166:167], v[22:23] op_sel_hi:[0,1]
	v_pk_mul_f32 v[20:21], v[166:167], v[20:21] op_sel_hi:[0,1]
	v_max_f32_e32 v16, 0, v16
	v_max_f32_e32 v17, 0, v17
	v_max_f32_e32 v18, 0, v18
	v_cvt_pk_bf16_f32 v27, v30, v27
	global_store_dwordx4 v[28:29], v[24:27], off sc1
	v_max_f32_e32 v20, 0, v20
	v_mul_f32_e32 v20, v20, v20
	v_mul_f32_e32 v24, v16, v16
	v_max_f32_e32 v16, 0, v21
	v_mul_f32_e32 v21, v17, v17
	v_max_f32_e32 v17, 0, v22
	v_mul_f32_e32 v22, v18, v18
	v_max_f32_e32 v18, 0, v23
	v_mul_f32_e32 v16, v16, v16
	v_mul_f32_e32 v17, v17, v17
	v_max_f32_e32 v19, 0, v19
	v_mul_f32_e32 v18, v18, v18
	v_pk_mul_f32 v[10:11], v[168:169], v[10:11] op_sel_hi:[0,1]
	v_pk_mul_f32 v[8:9], v[168:169], v[8:9] op_sel_hi:[0,1]
	v_mul_f32_e32 v19, v19, v19
	v_cvt_pk_bf16_f32 v16, v20, v16
	v_cvt_pk_bf16_f32 v17, v17, v18
	v_cvt_pk_bf16_f32 v18, v24, v21
	v_lshl_add_u64 v[20:21], v[32:33], 0, s[6:7]
	v_pk_mul_f32 v[14:15], v[168:169], v[14:15] op_sel_hi:[0,1]
	v_pk_mul_f32 v[12:13], v[168:169], v[12:13] op_sel_hi:[0,1]
	v_max_f32_e32 v8, 0, v8
	v_max_f32_e32 v9, 0, v9
	v_max_f32_e32 v10, 0, v10
	v_cvt_pk_bf16_f32 v19, v22, v19
	global_store_dwordx4 v[20:21], v[16:19], off sc1
	v_or_b32_e32 v144, 0x1800, v50
	v_max_f32_e32 v12, 0, v12
	v_mul_f32_e32 v18, v8, v8
	v_max_f32_e32 v8, 0, v13
	v_mul_f32_e32 v13, v9, v9
	v_max_f32_e32 v9, 0, v14
	v_mul_f32_e32 v14, v10, v10
	v_max_f32_e32 v10, 0, v15
	v_lshl_add_u64 v[16:17], v[64:65], 0, v[144:145]
	v_mul_f32_e32 v12, v12, v12
	v_mul_f32_e32 v8, v8, v8
	v_mul_f32_e32 v9, v9, v9
	v_max_f32_e32 v11, 0, v11
	v_mul_f32_e32 v10, v10, v10
	v_pk_mul_f32 v[2:3], v[168:169], v[2:3] op_sel_hi:[0,1]
	v_pk_mul_f32 v[0:1], v[168:169], v[0:1] op_sel_hi:[0,1]
	v_mul_f32_e32 v11, v11, v11
	v_cvt_pk_bf16_f32 v8, v12, v8
	v_cvt_pk_bf16_f32 v9, v9, v10
	v_cvt_pk_bf16_f32 v10, v18, v13
	v_lshl_add_u64 v[12:13], v[16:17], 0, s[0:1]
	v_pk_mul_f32 v[6:7], v[168:169], v[6:7] op_sel_hi:[0,1]
	v_pk_mul_f32 v[4:5], v[168:169], v[4:5] op_sel_hi:[0,1]
	v_max_f32_e32 v0, 0, v0
	v_max_f32_e32 v1, 0, v1
	v_max_f32_e32 v2, 0, v2
	v_cvt_pk_bf16_f32 v11, v14, v11
	global_store_dwordx4 v[12:13], v[8:11], off sc1
	v_max_f32_e32 v4, 0, v4
	v_mul_f32_e32 v4, v4, v4
	v_mul_f32_e32 v8, v0, v0
	v_max_f32_e32 v0, 0, v5
	v_mul_f32_e32 v5, v1, v1
	v_max_f32_e32 v1, 0, v6
	v_mul_f32_e32 v6, v2, v2
	v_max_f32_e32 v2, 0, v7
	v_mul_f32_e32 v0, v0, v0
	v_mul_f32_e32 v1, v1, v1
	v_max_f32_e32 v3, 0, v3
	v_mul_f32_e32 v2, v2, v2
	v_mul_f32_e32 v3, v3, v3
	v_cvt_pk_bf16_f32 v0, v4, v0
	v_cvt_pk_bf16_f32 v1, v1, v2
	v_cvt_pk_bf16_f32 v2, v8, v5
	v_lshl_add_u64 v[4:5], v[16:17], 0, s[6:7]
	s_andn2_b64 vcc, exec, s[38:39]
	s_mov_b64 s[0:1], -1
	v_cvt_pk_bf16_f32 v3, v6, v3
	global_store_dwordx4 v[4:5], v[0:3], off sc1
	s_cbranch_vccnz .LBB0_545
	s_cmp_eq_u32 s56, s40
	s_cbranch_scc1 .LBB0_559
; __device__ __forceinline__ void rows_rstd(float (&rs)[2][4], const float* ssq, int row0, int fq) {
;     f32x4 pa[2][4], pb[2][4];
; #pragma unroll
;     for (int ai = 0; ai < 2; ++ai)
; #pragma unroll
;         for (int m = 0; m < 4; ++m) { const f32x4* p = (const f32x4*)(ssq + (size_t)(row0 + ai * HALF + m * 16) * 32 + 8 * fq); pa[ai][m] = p[0]; pb[ai][m] = p[1]; }
; #pragma unroll
;     for (int ai = 0; ai < 2; ++ai)
; #pragma unroll
;         for (int m = 0; m < 4; ++m) { const f32x4 a = pa[ai][m] + pb[ai][m]; float t = (a[0] + a[1]) + (a[2] + a[3]);
;             t += __shfl_xor(t, 16); t += __shfl_xor(t, 32); rs[ai][m] = 1.0f / sqrtf(t * (1.0f / 2048.0f) + RMS_EPS); }
; }
;     __device__ __forceinline__ void init(f32x4 (&acc)[2][2][4][2], State& st, const Unit& u, int wr, int, int fr, int fq) const { zero_acc(acc);
;         if (st.pm != u.pm) { float t[2][4]; rows_rstd(t, ssq, u.pm * BM + wr * 64 + fr, fq); st.ra = (f32x4){t[0][0], t[0][1], t[0][2], t[0][3]}; st.rb = (f32x4){t[1][0], t[1][1], t[1][2], t[1][3]}; st.pm = u.pm; } }
	v_lshl_add_u32 v0, s40, 8, v143
	v_ashrrev_i32_e32 v1, 31, v0
	v_lshlrev_b64 v[2:3], 7, v[0:1]
	v_lshl_add_u64 v[2:3], v[136:137], 0, v[2:3]
	global_load_dwordx4 v[58:61], v[2:3], off
	global_load_dwordx4 v[62:65], v[2:3], off offset:16
	v_or_b32_e32 v4, 16, v0
	v_ashrrev_i32_e32 v5, 31, v4
	v_lshlrev_b64 v[4:5], 7, v[4:5]
	v_lshl_add_u64 v[4:5], v[136:137], 0, v[4:5]
	global_load_dwordx4 v[48:51], v[4:5], off
	global_load_dwordx4 v[52:55], v[4:5], off offset:16
	v_or_b32_e32 v4, 32, v0
	v_ashrrev_i32_e32 v5, 31, v4
	v_lshlrev_b64 v[4:5], 7, v[4:5]
	v_lshl_add_u64 v[4:5], v[136:137], 0, v[4:5]
	global_load_dwordx4 v[40:43], v[4:5], off
	global_load_dwordx4 v[44:47], v[4:5], off offset:16
	v_or_b32_e32 v0, 48, v0
	v_ashrrev_i32_e32 v1, 31, v0
	v_lshlrev_b64 v[0:1], 7, v[0:1]
	v_lshl_add_u64 v[0:1], v[136:137], 0, v[0:1]
	s_mov_b64 s[0:1], 0x4000
	global_load_dwordx4 v[32:35], v[0:1], off
	global_load_dwordx4 v[36:39], v[0:1], off offset:16
	v_lshl_add_u64 v[0:1], v[2:3], 0, s[0:1]
	s_movk_i32 s0, 0x4000
	v_add_co_u32_e32 v4, vcc, s0, v2
	s_movk_i32 s0, 0x5000
	s_nop 0
	v_addc_co_u32_e32 v5, vcc, 0, v3, vcc
	v_add_co_u32_e32 v6, vcc, s0, v2
	s_mov_b64 s[0:1], 0x4800
	s_nop 0
	v_addc_co_u32_e32 v7, vcc, 0, v3, vcc
	v_cmp_lt_i32_e32 vcc, v191, v192
	global_load_dwordx4 v[24:27], v[6:7], off offset:-4096
	global_load_dwordx4 v[28:31], v[0:1], off offset:16
	v_cndmask_b32_e32 v56, v190, v191, vcc
	v_lshlrev_b32_e32 v56, 2, v56
	v_cmp_lt_i32_e32 vcc, v193, v192
	v_lshl_add_u64 v[0:1], v[2:3], 0, s[0:1]
	s_mov_b64 s[0:1], 0x5000
	v_cndmask_b32_e32 v57, v190, v193, vcc
	v_lshlrev_b32_e32 v57, 2, v57
	global_load_dwordx4 v[16:19], v[4:5], off offset:2048
	global_load_dwordx4 v[20:23], v[0:1], off offset:16
	v_lshl_add_u64 v[0:1], v[2:3], 0, s[0:1]
	s_mov_b64 s[0:1], 0x5800
	v_lshl_add_u64 v[4:5], v[2:3], 0, s[0:1]
	global_load_dwordx4 v[8:11], v[6:7], off
	global_load_dwordx4 v[12:15], v[0:1], off offset:16
	s_nop 0
	global_load_dwordx4 v[0:3], v[6:7], off offset:2048
	s_nop 0
	global_load_dwordx4 v[4:7], v[4:5], off offset:16
	s_mov_b32 s56, s40
	s_waitcnt vmcnt(0)
	v_pk_add_f32 v[60:61], v[60:61], v[64:65]
	v_pk_add_f32 v[58:59], v[58:59], v[62:63]
	v_pk_add_f32 v[50:51], v[50:51], v[54:55]
	v_pk_mov_b32 v[62:63], v[58:59], v[60:61] op_sel:[1,0]
	v_mov_b32_e32 v59, v61
	v_pk_add_f32 v[58:59], v[62:63], v[58:59]
	v_pk_add_f32 v[48:49], v[48:49], v[52:53]
	v_add_f32_e32 v58, v58, v59
	ds_bpermute_b32 v59, v56, v58
	v_pk_mov_b32 v[52:53], v[48:49], v[50:51] op_sel:[1,0]
	v_mov_b32_e32 v49, v51
	v_pk_add_f32 v[48:49], v[52:53], v[48:49]
	v_pk_add_f32 v[42:43], v[42:43], v[46:47]
	s_waitcnt lgkmcnt(0)
	v_add_f32_e32 v58, v58, v59
	ds_bpermute_b32 v59, v57, v58
	v_add_f32_e32 v48, v48, v49
	ds_bpermute_b32 v49, v56, v48
	v_pk_add_f32 v[40:41], v[40:41], v[44:45]
	v_pk_add_f32 v[34:35], v[34:35], v[38:39]
	s_waitcnt lgkmcnt(1)
	v_add_f32_e32 v58, v58, v59
	v_fmamk_f32 v58, v58, 0x3a000000, v186
	v_cmp_gt_f32_e32 vcc, s65, v58
	v_mul_f32_e32 v59, 0x4f800000, v58
	s_waitcnt lgkmcnt(0)
	v_add_f32_e32 v48, v48, v49
	v_cndmask_b32_e32 v58, v58, v59, vcc
	v_sqrt_f32_e32 v59, v58
	ds_bpermute_b32 v49, v57, v48
	v_pk_mov_b32 v[44:45], v[40:41], v[42:43] op_sel:[1,0]
	v_mov_b32_e32 v41, v43
	v_add_u32_e32 v60, -1, v59
	v_fma_f32 v61, -v60, v59, v58
	v_cmp_ge_f32_e64 s[38:39], 0, v61
	v_add_u32_e32 v61, 1, v59
	s_waitcnt lgkmcnt(0)
	v_add_f32_e32 v48, v48, v49
	v_cndmask_b32_e64 v60, v59, v60, s[38:39]
	v_fma_f32 v59, -v61, v59, v58
	v_cmp_lt_f32_e64 s[38:39], 0, v59
	v_fmamk_f32 v48, v48, 0x3a000000, v186
	v_mul_f32_e32 v49, 0x4f800000, v48
	v_cndmask_b32_e64 v59, v60, v61, s[38:39]
	v_mul_f32_e32 v60, 0x37800000, v59
	v_cndmask_b32_e32 v59, v59, v60, vcc
	v_cmp_class_f32_e32 vcc, v58, v187
	v_pk_add_f32 v[40:41], v[44:45], v[40:41]
	v_pk_add_f32 v[32:33], v[32:33], v[36:37]
	v_cndmask_b32_e32 v58, v59, v58, vcc
	v_div_scale_f32 v59, s[0:1], v58, v58, 1.0
	v_rcp_f32_e32 v60, v59
	v_add_f32_e32 v40, v40, v41
	ds_bpermute_b32 v41, v56, v40
	v_pk_mov_b32 v[36:37], v[32:33], v[34:35] op_sel:[1,0]
	v_fma_f32 v61, -v59, v60, 1.0
	v_fmac_f32_e32 v60, v61, v60
	v_div_scale_f32 v61, vcc, 1.0, v58, 1.0
	v_mul_f32_e32 v62, v61, v60
	v_fma_f32 v63, -v59, v62, v61
	v_fmac_f32_e32 v62, v63, v60
	v_fma_f32 v59, -v59, v62, v61
	v_div_fmas_f32 v59, v59, v60, v62
	v_cmp_gt_f32_e32 vcc, s65, v48
	s_waitcnt lgkmcnt(0)
	v_add_f32_e32 v40, v40, v41
	ds_bpermute_b32 v41, v57, v40
	v_cndmask_b32_e32 v48, v48, v49, vcc
	v_sqrt_f32_e32 v49, v48
	v_mov_b32_e32 v33, v35
	v_pk_add_f32 v[32:33], v[36:37], v[32:33]
	s_waitcnt lgkmcnt(0)
	v_add_f32_e32 v40, v40, v41
	v_add_u32_e32 v50, -1, v49
	v_fma_f32 v51, -v50, v49, v48
	v_cmp_ge_f32_e64 s[38:39], 0, v51
	v_add_u32_e32 v51, 1, v49
	v_fmamk_f32 v40, v40, 0x3a000000, v186
	v_cndmask_b32_e64 v50, v49, v50, s[38:39]
	v_fma_f32 v49, -v51, v49, v48
	v_cmp_lt_f32_e64 s[38:39], 0, v49
	v_mul_f32_e32 v41, 0x4f800000, v40
	v_add_f32_e32 v32, v32, v33
	v_cndmask_b32_e64 v49, v50, v51, s[38:39]
	v_mul_f32_e32 v50, 0x37800000, v49
	v_cndmask_b32_e32 v49, v49, v50, vcc
	v_cmp_class_f32_e32 vcc, v48, v187
	ds_bpermute_b32 v33, v56, v32
	v_pk_add_f32 v[26:27], v[26:27], v[30:31]
	v_cndmask_b32_e32 v48, v49, v48, vcc
	v_div_scale_f32 v49, s[0:1], v48, v48, 1.0
	v_rcp_f32_e32 v50, v49
	s_waitcnt lgkmcnt(0)
	v_add_f32_e32 v32, v32, v33
	ds_bpermute_b32 v33, v57, v32
	v_pk_add_f32 v[24:25], v[24:25], v[28:29]
	v_fma_f32 v51, -v49, v50, 1.0
	v_fmac_f32_e32 v50, v51, v50
	v_div_scale_f32 v51, vcc, 1.0, v48, 1.0
	v_mul_f32_e32 v52, v51, v50
	v_fma_f32 v53, -v49, v52, v51
	v_fmac_f32_e32 v52, v53, v50
	v_fma_f32 v49, -v49, v52, v51
	v_div_fmas_f32 v49, v49, v50, v52
	v_cmp_gt_f32_e32 vcc, s65, v40
	s_waitcnt lgkmcnt(0)
; __device__ __forceinline__ void rows_rstd(float (&rs)[2][4], const float* ssq, int row0, int fq) {
;     f32x4 pa[2][4], pb[2][4];
; #pragma unroll
;     for (int ai = 0; ai < 2; ++ai)
; #pragma unroll
;         for (int m = 0; m < 4; ++m) { const f32x4* p = (const f32x4*)(ssq + (size_t)(row0 + ai * HALF + m * 16) * 32 + 8 * fq); pa[ai][m] = p[0]; pb[ai][m] = p[1]; }
; #pragma unroll
;     for (int ai = 0; ai < 2; ++ai)
; #pragma unroll
;         for (int m = 0; m < 4; ++m) { const f32x4 a = pa[ai][m] + pb[ai][m]; float t = (a[0] + a[1]) + (a[2] + a[3]);
;             t += __shfl_xor(t, 16); t += __shfl_xor(t, 32); rs[ai][m] = 1.0f / sqrtf(t * (1.0f / 2048.0f) + RMS_EPS); }
; }
	v_add_f32_e32 v32, v32, v33
	v_fmamk_f32 v32, v32, 0x3a000000, v186
	v_cndmask_b32_e32 v40, v40, v41, vcc
	v_sqrt_f32_e32 v41, v40
	v_mul_f32_e32 v33, 0x4f800000, v32
	v_pk_mov_b32 v[28:29], v[24:25], v[26:27] op_sel:[1,0]
	v_mov_b32_e32 v25, v27
	v_add_u32_e32 v42, -1, v41
	v_fma_f32 v43, -v42, v41, v40
	v_cmp_ge_f32_e64 s[38:39], 0, v43
	v_add_u32_e32 v43, 1, v41
	v_pk_add_f32 v[24:25], v[28:29], v[24:25]
	v_cndmask_b32_e64 v42, v41, v42, s[38:39]
	v_fma_f32 v41, -v43, v41, v40
	v_cmp_lt_f32_e64 s[38:39], 0, v41
	v_add_f32_e32 v24, v24, v25
	ds_bpermute_b32 v25, v56, v24
	v_cndmask_b32_e64 v41, v42, v43, s[38:39]
	v_mul_f32_e32 v42, 0x37800000, v41
	v_cndmask_b32_e32 v41, v41, v42, vcc
	v_cmp_class_f32_e32 vcc, v40, v187
	s_waitcnt lgkmcnt(0)
	v_add_f32_e32 v24, v24, v25
	ds_bpermute_b32 v25, v57, v24
	v_cndmask_b32_e32 v40, v41, v40, vcc
	v_div_scale_f32 v41, s[0:1], v40, v40, 1.0
	v_rcp_f32_e32 v42, v41
	s_waitcnt lgkmcnt(0)
	v_add_f32_e32 v24, v24, v25
	v_fmamk_f32 v24, v24, 0x3a000000, v186
	v_mul_f32_e32 v25, 0x4f800000, v24
	v_fma_f32 v43, -v41, v42, 1.0
	v_fmac_f32_e32 v42, v43, v42
	v_div_scale_f32 v43, vcc, 1.0, v40, 1.0
	v_mul_f32_e32 v44, v43, v42
	v_fma_f32 v45, -v41, v44, v43
	v_fmac_f32_e32 v44, v45, v42
	v_fma_f32 v41, -v41, v44, v43
	v_div_fmas_f32 v41, v41, v42, v44
	v_cmp_gt_f32_e32 vcc, s65, v32
	v_pk_add_f32 v[18:19], v[18:19], v[22:23]
	v_pk_add_f32 v[16:17], v[16:17], v[20:21]
	v_cndmask_b32_e32 v32, v32, v33, vcc
	v_sqrt_f32_e32 v33, v32
	v_pk_mov_b32 v[20:21], v[16:17], v[18:19] op_sel:[1,0]
	v_mov_b32_e32 v17, v19
	v_pk_add_f32 v[16:17], v[20:21], v[16:17]
	v_add_u32_e32 v34, -1, v33
	v_fma_f32 v35, -v34, v33, v32
	v_cmp_ge_f32_e64 s[38:39], 0, v35
	v_add_u32_e32 v35, 1, v33
	v_add_f32_e32 v16, v16, v17
	v_cndmask_b32_e64 v34, v33, v34, s[38:39]
	v_fma_f32 v33, -v35, v33, v32
	v_cmp_lt_f32_e64 s[38:39], 0, v33
	ds_bpermute_b32 v17, v56, v16
	v_pk_add_f32 v[10:11], v[10:11], v[14:15]
	v_cndmask_b32_e64 v33, v34, v35, s[38:39]
	v_mul_f32_e32 v34, 0x37800000, v33
	v_cndmask_b32_e32 v33, v33, v34, vcc
	v_cmp_class_f32_e32 vcc, v32, v187
	s_waitcnt lgkmcnt(0)
	v_add_f32_e32 v16, v16, v17
	ds_bpermute_b32 v17, v57, v16
	v_cndmask_b32_e32 v32, v33, v32, vcc
	v_div_scale_f32 v33, s[0:1], v32, v32, 1.0
	v_rcp_f32_e32 v34, v33
	s_waitcnt lgkmcnt(0)
	v_add_f32_e32 v16, v16, v17
	v_fmamk_f32 v16, v16, 0x3a000000, v186
	v_mul_f32_e32 v17, 0x4f800000, v16
	v_fma_f32 v35, -v33, v34, 1.0
	v_fmac_f32_e32 v34, v35, v34
	v_div_scale_f32 v35, vcc, 1.0, v32, 1.0
	v_mul_f32_e32 v36, v35, v34
	v_fma_f32 v37, -v33, v36, v35
	v_fmac_f32_e32 v36, v37, v34
	v_fma_f32 v33, -v33, v36, v35
	v_div_fmas_f32 v33, v33, v34, v36
	v_cmp_gt_f32_e32 vcc, s65, v24
	v_pk_add_f32 v[8:9], v[8:9], v[12:13]
	v_pk_add_f32 v[2:3], v[2:3], v[6:7]
	v_cndmask_b32_e32 v24, v24, v25, vcc
	v_sqrt_f32_e32 v25, v24
	v_pk_mov_b32 v[12:13], v[8:9], v[10:11] op_sel:[1,0]
	v_mov_b32_e32 v9, v11
	v_pk_add_f32 v[8:9], v[12:13], v[8:9]
	v_add_u32_e32 v26, -1, v25
	v_fma_f32 v27, -v26, v25, v24
	v_cmp_ge_f32_e64 s[38:39], 0, v27
	v_add_u32_e32 v27, 1, v25
	v_add_f32_e32 v8, v8, v9
	v_cndmask_b32_e64 v26, v25, v26, s[38:39]
	v_fma_f32 v25, -v27, v25, v24
	v_cmp_lt_f32_e64 s[38:39], 0, v25
	ds_bpermute_b32 v9, v56, v8
	v_pk_add_f32 v[0:1], v[0:1], v[4:5]
	v_cndmask_b32_e64 v25, v26, v27, s[38:39]
	v_mul_f32_e32 v26, 0x37800000, v25
	v_cndmask_b32_e32 v25, v25, v26, vcc
	v_cmp_class_f32_e32 vcc, v24, v187
	s_waitcnt lgkmcnt(0)
	v_add_f32_e32 v8, v8, v9
	ds_bpermute_b32 v9, v57, v8
	v_cndmask_b32_e32 v24, v25, v24, vcc
	v_div_scale_f32 v25, s[0:1], v24, v24, 1.0
	v_rcp_f32_e32 v26, v25
	s_waitcnt lgkmcnt(0)
; __device__ __forceinline__ void rows_rstd(float (&rs)[2][4], const float* ssq, int row0, int fq) {
;     f32x4 pa[2][4], pb[2][4];
; #pragma unroll
;     for (int ai = 0; ai < 2; ++ai)
; #pragma unroll
;         for (int m = 0; m < 4; ++m) { const f32x4* p = (const f32x4*)(ssq + (size_t)(row0 + ai * HALF + m * 16) * 32 + 8 * fq); pa[ai][m] = p[0]; pb[ai][m] = p[1]; }
; #pragma unroll
;     for (int ai = 0; ai < 2; ++ai)
; #pragma unroll
;         for (int m = 0; m < 4; ++m) { const f32x4 a = pa[ai][m] + pb[ai][m]; float t = (a[0] + a[1]) + (a[2] + a[3]);
;             t += __shfl_xor(t, 16); t += __shfl_xor(t, 32); rs[ai][m] = 1.0f / sqrtf(t * (1.0f / 2048.0f) + RMS_EPS); }
; }
	v_add_f32_e32 v8, v8, v9
	v_fmamk_f32 v8, v8, 0x3a000000, v186
	v_mul_f32_e32 v9, 0x4f800000, v8
	v_fma_f32 v27, -v25, v26, 1.0
	v_fmac_f32_e32 v26, v27, v26
	v_div_scale_f32 v27, vcc, 1.0, v24, 1.0
	v_mul_f32_e32 v28, v27, v26
	v_fma_f32 v29, -v25, v28, v27
	v_fmac_f32_e32 v28, v29, v26
	v_fma_f32 v25, -v25, v28, v27
	v_div_fmas_f32 v25, v25, v26, v28
	v_cmp_gt_f32_e32 vcc, s65, v16
	v_pk_mov_b32 v[4:5], v[0:1], v[2:3] op_sel:[1,0]
	v_mov_b32_e32 v1, v3
	v_cndmask_b32_e32 v16, v16, v17, vcc
	v_sqrt_f32_e32 v17, v16
	v_pk_add_f32 v[0:1], v[4:5], v[0:1]
	v_div_fixup_f32 v128, v59, v58, 1.0
	v_add_f32_e32 v0, v0, v1
	v_add_u32_e32 v18, -1, v17
	v_fma_f32 v19, -v18, v17, v16
	v_cmp_ge_f32_e64 s[38:39], 0, v19
	v_add_u32_e32 v19, 1, v17
	ds_bpermute_b32 v1, v56, v0
	v_cndmask_b32_e64 v18, v17, v18, s[38:39]
	v_fma_f32 v17, -v19, v17, v16
	v_cmp_lt_f32_e64 s[38:39], 0, v17
	v_div_fixup_f32 v130, v49, v48, 1.0
	s_waitcnt lgkmcnt(0)
	v_add_f32_e32 v0, v0, v1
	v_cndmask_b32_e64 v17, v18, v19, s[38:39]
	v_mul_f32_e32 v18, 0x37800000, v17
	v_cndmask_b32_e32 v17, v17, v18, vcc
	v_cmp_class_f32_e32 vcc, v16, v187
	ds_bpermute_b32 v1, v57, v0
	v_div_fixup_f32 v142, v41, v40, 1.0
	v_cndmask_b32_e32 v16, v17, v16, vcc
	v_div_scale_f32 v17, s[0:1], v16, v16, 1.0
	v_rcp_f32_e32 v18, v17
	s_waitcnt lgkmcnt(0)
	v_add_f32_e32 v0, v0, v1
	v_fmamk_f32 v0, v0, 0x3a000000, v186
	v_mul_f32_e32 v1, 0x4f800000, v0
	v_fma_f32 v19, -v17, v18, 1.0
	v_fmac_f32_e32 v18, v19, v18
	v_div_scale_f32 v19, vcc, 1.0, v16, 1.0
	v_mul_f32_e32 v20, v19, v18
	v_fma_f32 v21, -v17, v20, v19
	v_fmac_f32_e32 v20, v21, v18
	v_fma_f32 v17, -v17, v20, v19
	v_div_fmas_f32 v17, v17, v18, v20
	v_cmp_gt_f32_e32 vcc, s65, v8
	v_div_fixup_f32 v160, v33, v32, 1.0
	v_div_fixup_f32 v162, v25, v24, 1.0
	v_cndmask_b32_e32 v8, v8, v9, vcc
	v_sqrt_f32_e32 v9, v8
	v_div_fixup_f32 v164, v17, v16, 1.0
	v_add_u32_e32 v10, -1, v9
	v_fma_f32 v11, -v10, v9, v8
	v_cmp_ge_f32_e64 s[38:39], 0, v11
	v_add_u32_e32 v11, 1, v9
	s_nop 0
	v_cndmask_b32_e64 v10, v9, v10, s[38:39]
	v_fma_f32 v9, -v11, v9, v8
	v_cmp_lt_f32_e64 s[38:39], 0, v9
	s_nop 1
	v_cndmask_b32_e64 v9, v10, v11, s[38:39]
	v_mul_f32_e32 v10, 0x37800000, v9
	v_cndmask_b32_e32 v9, v9, v10, vcc
	v_cmp_class_f32_e32 vcc, v8, v187
	s_nop 1
	v_cndmask_b32_e32 v8, v9, v8, vcc
	v_div_scale_f32 v9, s[0:1], v8, v8, 1.0
	v_rcp_f32_e32 v10, v9
	s_nop 0
	v_fma_f32 v11, -v9, v10, 1.0
	v_fmac_f32_e32 v10, v11, v10
	v_div_scale_f32 v11, vcc, 1.0, v8, 1.0
	v_mul_f32_e32 v12, v11, v10
	v_fma_f32 v13, -v9, v12, v11
	v_fmac_f32_e32 v12, v13, v10
	v_fma_f32 v9, -v9, v12, v11
	v_div_fmas_f32 v9, v9, v10, v12
	v_cmp_gt_f32_e32 vcc, s65, v0
	v_div_fixup_f32 v166, v9, v8, 1.0
	s_nop 0
	v_cndmask_b32_e32 v0, v0, v1, vcc
	v_sqrt_f32_e32 v1, v0
	s_nop 0
	v_add_u32_e32 v2, -1, v1
	v_fma_f32 v3, -v2, v1, v0
	v_cmp_ge_f32_e64 s[38:39], 0, v3
	v_add_u32_e32 v3, 1, v1
	s_nop 0
	v_cndmask_b32_e64 v2, v1, v2, s[38:39]
	v_fma_f32 v1, -v3, v1, v0
	v_cmp_lt_f32_e64 s[38:39], 0, v1
	s_nop 1
	v_cndmask_b32_e64 v1, v2, v3, s[38:39]
	v_mul_f32_e32 v2, 0x37800000, v1
	v_cndmask_b32_e32 v1, v1, v2, vcc
	v_cmp_class_f32_e32 vcc, v0, v187
	s_nop 1
	v_cndmask_b32_e32 v0, v1, v0, vcc
	v_div_scale_f32 v1, s[0:1], v0, v0, 1.0
	v_rcp_f32_e32 v2, v1
	s_nop 0
	v_fma_f32 v3, -v1, v2, 1.0
	v_fmac_f32_e32 v2, v3, v2
	v_div_scale_f32 v3, vcc, 1.0, v0, 1.0
	v_mul_f32_e32 v4, v3, v2
	v_fma_f32 v5, -v1, v4, v3
	v_fmac_f32_e32 v4, v5, v2
	v_fma_f32 v1, -v1, v4, v3
	v_div_fmas_f32 v1, v1, v2, v4
	v_div_fixup_f32 v168, v1, v0, 1.0

; #define PG8_STAGE(bufoff, gbase, voff) do { _Pragma("unroll") for (int _i = 0; _i < 2; ++_i) \
;         __builtin_amdgcn_global_load_lds((const unsigned*)((const char*)(gbase) + (voff)[_i]), (PG8_LAS unsigned*)(lds + (bufoff) + ldsw + _i * 8192), 16, 0, 0); } while (0)
; #define PG8_LDA(dst, b, h) do { _Pragma("unroll") for (int m = 0; m < 4; ++m) _Pragma("unroll") for (int k = 0; k < 2; ++k) dst[m][k] = *(const PG8_LAS bf16x8*)(lds + PG8_SA(b, h) + aoff + m * 2048 + k * 1024); } while (0)
; #define PG8_LDB(dst, b, h) do { _Pragma("unroll") for (int n = 0; n < 2; ++n) _Pragma("unroll") for (int k = 0; k < 2; ++k) dst[n][k] = *(const PG8_LAS bf16x8*)(lds + PG8_SB(b, h) + boff + n * 2048 + k * 1024); } while (0)
; #define PG8_MMA(ai, bj, At, Bt) do { __builtin_amdgcn_s_setprio(1); _Pragma("unroll") for (int m = 0; m < 4; ++m) _Pragma("unroll") for (int n = 0; n < 2; ++n) _Pragma("unroll") for (int k = 0; k < 2; ++k) \
;         acc[ai][bj][m][n] = __builtin_amdgcn_mfma_f32_16x16x32_bf16(Bt[n][k], At[m][k], acc[ai][bj][m][n], 0, 0, 0); __builtin_amdgcn_s_setprio(0); } while (0)
; #define PG8_WAIT_V(n) asm volatile("s_waitcnt vmcnt(" #n ")" ::: "memory")
; template <class Epi, class Sched, bool ALIGN_EPI = false, bool SP2 = false>
; __device__ __forceinline__ void gemm_phase(PG8_LAS unsigned char* lds, const Gemm g, const Sched& S, const Epi& E) {
;     ...
;             PG8_LDB(B0, 0, 0); PG8_LDB(B1, 0, 1); PG8_SCHED; PG8_LDA(At, 0, 0); PG8_STAGE(PG8_SA(1, 1), a1 + hstepA, voffA);
;             PG8_WAIT_V(8); PG8_WAIT_L(0); PG8_BAR; PG8_MMA(0, 0, At, B0); PG8_MMA(0, 1, At, B1); PG8_BAR; PG8_SCHED;
;             PG8_LDA(At, 0, 1); PG8_STAGE(PG8_SB(0, 0), b2, voffB); PG8_STAGE(PG8_SB(0, 1), b2 + hstepB, voffB); PG8_STAGE(PG8_SA(0, 0), a2, voffA);
;             PG8_WAIT_V(8); PG8_WAIT_L(0); PG8_BAR; PG8_MMA(1, 0, At, B0); PG8_MMA(1, 1, At, B1); PG8_BAR; PG8_SCHED;
;             PG8_LDB(B0, 1, 0); PG8_LDB(B1, 1, 1); PG8_SCHED; PG8_LDA(At, 1, 0); PG8_STAGE(PG8_SA(0, 1), a2 + hstepA, voffA);
;             PG8_WAIT_V(8); PG8_WAIT_L(0); PG8_BAR; PG8_MMA(0, 0, At, B0); PG8_MMA(0, 1, At, B1); PG8_BAR; PG8_SCHED;
;             PG8_LDA(At, 1, 1); PG8_STAGE(PG8_SB(1, 0), b3, voffB); PG8_STAGE(PG8_SB(1, 1), b3 + hstepB, voffB); PG8_STAGE(PG8_SA(1, 0), a3, voffA);
;             PG8_WAIT_V(8); PG8_WAIT_L(0); PG8_BAR; PG8_MMA(1, 0, At, B0); PG8_MMA(1, 1, At, B1); PG8_BAR; PG8_SCHED;
.LBB0_629:
	s_add_u32 s6, s0, 0x10000
	s_addc_u32 s7, s1, 0
	s_cmpk_eq_i32 s61, 0x7c
	s_cselect_b32 s24, s43, s6
	s_cselect_b32 s25, s27, s7
	s_cselect_b32 s22, s56, s59
	s_cselect_b32 s23, s31, s60
	s_add_u32 s8, s24, 0x8000
	s_addc_u32 s9, s25, 0
	s_add_i32 s73, 0, 0x10000
	v_add_u32_e32 v144, s73, v166
	s_add_i32 s76, 0, 0x14000
	ds_read_b128 v[140:143], v144
	ds_read_b128 v[160:163], v144 offset:1024
	ds_read_b128 v[170:173], v144 offset:2048
	ds_read_b128 v[178:181], v144 offset:3072
	v_add_u32_e32 v144, s76, v166
	ds_read_b128 v[198:201], v144
	ds_read_b128 v[202:205], v144 offset:1024
	ds_read_b128 v[206:209], v144 offset:2048
	ds_read_b128 v[210:213], v144 offset:3072
	v_lshl_add_u64 v[174:175], s[0:1], 0, v[128:129]
	s_add_i32 m0, s54, 0xc000
	ds_read_b128 v[214:217], v168
	ds_read_b128 v[218:221], v168 offset:1024
	ds_read_b128 v[222:225], v168 offset:2048
	ds_read_b128 v[226:229], v168 offset:3072
	ds_read_b128 v[230:233], v168 offset:4096
	ds_read_b128 v[234:237], v168 offset:5120
	ds_read_b128 v[238:241], v168 offset:6144
	ds_read_b128 v[242:245], v168 offset:7168
	global_load_lds_dwordx4 v[174:175], off
	v_lshl_add_u64 v[174:175], s[0:1], 0, v[130:131]
	s_add_i32 m0, s54, 0xe000
	s_nop 0
	global_load_lds_dwordx4 v[174:175], off
	s_waitcnt vmcnt(8)
	s_waitcnt lgkmcnt(0)
	s_barrier
	s_setprio 1
	s_waitcnt lgkmcnt(0)
	v_mfma_f32_16x16x32_bf16 v[112:115], v[140:143], v[214:217], v[112:115]
	v_mfma_f32_16x16x32_bf16 v[120:123], v[170:173], v[214:217], v[120:123]
	v_mfma_f32_16x16x32_bf16 v[80:83], v[140:143], v[222:225], v[80:83]
	v_mfma_f32_16x16x32_bf16 v[56:59], v[170:173], v[222:225], v[56:59]
	v_mfma_f32_16x16x32_bf16 v[60:63], v[140:143], v[230:233], v[60:63]
	v_mfma_f32_16x16x32_bf16 v[100:103], v[170:173], v[230:233], v[100:103]
	v_mfma_f32_16x16x32_bf16 v[68:71], v[140:143], v[238:241], v[68:71]
	v_mfma_f32_16x16x32_bf16 v[48:51], v[170:173], v[238:241], v[48:51]
	v_mfma_f32_16x16x32_bf16 v[112:115], v[160:163], v[218:221], v[112:115]
	v_mfma_f32_16x16x32_bf16 v[120:123], v[178:181], v[218:221], v[120:123]
	v_mfma_f32_16x16x32_bf16 v[80:83], v[160:163], v[226:229], v[80:83]
	v_mfma_f32_16x16x32_bf16 v[56:59], v[178:181], v[226:229], v[56:59]
	v_mfma_f32_16x16x32_bf16 v[60:63], v[160:163], v[234:237], v[60:63]
	v_mfma_f32_16x16x32_bf16 v[100:103], v[178:181], v[234:237], v[100:103]
	v_mfma_f32_16x16x32_bf16 v[68:71], v[160:163], v[242:245], v[68:71]
	v_mfma_f32_16x16x32_bf16 v[48:51], v[178:181], v[242:245], v[48:51]
	s_setprio 0
	s_setprio 1
	v_mfma_f32_16x16x32_bf16 v[116:119], v[198:201], v[214:217], v[116:119]
	v_mfma_f32_16x16x32_bf16 v[124:127], v[206:209], v[214:217], v[124:127]
	v_mfma_f32_16x16x32_bf16 v[72:75], v[198:201], v[222:225], v[72:75]
	v_mfma_f32_16x16x32_bf16 v[92:95], v[206:209], v[222:225], v[92:95]
	v_mfma_f32_16x16x32_bf16 v[104:107], v[198:201], v[230:233], v[104:107]
	v_mfma_f32_16x16x32_bf16 v[108:111], v[206:209], v[230:233], v[108:111]
	v_mfma_f32_16x16x32_bf16 v[64:67], v[198:201], v[238:241], v[64:67]
	v_mfma_f32_16x16x32_bf16 v[76:79], v[206:209], v[238:241], v[76:79]
	v_mfma_f32_16x16x32_bf16 v[116:119], v[202:205], v[218:221], v[116:119]
	v_mfma_f32_16x16x32_bf16 v[124:127], v[210:213], v[218:221], v[124:127]
	v_mfma_f32_16x16x32_bf16 v[72:75], v[202:205], v[226:229], v[72:75]
	v_mfma_f32_16x16x32_bf16 v[92:95], v[210:213], v[226:229], v[92:95]
	v_mfma_f32_16x16x32_bf16 v[104:107], v[202:205], v[234:237], v[104:107]
	v_mfma_f32_16x16x32_bf16 v[108:111], v[210:213], v[234:237], v[108:111]
	v_mfma_f32_16x16x32_bf16 v[64:67], v[202:205], v[242:245], v[64:67]
	v_mfma_f32_16x16x32_bf16 v[76:79], v[210:213], v[242:245], v[76:79]
	s_setprio 0
	s_barrier
	s_add_i32 s0, s73, s50
	v_lshl_add_u64 v[174:175], s[22:23], 0, v[136:137]
	s_mov_b32 m0, s0
	ds_read_b128 v[214:217], v168 offset:16384
	ds_read_b128 v[218:221], v168 offset:17408
	ds_read_b128 v[222:225], v168 offset:18432
	ds_read_b128 v[226:229], v168 offset:19456
	ds_read_b128 v[230:233], v168 offset:20480
	ds_read_b128 v[234:237], v168 offset:21504
	ds_read_b128 v[238:241], v168 offset:22528
	ds_read_b128 v[242:245], v168 offset:23552
	global_load_lds_dwordx4 v[174:175], off
	s_add_i32 m0, s0, 0x2000
	s_add_u32 s0, s22, 0x4000
	v_lshl_add_u64 v[174:175], s[22:23], 0, v[132:133]
	s_addc_u32 s1, s23, 0
	s_add_i32 s73, s76, s50
	global_load_lds_dwordx4 v[174:175], off
	v_lshl_add_u64 v[174:175], s[0:1], 0, v[136:137]
	s_mov_b32 m0, s73
	s_nop 0
	global_load_lds_dwordx4 v[174:175], off
	v_lshl_add_u64 v[174:175], s[0:1], 0, v[132:133]
	s_add_i32 m0, s73, 0x2000
	s_nop 0
	global_load_lds_dwordx4 v[174:175], off
	v_lshl_add_u64 v[174:175], s[24:25], 0, v[138:139]
	s_mov_b32 m0, s54
	s_nop 0
	global_load_lds_dwordx4 v[174:175], off
	v_lshl_add_u64 v[174:175], s[24:25], 0, v[134:135]
	s_mov_b32 m0, s55
	s_nop 0
	global_load_lds_dwordx4 v[174:175], off
	s_waitcnt vmcnt(8)
	s_waitcnt lgkmcnt(0)
	s_barrier
; #define PG8_STAGE(bufoff, gbase, voff) do { _Pragma("unroll") for (int _i = 0; _i < 2; ++_i) \
;         __builtin_amdgcn_global_load_lds((const unsigned*)((const char*)(gbase) + (voff)[_i]), (PG8_LAS unsigned*)(lds + (bufoff) + ldsw + _i * 8192), 16, 0, 0); } while (0)
; #define PG8_LDA(dst, b, h) do { _Pragma("unroll") for (int m = 0; m < 4; ++m) _Pragma("unroll") for (int k = 0; k < 2; ++k) dst[m][k] = *(const PG8_LAS bf16x8*)(lds + PG8_SA(b, h) + aoff + m * 2048 + k * 1024); } while (0)
; #define PG8_LDB(dst, b, h) do { _Pragma("unroll") for (int n = 0; n < 2; ++n) _Pragma("unroll") for (int k = 0; k < 2; ++k) dst[n][k] = *(const PG8_LAS bf16x8*)(lds + PG8_SB(b, h) + boff + n * 2048 + k * 1024); } while (0)
; #define PG8_MMA(ai, bj, At, Bt) do { __builtin_amdgcn_s_setprio(1); _Pragma("unroll") for (int m = 0; m < 4; ++m) _Pragma("unroll") for (int n = 0; n < 2; ++n) _Pragma("unroll") for (int k = 0; k < 2; ++k) \
;         acc[ai][bj][m][n] = __builtin_amdgcn_mfma_f32_16x16x32_bf16(Bt[n][k], At[m][k], acc[ai][bj][m][n], 0, 0, 0); __builtin_amdgcn_s_setprio(0); } while (0)
; #define PG8_WAIT_V(n) asm volatile("s_waitcnt vmcnt(" #n ")" ::: "memory")
; template <class Epi, class Sched, bool ALIGN_EPI = false, bool SP2 = false>
; __device__ __forceinline__ void gemm_phase(PG8_LAS unsigned char* lds, const Gemm g, const Sched& S, const Epi& E) {
;     ...
;             PG8_LDB(B0, 0, 0); PG8_LDB(B1, 0, 1); PG8_SCHED; PG8_LDA(At, 0, 0); PG8_STAGE(PG8_SA(1, 1), a1 + hstepA, voffA);
;             PG8_WAIT_V(8); PG8_WAIT_L(0); PG8_BAR; PG8_MMA(0, 0, At, B0); PG8_MMA(0, 1, At, B1); PG8_BAR; PG8_SCHED;
;             PG8_LDA(At, 0, 1); PG8_STAGE(PG8_SB(0, 0), b2, voffB); PG8_STAGE(PG8_SB(0, 1), b2 + hstepB, voffB); PG8_STAGE(PG8_SA(0, 0), a2, voffA);
;             PG8_WAIT_V(8); PG8_WAIT_L(0); PG8_BAR; PG8_MMA(1, 0, At, B0); PG8_MMA(1, 1, At, B1); PG8_BAR; PG8_SCHED;
;             PG8_LDB(B0, 1, 0); PG8_LDB(B1, 1, 1); PG8_SCHED; PG8_LDA(At, 1, 0); PG8_STAGE(PG8_SA(0, 1), a2 + hstepA, voffA);
;             PG8_WAIT_V(8); PG8_WAIT_L(0); PG8_BAR; PG8_MMA(0, 0, At, B0); PG8_MMA(0, 1, At, B1); PG8_BAR; PG8_SCHED;
;             PG8_LDA(At, 1, 1); PG8_STAGE(PG8_SB(1, 0), b3, voffB); PG8_STAGE(PG8_SB(1, 1), b3 + hstepB, voffB); PG8_STAGE(PG8_SA(1, 0), a3, voffA);
;             PG8_WAIT_V(8); PG8_WAIT_L(0); PG8_BAR; PG8_MMA(1, 0, At, B0); PG8_MMA(1, 1, At, B1); PG8_BAR; PG8_SCHED;
	s_setprio 1
	s_waitcnt lgkmcnt(0)
	v_mfma_f32_16x16x32_bf16 v[40:43], v[140:143], v[214:217], v[40:43]
	v_mfma_f32_16x16x32_bf16 v[44:47], v[170:173], v[214:217], v[44:47]
	v_mfma_f32_16x16x32_bf16 v[16:19], v[140:143], v[222:225], v[16:19]
	v_mfma_f32_16x16x32_bf16 v[88:91], v[170:173], v[222:225], v[88:91]
	v_mfma_f32_16x16x32_bf16 v[24:27], v[140:143], v[230:233], v[24:27]
	v_mfma_f32_16x16x32_bf16 v[28:31], v[170:173], v[230:233], v[28:31]
	v_mfma_f32_16x16x32_bf16 v[4:7], v[140:143], v[238:241], v[4:7]
	v_mfma_f32_16x16x32_bf16 v[8:11], v[170:173], v[238:241], v[8:11]
	v_mfma_f32_16x16x32_bf16 v[40:43], v[160:163], v[218:221], v[40:43]
	v_mfma_f32_16x16x32_bf16 v[44:47], v[178:181], v[218:221], v[44:47]
	v_mfma_f32_16x16x32_bf16 v[16:19], v[160:163], v[226:229], v[16:19]
	v_mfma_f32_16x16x32_bf16 v[88:91], v[178:181], v[226:229], v[88:91]
	v_mfma_f32_16x16x32_bf16 v[24:27], v[160:163], v[234:237], v[24:27]
	v_mfma_f32_16x16x32_bf16 v[28:31], v[178:181], v[234:237], v[28:31]
	v_mfma_f32_16x16x32_bf16 v[4:7], v[160:163], v[242:245], v[4:7]
	v_mfma_f32_16x16x32_bf16 v[8:11], v[178:181], v[242:245], v[8:11]
	s_setprio 0
	s_setprio 1
	v_mfma_f32_16x16x32_bf16 v[36:39], v[198:201], v[214:217], v[36:39]
	v_mfma_f32_16x16x32_bf16 v[52:55], v[206:209], v[214:217], v[52:55]
	v_mfma_f32_16x16x32_bf16 v[84:87], v[198:201], v[222:225], v[84:87]
	v_mfma_f32_16x16x32_bf16 v[96:99], v[206:209], v[222:225], v[96:99]
	v_mfma_f32_16x16x32_bf16 v[20:23], v[198:201], v[230:233], v[20:23]
	v_mfma_f32_16x16x32_bf16 v[32:35], v[206:209], v[230:233], v[32:35]
	v_mfma_f32_16x16x32_bf16 v[0:3], v[198:201], v[238:241], v[0:3]
	v_mfma_f32_16x16x32_bf16 v[12:15], v[206:209], v[238:241], v[12:15]
	v_mfma_f32_16x16x32_bf16 v[36:39], v[202:205], v[218:221], v[36:39]
	v_mfma_f32_16x16x32_bf16 v[52:55], v[210:213], v[218:221], v[52:55]
	v_mfma_f32_16x16x32_bf16 v[84:87], v[202:205], v[226:229], v[84:87]
	v_mfma_f32_16x16x32_bf16 v[96:99], v[210:213], v[226:229], v[96:99]
	v_mfma_f32_16x16x32_bf16 v[20:23], v[202:205], v[234:237], v[20:23]
	v_mfma_f32_16x16x32_bf16 v[32:35], v[210:213], v[234:237], v[32:35]
	v_mfma_f32_16x16x32_bf16 v[0:3], v[202:205], v[242:245], v[0:3]
	v_mfma_f32_16x16x32_bf16 v[12:15], v[210:213], v[242:245], v[12:15]
	s_setprio 0
	s_barrier
	s_add_i32 s73, 0, 0x18000
	v_add_u32_e32 v144, s73, v166
	s_add_i32 s76, 0, 0x1c000
	ds_read_b128 v[140:143], v144
	ds_read_b128 v[160:163], v144 offset:1024
	ds_read_b128 v[170:173], v144 offset:2048
	ds_read_b128 v[178:181], v144 offset:3072
	v_add_u32_e32 v144, s76, v166
	ds_read_b128 v[198:201], v144
	ds_read_b128 v[202:205], v144 offset:1024
	ds_read_b128 v[206:209], v144 offset:2048
	ds_read_b128 v[210:213], v144 offset:3072
	s_add_u32 s0, s24, 0x4000
	s_addc_u32 s1, s25, 0
	s_mov_b32 m0, s66
	v_lshl_add_u64 v[174:175], s[0:1], 0, v[138:139]
	ds_read_b128 v[214:217], v168 offset:32768
	ds_read_b128 v[218:221], v168 offset:33792
	ds_read_b128 v[222:225], v168 offset:34816
	ds_read_b128 v[226:229], v168 offset:35840
	ds_read_b128 v[230:233], v168 offset:36864
	ds_read_b128 v[234:237], v168 offset:37888
	ds_read_b128 v[238:241], v168 offset:38912
	ds_read_b128 v[242:245], v168 offset:39936
	global_load_lds_dwordx4 v[174:175], off
	v_lshl_add_u64 v[174:175], s[0:1], 0, v[134:135]
	s_mov_b32 m0, s67
	s_nop 0
	global_load_lds_dwordx4 v[174:175], off
	s_waitcnt vmcnt(8)
	s_waitcnt lgkmcnt(0)
	s_barrier
	s_setprio 1
	s_waitcnt lgkmcnt(0)
	v_mfma_f32_16x16x32_bf16 v[112:115], v[140:143], v[214:217], v[112:115]
	v_mfma_f32_16x16x32_bf16 v[120:123], v[170:173], v[214:217], v[120:123]
	v_mfma_f32_16x16x32_bf16 v[80:83], v[140:143], v[222:225], v[80:83]
	v_mfma_f32_16x16x32_bf16 v[56:59], v[170:173], v[222:225], v[56:59]
	v_mfma_f32_16x16x32_bf16 v[60:63], v[140:143], v[230:233], v[60:63]
	v_mfma_f32_16x16x32_bf16 v[100:103], v[170:173], v[230:233], v[100:103]
	v_mfma_f32_16x16x32_bf16 v[68:71], v[140:143], v[238:241], v[68:71]
	v_mfma_f32_16x16x32_bf16 v[48:51], v[170:173], v[238:241], v[48:51]
	v_mfma_f32_16x16x32_bf16 v[112:115], v[160:163], v[218:221], v[112:115]
	v_mfma_f32_16x16x32_bf16 v[120:123], v[178:181], v[218:221], v[120:123]
	v_mfma_f32_16x16x32_bf16 v[80:83], v[160:163], v[226:229], v[80:83]
	v_mfma_f32_16x16x32_bf16 v[56:59], v[178:181], v[226:229], v[56:59]
	v_mfma_f32_16x16x32_bf16 v[60:63], v[160:163], v[234:237], v[60:63]
	v_mfma_f32_16x16x32_bf16 v[100:103], v[178:181], v[234:237], v[100:103]
	v_mfma_f32_16x16x32_bf16 v[68:71], v[160:163], v[242:245], v[68:71]
	v_mfma_f32_16x16x32_bf16 v[48:51], v[178:181], v[242:245], v[48:51]
	s_setprio 0
	s_setprio 1
	v_mfma_f32_16x16x32_bf16 v[116:119], v[198:201], v[214:217], v[116:119]
	v_mfma_f32_16x16x32_bf16 v[124:127], v[206:209], v[214:217], v[124:127]
	v_mfma_f32_16x16x32_bf16 v[72:75], v[198:201], v[222:225], v[72:75]
	v_mfma_f32_16x16x32_bf16 v[92:95], v[206:209], v[222:225], v[92:95]
	v_mfma_f32_16x16x32_bf16 v[104:107], v[198:201], v[230:233], v[104:107]
	v_mfma_f32_16x16x32_bf16 v[108:111], v[206:209], v[230:233], v[108:111]
	v_mfma_f32_16x16x32_bf16 v[64:67], v[198:201], v[238:241], v[64:67]
	v_mfma_f32_16x16x32_bf16 v[76:79], v[206:209], v[238:241], v[76:79]
	v_mfma_f32_16x16x32_bf16 v[116:119], v[202:205], v[218:221], v[116:119]
	v_mfma_f32_16x16x32_bf16 v[124:127], v[210:213], v[218:221], v[124:127]
	v_mfma_f32_16x16x32_bf16 v[72:75], v[202:205], v[226:229], v[72:75]
	v_mfma_f32_16x16x32_bf16 v[92:95], v[210:213], v[226:229], v[92:95]
	v_mfma_f32_16x16x32_bf16 v[104:107], v[202:205], v[234:237], v[104:107]
	v_mfma_f32_16x16x32_bf16 v[108:111], v[210:213], v[234:237], v[108:111]
	v_mfma_f32_16x16x32_bf16 v[64:67], v[202:205], v[242:245], v[64:67]
	v_mfma_f32_16x16x32_bf16 v[76:79], v[210:213], v[242:245], v[76:79]
	s_setprio 0
	s_barrier
; #define PG8_STAGE(bufoff, gbase, voff) do { _Pragma("unroll") for (int _i = 0; _i < 2; ++_i) \
;         __builtin_amdgcn_global_load_lds((const unsigned*)((const char*)(gbase) + (voff)[_i]), (PG8_LAS unsigned*)(lds + (bufoff) + ldsw + _i * 8192), 16, 0, 0); } while (0)
; #define PG8_LDA(dst, b, h) do { _Pragma("unroll") for (int m = 0; m < 4; ++m) _Pragma("unroll") for (int k = 0; k < 2; ++k) dst[m][k] = *(const PG8_LAS bf16x8*)(lds + PG8_SA(b, h) + aoff + m * 2048 + k * 1024); } while (0)
; #define PG8_WAIT_V(n) asm volatile("s_waitcnt vmcnt(" #n ")" ::: "memory")
;     __device__ __forceinline__ void operator()(const f32x4 (&acc)[2][2][4][2], const State&, const Unit& u, int wr, int wc, int fr, int fq) const {
;     ...
;         if (xout_f) {
; #pragma unroll
;             for (int ai = 0; ai < 2; ++ai)
; #pragma unroll
;                 for (int m = 0; m < 4; ++m) { const size_t off = (size_t)(row0 + ai * HALF + m * 16) * ldc + col0;
; #pragma unroll
;                     for (int bj = 0; bj < 2; ++bj)
; #pragma unroll
;                         for (int n = 0; n < 2; ++n) *(f32x4*)(xout_f + off + bj * HALF + n * 4) = acc[ai][bj][m][n]; }
; template <class Epi, class Sched, bool ALIGN_EPI = false, bool SP2 = false>
; __device__ __forceinline__ void gemm_phase(PG8_LAS unsigned char* lds, const Gemm g, const Sched& S, const Epi& E) {
;     ...
;             PG8_LDB(B0, 0, 0); PG8_LDB(B1, 0, 1); PG8_SCHED; PG8_LDA(At, 0, 0); PG8_STAGE(PG8_SA(1, 1), a1 + hstepA, voffA);
;             PG8_WAIT_V(8); PG8_WAIT_L(0); PG8_BAR; PG8_MMA(0, 0, At, B0); PG8_MMA(0, 1, At, B1); PG8_BAR; PG8_SCHED;
;             PG8_LDA(At, 0, 1); PG8_STAGE(PG8_SB(0, 0), b2, voffB); PG8_STAGE(PG8_SB(0, 1), b2 + hstepB, voffB); PG8_STAGE(PG8_SA(0, 0), a2, voffA);
;             PG8_WAIT_V(8); PG8_WAIT_L(0); PG8_BAR; PG8_MMA(1, 0, At, B0); PG8_MMA(1, 1, At, B1); PG8_BAR; PG8_SCHED;
;             PG8_LDB(B0, 1, 0); PG8_LDB(B1, 1, 1); PG8_SCHED; PG8_LDA(At, 1, 0); PG8_STAGE(PG8_SA(0, 1), a2 + hstepA, voffA);
;             PG8_WAIT_V(8); PG8_WAIT_L(0); PG8_BAR; PG8_MMA(0, 0, At, B0); PG8_MMA(0, 1, At, B1); PG8_BAR; PG8_SCHED;
;             PG8_LDA(At, 1, 1); PG8_STAGE(PG8_SB(1, 0), b3, voffB); PG8_STAGE(PG8_SB(1, 1), b3 + hstepB, voffB); PG8_STAGE(PG8_SA(1, 0), a3, voffA);
;             PG8_WAIT_V(8); PG8_WAIT_L(0); PG8_BAR; PG8_MMA(1, 0, At, B0); PG8_MMA(1, 1, At, B1); PG8_BAR; PG8_SCHED;
	s_add_u32 s0, s22, 0x8000
	s_addc_u32 s1, s23, 0
	s_add_i32 s24, s73, s50
	v_lshl_add_u64 v[174:175], s[0:1], 0, v[136:137]
	s_mov_b32 m0, s24
	ds_read_b128 v[214:217], v168 offset:49152
	ds_read_b128 v[218:221], v168 offset:50176
	ds_read_b128 v[222:225], v168 offset:51200
	ds_read_b128 v[226:229], v168 offset:52224
	ds_read_b128 v[230:233], v168 offset:53248
	ds_read_b128 v[234:237], v168 offset:54272
	ds_read_b128 v[238:241], v168 offset:55296
	ds_read_b128 v[242:245], v168 offset:56320
	global_load_lds_dwordx4 v[174:175], off
	s_add_i32 m0, s24, 0x2000
	v_lshl_add_u64 v[174:175], s[0:1], 0, v[132:133]
	s_add_u32 s0, s22, 0xc000
	s_addc_u32 s1, s23, 0
	s_add_i32 s22, s76, s50
	global_load_lds_dwordx4 v[174:175], off
	v_lshl_add_u64 v[174:175], s[0:1], 0, v[136:137]
	s_mov_b32 m0, s22
	s_nop 0
	global_load_lds_dwordx4 v[174:175], off
	v_lshl_add_u64 v[174:175], s[0:1], 0, v[132:133]
	s_add_i32 m0, s22, 0x2000
	s_nop 0
	global_load_lds_dwordx4 v[174:175], off
	v_lshl_add_u64 v[174:175], s[8:9], 0, v[138:139]
	s_mov_b32 m0, s68
	s_nop 0
	global_load_lds_dwordx4 v[174:175], off
	v_lshl_add_u64 v[174:175], s[8:9], 0, v[134:135]
	s_mov_b32 m0, s69
	s_nop 0
	global_load_lds_dwordx4 v[174:175], off
	s_waitcnt vmcnt(8)
	s_waitcnt lgkmcnt(0)
	s_barrier
	s_setprio 1
	s_waitcnt lgkmcnt(0)
	v_mfma_f32_16x16x32_bf16 v[40:43], v[140:143], v[214:217], v[40:43]
	v_mfma_f32_16x16x32_bf16 v[44:47], v[170:173], v[214:217], v[44:47]
	v_mfma_f32_16x16x32_bf16 v[16:19], v[140:143], v[222:225], v[16:19]
	v_mfma_f32_16x16x32_bf16 v[88:91], v[170:173], v[222:225], v[88:91]
	v_mfma_f32_16x16x32_bf16 v[24:27], v[140:143], v[230:233], v[24:27]
	v_mfma_f32_16x16x32_bf16 v[28:31], v[170:173], v[230:233], v[28:31]
	v_mfma_f32_16x16x32_bf16 v[4:7], v[140:143], v[238:241], v[4:7]
	v_mfma_f32_16x16x32_bf16 v[8:11], v[170:173], v[238:241], v[8:11]
	v_mfma_f32_16x16x32_bf16 v[40:43], v[160:163], v[218:221], v[40:43]
	v_mfma_f32_16x16x32_bf16 v[44:47], v[178:181], v[218:221], v[44:47]
	v_mfma_f32_16x16x32_bf16 v[16:19], v[160:163], v[226:229], v[16:19]
	v_mfma_f32_16x16x32_bf16 v[88:91], v[178:181], v[226:229], v[88:91]
	v_mfma_f32_16x16x32_bf16 v[24:27], v[160:163], v[234:237], v[24:27]
	v_mfma_f32_16x16x32_bf16 v[28:31], v[178:181], v[234:237], v[28:31]
	v_mfma_f32_16x16x32_bf16 v[4:7], v[160:163], v[242:245], v[4:7]
	v_mfma_f32_16x16x32_bf16 v[8:11], v[178:181], v[242:245], v[8:11]
	s_setprio 0
	s_setprio 1
	v_mfma_f32_16x16x32_bf16 v[36:39], v[198:201], v[214:217], v[36:39]
	v_mfma_f32_16x16x32_bf16 v[52:55], v[206:209], v[214:217], v[52:55]
	v_mfma_f32_16x16x32_bf16 v[84:87], v[198:201], v[222:225], v[84:87]
	v_mfma_f32_16x16x32_bf16 v[96:99], v[206:209], v[222:225], v[96:99]
	v_mfma_f32_16x16x32_bf16 v[20:23], v[198:201], v[230:233], v[20:23]
	v_mfma_f32_16x16x32_bf16 v[32:35], v[206:209], v[230:233], v[32:35]
	v_mfma_f32_16x16x32_bf16 v[0:3], v[198:201], v[238:241], v[0:3]
	v_mfma_f32_16x16x32_bf16 v[12:15], v[206:209], v[238:241], v[12:15]
	v_mfma_f32_16x16x32_bf16 v[36:39], v[202:205], v[218:221], v[36:39]
	v_mfma_f32_16x16x32_bf16 v[52:55], v[210:213], v[218:221], v[52:55]
	v_mfma_f32_16x16x32_bf16 v[84:87], v[202:205], v[226:229], v[84:87]
	v_mfma_f32_16x16x32_bf16 v[96:99], v[210:213], v[226:229], v[96:99]
	v_mfma_f32_16x16x32_bf16 v[20:23], v[202:205], v[234:237], v[20:23]
	v_mfma_f32_16x16x32_bf16 v[32:35], v[210:213], v[234:237], v[32:35]
	v_mfma_f32_16x16x32_bf16 v[0:3], v[202:205], v[242:245], v[0:3]
	v_mfma_f32_16x16x32_bf16 v[12:15], v[210:213], v[242:245], v[12:15]
	s_setprio 0
	s_barrier
	s_add_i32 s61, s61, 2
	s_add_u32 s59, s59, 0x10000
	s_addc_u32 s60, s60, 0
	s_cmpk_gt_u32 s61, 0x7d
	s_mov_b64 s[0:1], s[6:7]
	s_cbranch_scc0 .LBB0_629
	s_lshl_b32 s7, s26, 8
	s_add_i32 s7, s7, s51
	v_or_b32_e32 v140, s7, v164
	s_lshl_b32 s0, s14, 8
	s_or_b32 s6, s0, s52
	s_andn2_b64 vcc, exec, s[20:21]
	v_or_b32_e32 v162, 16, v140
	v_or_b32_e32 v160, 32, v140
	v_or_b32_e32 v142, 48, v140
	s_cbranch_vccnz .LBB0_633
	v_or_b32_e32 v170, s6, v165
	v_ashrrev_i32_e32 v141, 31, v140
	v_ashrrev_i32_e32 v163, 31, v162
	v_ashrrev_i32_e32 v171, 31, v170
	v_lshlrev_b64 v[172:173], 13, v[140:141]
	v_lshlrev_b64 v[174:175], 13, v[162:163]
	v_lshl_add_u64 v[172:173], s[16:17], 0, v[172:173]
	v_lshlrev_b64 v[170:171], 2, v[170:171]
	v_lshl_add_u64 v[174:175], s[16:17], 0, v[174:175]
	v_lshl_add_u64 v[172:173], v[172:173], 0, v[170:171]
	v_lshl_add_u64 v[174:175], v[174:175], 0, v[170:171]
	v_ashrrev_i32_e32 v161, 31, v160
	global_store_dwordx4 v[172:173], v[112:115], off sc1
	global_store_dwordx4 v[172:173], v[120:123], off offset:16 sc1
	global_store_dwordx4 v[172:173], v[116:119], off offset:512 sc1
	global_store_dwordx4 v[172:173], v[124:127], off offset:528 sc1
	global_store_dwordx4 v[174:175], v[80:83], off sc1
	global_store_dwordx4 v[174:175], v[56:59], off offset:16 sc1
	global_store_dwordx4 v[174:175], v[72:75], off offset:512 sc1
	global_store_dwordx4 v[174:175], v[92:95], off offset:528 sc1
	v_lshlrev_b64 v[174:175], 13, v[160:161]
	v_lshl_add_u64 v[174:175], s[16:17], 0, v[174:175]
	v_lshl_add_u64 v[174:175], v[174:175], 0, v[170:171]
	v_ashrrev_i32_e32 v143, 31, v142
	global_store_dwordx4 v[174:175], v[60:63], off sc1
	global_store_dwordx4 v[174:175], v[100:103], off offset:16 sc1
	global_store_dwordx4 v[174:175], v[104:107], off offset:512 sc1
	global_store_dwordx4 v[174:175], v[108:111], off offset:528 sc1
	v_lshlrev_b64 v[174:175], 13, v[142:143]
	v_lshl_add_u64 v[174:175], s[16:17], 0, v[174:175]
	v_lshl_add_u64 v[170:171], v[174:175], 0, v[170:171]
	s_mov_b64 s[0:1], 0x100000
	global_store_dwordx4 v[170:171], v[68:71], off sc1
	global_store_dwordx4 v[170:171], v[48:51], off offset:16 sc1
; __device__ __forceinline__ unsigned cvt_pk_bf16(float lo, float hi) { unsigned r; asm volatile("v_cvt_pk_bf16_f32 %0, %1, %2" : "=v"(r) : "v"(lo), "v"(hi)); return r; }
;     __device__ __forceinline__ size_t xb_off(int row, int col) const { return ((size_t)(row >> 8) * (ldc >> 6) + (col >> 6)) * (256 * 64) + blk_off(row & 255, col & 63); }
;     __device__ __forceinline__ void operator()(const f32x4 (&acc)[2][2][4][2], const State&, const Unit& u, int wr, int wc, int fr, int fq) const {
;     ...
;         if (xout_f) {
; #pragma unroll
;             for (int ai = 0; ai < 2; ++ai)
; #pragma unroll
;                 for (int m = 0; m < 4; ++m) { const size_t off = (size_t)(row0 + ai * HALF + m * 16) * ldc + col0;
; #pragma unroll
;                     for (int bj = 0; bj < 2; ++bj)
; #pragma unroll
;                         for (int n = 0; n < 2; ++n) *(f32x4*)(xout_f + off + bj * HALF + n * 4) = acc[ai][bj][m][n]; }
;         } else {
; #pragma unroll
;             for (int ai = 0; ai < 2; ++ai)
; #pragma unroll
;                 for (int m = 0; m < 4; ++m) { const int row = row0 + ai * HALF + m * 16; const size_t off = (size_t)row * ldc + col0; float ss = 0.f;
; #pragma unroll
;                     for (int bj = 0; bj < 2; ++bj) { const f32x4 v0 = acc[ai][bj][m][0], v1 = acc[ai][bj][m][1];
;                         u32x4 w; w.x = cvt_pk_bf16(v0[0], v0[1]); w.y = cvt_pk_bf16(v0[2], v0[3]); w.z = cvt_pk_bf16(v1[0], v1[1]); w.w = cvt_pk_bf16(v1[2], v1[3]);
;                         *(u32x4*)(xb + xb_off(row, col0 + bj * HALF)) = w;
;                         ss += ((v0[0] * v0[0] + v0[1] * v0[1]) + (v0[2] * v0[2] + v0[3] * v0[3])) + ((v1[0] * v1[0] + v1[1] * v1[1]) + (v1[2] * v1[2] + v1[3] * v1[3])); }
;                     ss += __shfl_xor(ss, 16); ss += __shfl_xor(ss, 32);
;                     if (fq == 0) ssq[(size_t)row * 32 + u.pn * 4 + wc] = ss; }
	global_store_dwordx4 v[170:171], v[64:67], off offset:512 sc1
	global_store_dwordx4 v[170:171], v[76:79], off offset:528 sc1
	v_lshl_add_u64 v[170:171], v[172:173], 0, s[0:1]
	s_mov_b32 s0, 0x100000
	v_add_co_u32_e32 v174, vcc, s0, v172
	s_mov_b64 s[0:1], 0x120000
	s_nop 0
	v_addc_co_u32_e32 v175, vcc, 0, v173, vcc
	global_store_dwordx4 v[174:175], v[40:43], off sc1
	global_store_dwordx4 v[170:171], v[44:47], off offset:16 sc1
	global_store_dwordx4 v[170:171], v[36:39], off offset:512 sc1
	global_store_dwordx4 v[170:171], v[52:55], off offset:528 sc1
	v_lshl_add_u64 v[170:171], v[172:173], 0, s[0:1]
	s_mov_b32 s0, 0x120000
	v_add_co_u32_e32 v174, vcc, s0, v172
	s_mov_b64 s[0:1], 0x140000
	s_nop 0
	v_addc_co_u32_e32 v175, vcc, 0, v173, vcc
	global_store_dwordx4 v[174:175], v[16:19], off sc1
	global_store_dwordx4 v[170:171], v[88:91], off offset:16 sc1
	global_store_dwordx4 v[170:171], v[84:87], off offset:512 sc1
	global_store_dwordx4 v[170:171], v[96:99], off offset:528 sc1
	v_add_co_u32_e32 v174, vcc, 0x140000, v172
	v_lshl_add_u64 v[170:171], v[172:173], 0, s[0:1]
	s_nop 0
	v_addc_co_u32_e32 v175, vcc, 0, v173, vcc
	s_mov_b64 s[0:1], 0x160000
	global_store_dwordx4 v[174:175], v[24:27], off sc1
	global_store_dwordx4 v[170:171], v[28:31], off offset:16 sc1
	global_store_dwordx4 v[170:171], v[20:23], off offset:512 sc1
	global_store_dwordx4 v[170:171], v[32:35], off offset:528 sc1
	v_lshl_add_u64 v[170:171], v[172:173], 0, s[0:1]
	v_add_co_u32_e32 v172, vcc, 0x160000, v172
	s_nop 1
	v_addc_co_u32_e32 v173, vcc, 0, v173, vcc
	global_store_dwordx4 v[172:173], v[4:7], off sc1
	global_store_dwordx4 v[170:171], v[8:11], off offset:16 sc1
	global_store_dwordx4 v[170:171], v[0:3], off offset:512 sc1
	global_store_dwordx4 v[170:171], v[12:15], off offset:528 sc1
	s_cbranch_execz .LBB0_634
	s_mov_b64 s[0:1], -1
	s_and_b64 vcc, s[40:41], exec
	s_cbranch_vccz .LBB0_621
	s_branch .LBB0_651
.LBB0_633:
.LBB0_634:
	v_cvt_pk_bf16_f32 v170, v112, v113
	v_mul_f32_e32 v113, v113, v113
	v_fmac_f32_e32 v113, v112, v112
	v_mul_f32_e32 v112, v115, v115
	v_fmac_f32_e32 v112, v114, v114
	v_cvt_pk_bf16_f32 v171, v114, v115
	v_add_f32_e32 v112, v113, v112
	v_mul_f32_e32 v113, v121, v121
	v_mul_f32_e32 v114, v123, v123
	v_fmac_f32_e32 v113, v120, v120
	v_fmac_f32_e32 v114, v122, v122
	v_add_f32_e32 v113, v113, v114
	v_add_f32_e32 v112, v112, v113
	v_mul_f32_e32 v113, v117, v117
	v_mul_f32_e32 v114, v119, v119
	v_fmac_f32_e32 v113, v116, v116
	v_fmac_f32_e32 v114, v118, v118
	v_add_f32_e32 v113, v113, v114
	v_mul_f32_e32 v114, v125, v125
	v_mul_f32_e32 v115, v127, v127
	v_fmac_f32_e32 v114, v124, v124
	v_fmac_f32_e32 v115, v126, v126
	v_add_f32_e32 v114, v114, v115
	v_add_f32_e32 v113, v113, v114
	v_cmp_lt_i32_e32 vcc, v191, v192
	s_ashr_i32 s8, s7, 8
	v_add_f32_e32 v113, v112, v113
	v_cndmask_b32_e32 v112, v190, v191, vcc
	s_lshl_b32 s0, s14, 2
	s_ashr_i32 s9, s8, 31
	s_ashr_i32 s6, s6, 6
	v_lshlrev_b32_e32 v112, 2, v112
	s_ashr_i32 s1, s0, 31
	s_lshl_b64 s[24:25], s[8:9], 5
	s_ashr_i32 s7, s6, 31
	ds_bpermute_b32 v114, v112, v113
	s_add_u32 s8, s24, s6
	s_addc_u32 s9, s25, s7
	s_lshl_b64 s[8:9], s[8:9], 15
	s_add_u32 s22, s10, s8
	v_cmp_lt_i32_e32 vcc, v193, v192
	s_addc_u32 s23, s11, s9
	s_or_b32 s8, s6, 2
	s_waitcnt lgkmcnt(0)
	v_add_f32_e32 v114, v113, v114
	v_cndmask_b32_e32 v113, v190, v193, vcc
	s_ashr_i32 s9, s8, 31
	v_lshlrev_b32_e32 v113, 2, v113
	v_lshlrev_b32_e32 v141, 6, v140
	s_add_u32 s24, s24, s8
	ds_bpermute_b32 v115, v113, v114
	v_and_b32_e32 v143, 0x2000, v141
	v_lshlrev_b32_e32 v141, 5, v140
	s_addc_u32 s25, s25, s9
	v_and_b32_e32 v144, 0x1e0, v141
	s_lshl_b64 s[24:25], s[24:25], 15
	v_or3_b32 v141, v143, v144, v167
	s_add_u32 s24, s10, s24
	v_lshlrev_b32_e32 v141, 1, v141
	s_addc_u32 s25, s11, s25
	v_cvt_pk_bf16_f32 v172, v120, v121
	v_cvt_pk_bf16_f32 v173, v122, v123
	global_store_dwordx4 v141, v[170:173], s[22:23] sc1
	v_cvt_pk_bf16_f32 v120, v116, v117
	v_cvt_pk_bf16_f32 v121, v118, v119
	v_cvt_pk_bf16_f32 v122, v124, v125
	v_cvt_pk_bf16_f32 v123, v126, v127
	global_store_dwordx4 v141, v[120:123], s[24:25] sc1
	s_and_saveexec_b64 s[26:27], s[38:39]
	s_cbranch_execz .LBB0_636
	v_ashrrev_i32_e32 v141, 31, v140
	v_lshlrev_b64 v[116:117], 7, v[140:141]
	v_lshl_add_u64 v[116:117], s[18:19], 0, v[116:117]
	v_lshl_add_u64 v[116:117], s[0:1], 2, v[116:117]
	s_lshl_b32 s14, s49, 2
	v_lshl_add_u64 v[116:117], v[116:117], 0, s[14:15]
	s_waitcnt lgkmcnt(0)
	v_add_f32_e32 v114, v114, v115
	global_store_dword v[116:117], v114, off
.LBB0_636:
	s_or_b64 exec, exec, s[26:27]
	v_lshrrev_b32_e32 v114, 3, v162
	v_and_or_b32 v114, v114, 10, s53
	v_lshl_or_b32 v114, v114, 9, v143
	v_or3_b32 v118, v114, v144, v165
	v_cvt_pk_bf16_f32 v114, v80, v81
	s_waitcnt lgkmcnt(0)
	v_cvt_pk_bf16_f32 v115, v82, v83
	v_cvt_pk_bf16_f32 v116, v56, v57
	v_mul_f32_e32 v81, v81, v81
	v_mul_f32_e32 v57, v57, v57
	v_fmac_f32_e32 v81, v80, v80
	v_mul_f32_e32 v80, v83, v83
	v_fmac_f32_e32 v57, v56, v56
	v_mul_f32_e32 v56, v59, v59
	v_fmac_f32_e32 v80, v82, v82
	v_fmac_f32_e32 v56, v58, v58
	v_add_f32_e32 v80, v81, v80
	v_add_f32_e32 v56, v57, v56
	v_add_f32_e32 v56, v80, v56
	v_mul_f32_e32 v57, v73, v73
	v_mul_f32_e32 v80, v75, v75
	v_fmac_f32_e32 v57, v72, v72
	v_fmac_f32_e32 v80, v74, v74
	v_add_f32_e32 v57, v57, v80
	v_mul_f32_e32 v80, v93, v93
	v_mul_f32_e32 v81, v95, v95
	v_fmac_f32_e32 v80, v92, v92
	v_fmac_f32_e32 v81, v94, v94
	v_add_f32_e32 v80, v80, v81
	v_add_f32_e32 v57, v57, v80
	v_add_f32_e32 v56, v56, v57
	ds_bpermute_b32 v57, v112, v56
	v_cvt_pk_bf16_f32 v117, v58, v59
	v_lshlrev_b32_e32 v58, 1, v118
	global_store_dwordx4 v58, v[114:117], s[22:23] sc1
	v_cvt_pk_bf16_f32 v72, v72, v73
	s_waitcnt lgkmcnt(0)
	v_add_f32_e32 v56, v56, v57
	ds_bpermute_b32 v57, v113, v56
	v_cvt_pk_bf16_f32 v73, v74, v75
	v_cvt_pk_bf16_f32 v74, v92, v93
	v_cvt_pk_bf16_f32 v75, v94, v95
	global_store_dwordx4 v58, v[72:75], s[24:25] sc1
	s_and_saveexec_b64 s[26:27], s[38:39]
	s_cbranch_execz .LBB0_638
	v_ashrrev_i32_e32 v163, 31, v162
	v_lshlrev_b64 v[58:59], 7, v[162:163]
	v_lshl_add_u64 v[58:59], s[18:19], 0, v[58:59]
	v_lshl_add_u64 v[58:59], s[0:1], 2, v[58:59]
	s_lshl_b32 s14, s49, 2
	v_lshl_add_u64 v[58:59], v[58:59], 0, s[14:15]
	s_waitcnt lgkmcnt(0)
	v_add_f32_e32 v56, v56, v57
	global_store_dword v[58:59], v56, off
; __device__ __forceinline__ unsigned cvt_pk_bf16(float lo, float hi) { unsigned r; asm volatile("v_cvt_pk_bf16_f32 %0, %1, %2" : "=v"(r) : "v"(lo), "v"(hi)); return r; }
;     __device__ __forceinline__ size_t xb_off(int row, int col) const { return ((size_t)(row >> 8) * (ldc >> 6) + (col >> 6)) * (256 * 64) + blk_off(row & 255, col & 63); }
;     __device__ __forceinline__ void operator()(const f32x4 (&acc)[2][2][4][2], const State&, const Unit& u, int wr, int wc, int fr, int fq) const {
;     ...
;             for (int ai = 0; ai < 2; ++ai)
; #pragma unroll
;                 for (int m = 0; m < 4; ++m) { const int row = row0 + ai * HALF + m * 16; const size_t off = (size_t)row * ldc + col0; float ss = 0.f;
; #pragma unroll
;                     for (int bj = 0; bj < 2; ++bj) { const f32x4 v0 = acc[ai][bj][m][0], v1 = acc[ai][bj][m][1];
;                         u32x4 w; w.x = cvt_pk_bf16(v0[0], v0[1]); w.y = cvt_pk_bf16(v0[2], v0[3]); w.z = cvt_pk_bf16(v1[0], v1[1]); w.w = cvt_pk_bf16(v1[2], v1[3]);
;                         *(u32x4*)(xb + xb_off(row, col0 + bj * HALF)) = w;
;                         ss += ((v0[0] * v0[0] + v0[1] * v0[1]) + (v0[2] * v0[2] + v0[3] * v0[3])) + ((v1[0] * v1[0] + v1[1] * v1[1]) + (v1[2] * v1[2] + v1[3] * v1[3])); }
;                     ss += __shfl_xor(ss, 16); ss += __shfl_xor(ss, 32);
;                     if (fq == 0) ssq[(size_t)row * 32 + u.pn * 4 + wc] = ss; }
.LBB0_638:
	s_or_b64 exec, exec, s[26:27]
	v_lshrrev_b32_e32 v56, 3, v160
	v_and_or_b32 v56, v56, 12, s53
	v_lshl_or_b32 v56, v56, 9, v143
	v_mul_f32_e32 v59, v61, v61
	v_or3_b32 v72, v56, v144, v165
	v_cvt_pk_bf16_f32 v56, v60, v61
	v_fmac_f32_e32 v59, v60, v60
	v_mul_f32_e32 v60, v63, v63
	v_fmac_f32_e32 v60, v62, v62
	v_add_f32_e32 v59, v59, v60
	v_mul_f32_e32 v60, v101, v101
	v_mul_f32_e32 v61, v103, v103
	v_fmac_f32_e32 v60, v100, v100
	v_fmac_f32_e32 v61, v102, v102
	v_add_f32_e32 v60, v60, v61
	v_add_f32_e32 v59, v59, v60
	v_mul_f32_e32 v60, v105, v105
	v_mul_f32_e32 v61, v107, v107
	v_fmac_f32_e32 v60, v104, v104
	v_fmac_f32_e32 v61, v106, v106
	s_waitcnt lgkmcnt(0)
	v_cvt_pk_bf16_f32 v57, v62, v63
	v_add_f32_e32 v60, v60, v61
	v_mul_f32_e32 v61, v109, v109
	v_mul_f32_e32 v62, v111, v111
	v_fmac_f32_e32 v61, v108, v108
	v_fmac_f32_e32 v62, v110, v110
	v_add_f32_e32 v61, v61, v62
	v_add_f32_e32 v60, v60, v61
	v_add_f32_e32 v60, v59, v60
	ds_bpermute_b32 v61, v112, v60
	v_lshlrev_b32_e32 v62, 1, v72
	v_cvt_pk_bf16_f32 v58, v100, v101
	v_cvt_pk_bf16_f32 v59, v102, v103
	global_store_dwordx4 v62, v[56:59], s[22:23] sc1
	s_waitcnt lgkmcnt(0)
	s_nop 0
	v_add_f32_e32 v56, v60, v61
	ds_bpermute_b32 v57, v113, v56
	v_cvt_pk_bf16_f32 v58, v104, v105
	v_cvt_pk_bf16_f32 v59, v106, v107
	v_cvt_pk_bf16_f32 v60, v108, v109
	v_cvt_pk_bf16_f32 v61, v110, v111
	global_store_dwordx4 v62, v[58:61], s[24:25] sc1
	s_and_saveexec_b64 s[26:27], s[38:39]
	s_cbranch_execz .LBB0_640
	v_ashrrev_i32_e32 v161, 31, v160
	v_lshlrev_b64 v[58:59], 7, v[160:161]
	v_lshl_add_u64 v[58:59], s[18:19], 0, v[58:59]
	v_lshl_add_u64 v[58:59], s[0:1], 2, v[58:59]
	s_lshl_b32 s14, s49, 2
	v_lshl_add_u64 v[58:59], v[58:59], 0, s[14:15]
	s_waitcnt lgkmcnt(0)
	v_add_f32_e32 v56, v56, v57
	global_store_dword v[58:59], v56, off
.LBB0_640:
	s_or_b64 exec, exec, s[26:27]
	v_lshrrev_b32_e32 v56, 3, v142
	v_and_or_b32 v56, v56, 14, s53
	v_lshl_or_b32 v56, v56, 9, v143
	v_or3_b32 v60, v56, v144, v165
	v_cvt_pk_bf16_f32 v56, v68, v69
	s_waitcnt lgkmcnt(0)
	v_cvt_pk_bf16_f32 v57, v70, v71
	v_cvt_pk_bf16_f32 v58, v48, v49
	v_mul_f32_e32 v49, v49, v49
	v_mul_f32_e32 v59, v69, v69
	v_mul_f32_e32 v61, v71, v71
	v_fmac_f32_e32 v49, v48, v48
	v_mul_f32_e32 v48, v51, v51
	v_fmac_f32_e32 v59, v68, v68
	v_fmac_f32_e32 v61, v70, v70
	v_fmac_f32_e32 v48, v50, v50
	v_add_f32_e32 v59, v59, v61
	v_add_f32_e32 v48, v49, v48
	v_add_f32_e32 v48, v59, v48
	v_mul_f32_e32 v49, v65, v65
	v_mul_f32_e32 v59, v67, v67
	v_fmac_f32_e32 v49, v64, v64
	v_fmac_f32_e32 v59, v66, v66
	v_add_f32_e32 v49, v49, v59
	v_mul_f32_e32 v59, v77, v77
	v_mul_f32_e32 v61, v79, v79
	v_fmac_f32_e32 v59, v76, v76
	v_fmac_f32_e32 v61, v78, v78
	v_add_f32_e32 v59, v59, v61
	v_add_f32_e32 v49, v49, v59
	v_add_f32_e32 v48, v48, v49
	ds_bpermute_b32 v49, v112, v48
	v_cvt_pk_bf16_f32 v59, v50, v51
	v_lshlrev_b32_e32 v50, 1, v60
	global_store_dwordx4 v50, v[56:59], s[22:23] sc1
	s_waitcnt lgkmcnt(0)
	v_add_f32_e32 v48, v48, v49
	ds_bpermute_b32 v49, v113, v48
	v_cvt_pk_bf16_f32 v56, v64, v65
	v_cvt_pk_bf16_f32 v57, v66, v67
	v_cvt_pk_bf16_f32 v58, v76, v77
	v_cvt_pk_bf16_f32 v59, v78, v79
	global_store_dwordx4 v50, v[56:59], s[24:25] sc1
	s_and_saveexec_b64 s[22:23], s[38:39]
	s_cbranch_execz .LBB0_642
	v_ashrrev_i32_e32 v143, 31, v142
	v_lshlrev_b64 v[50:51], 7, v[142:143]
	v_lshl_add_u64 v[50:51], s[18:19], 0, v[50:51]
	v_lshl_add_u64 v[50:51], s[0:1], 2, v[50:51]
	s_lshl_b32 s14, s49, 2
	v_lshl_add_u64 v[50:51], v[50:51], 0, s[14:15]
	s_waitcnt lgkmcnt(0)
	v_add_f32_e32 v48, v48, v49
	global_store_dword v[50:51], v48, off
.LBB0_642:
	s_or_b64 exec, exec, s[22:23]
	v_add_u32_e32 v50, 0x80, v140
	v_lshlrev_b32_e32 v51, 6, v50
	v_lshlrev_b32_e32 v56, 5, v50
	v_ashrrev_i32_e32 v48, 8, v50
	v_and_b32_e32 v51, 0x2000, v51
	v_and_b32_e32 v56, 0x1e0, v56
	s_waitcnt lgkmcnt(0)
	v_ashrrev_i32_e32 v49, 31, v48
	v_or3_b32 v51, v51, v56, v167
	v_cvt_pk_bf16_f32 v56, v40, v41
	v_mul_f32_e32 v41, v41, v41
	v_lshlrev_b64 v[60:61], 5, v[48:49]
	v_fmac_f32_e32 v41, v40, v40
	v_mul_f32_e32 v40, v43, v43
	v_lshl_add_u64 v[48:49], v[60:61], 0, s[6:7]
	v_fmac_f32_e32 v40, v42, v42
	v_cvt_pk_bf16_f32 v57, v42, v43
	v_lshlrev_b64 v[48:49], 15, v[48:49]
	v_add_f32_e32 v40, v41, v40
	v_mul_f32_e32 v41, v45, v45
	v_mul_f32_e32 v42, v47, v47
	v_lshl_add_u64 v[48:49], s[10:11], 0, v[48:49]
	v_lshlrev_b32_e32 v144, 1, v51
	v_fmac_f32_e32 v41, v44, v44
	v_fmac_f32_e32 v42, v46, v46
	v_lshl_add_u64 v[62:63], v[48:49], 0, v[144:145]
	v_add_f32_e32 v41, v41, v42
	v_cvt_pk_bf16_f32 v58, v44, v45
	v_cvt_pk_bf16_f32 v59, v46, v47
	global_store_dwordx4 v[62:63], v[56:59], off sc1
	v_add_f32_e32 v41, v40, v41
	v_cvt_pk_bf16_f32 v40, v36, v37
	v_mul_f32_e32 v37, v37, v37
	v_fmac_f32_e32 v37, v36, v36
	v_mul_f32_e32 v36, v39, v39
	v_fmac_f32_e32 v36, v38, v38
	v_add_f32_e32 v36, v37, v36
	v_mul_f32_e32 v37, v53, v53
	v_mul_f32_e32 v42, v55, v55
	v_fmac_f32_e32 v37, v52, v52
	v_fmac_f32_e32 v42, v54, v54
	v_add_f32_e32 v37, v37, v42
	v_add_f32_e32 v36, v36, v37
	v_add_f32_e32 v44, v41, v36
	ds_bpermute_b32 v45, v112, v44
	v_cvt_pk_bf16_f32 v41, v38, v39
	v_lshl_add_u64 v[36:37], v[60:61], 0, s[8:9]
	v_lshlrev_b64 v[36:37], 15, v[36:37]
	v_lshl_add_u64 v[36:37], s[10:11], 0, v[36:37]
	s_waitcnt lgkmcnt(0)
	v_add_f32_e32 v38, v44, v45
	ds_bpermute_b32 v39, v113, v38
	v_lshl_add_u64 v[44:45], v[36:37], 0, v[144:145]
	v_cvt_pk_bf16_f32 v42, v52, v53
	v_cvt_pk_bf16_f32 v43, v54, v55
	global_store_dwordx4 v[44:45], v[40:43], off sc1
	s_and_saveexec_b64 s[6:7], s[38:39]
	s_cbranch_execz .LBB0_644
	v_ashrrev_i32_e32 v51, 31, v50
	v_lshlrev_b64 v[40:41], 7, v[50:51]
	v_lshl_add_u64 v[40:41], s[18:19], 0, v[40:41]
	v_lshl_add_u64 v[40:41], s[0:1], 2, v[40:41]
	s_lshl_b32 s14, s49, 2
	v_lshl_add_u64 v[40:41], v[40:41], 0, s[14:15]
	s_waitcnt lgkmcnt(0)
	v_add_f32_e32 v38, v38, v39
	global_store_dword v[40:41], v38, off
; __device__ __forceinline__ unsigned cvt_pk_bf16(float lo, float hi) { unsigned r; asm volatile("v_cvt_pk_bf16_f32 %0, %1, %2" : "=v"(r) : "v"(lo), "v"(hi)); return r; }
;     __device__ __forceinline__ size_t xb_off(int row, int col) const { return ((size_t)(row >> 8) * (ldc >> 6) + (col >> 6)) * (256 * 64) + blk_off(row & 255, col & 63); }
;     __device__ __forceinline__ void operator()(const f32x4 (&acc)[2][2][4][2], const State&, const Unit& u, int wr, int wc, int fr, int fq) const {
;     ...
;             for (int ai = 0; ai < 2; ++ai)
; #pragma unroll
;                 for (int m = 0; m < 4; ++m) { const int row = row0 + ai * HALF + m * 16; const size_t off = (size_t)row * ldc + col0; float ss = 0.f;
; #pragma unroll
;                     for (int bj = 0; bj < 2; ++bj) { const f32x4 v0 = acc[ai][bj][m][0], v1 = acc[ai][bj][m][1];
;                         u32x4 w; w.x = cvt_pk_bf16(v0[0], v0[1]); w.y = cvt_pk_bf16(v0[2], v0[3]); w.z = cvt_pk_bf16(v1[0], v1[1]); w.w = cvt_pk_bf16(v1[2], v1[3]);
;                         *(u32x4*)(xb + xb_off(row, col0 + bj * HALF)) = w;
;                         ss += ((v0[0] * v0[0] + v0[1] * v0[1]) + (v0[2] * v0[2] + v0[3] * v0[3])) + ((v1[0] * v1[0] + v1[1] * v1[1]) + (v1[2] * v1[2] + v1[3] * v1[3])); }
;                     ss += __shfl_xor(ss, 16); ss += __shfl_xor(ss, 32);
;                     if (fq == 0) ssq[(size_t)row * 32 + u.pn * 4 + wc] = ss; }
.LBB0_644:
	s_or_b64 exec, exec, s[6:7]
	v_add_u32_e32 v38, 0x90, v140
	s_waitcnt lgkmcnt(0)
	v_lshlrev_b32_e32 v39, 6, v38
	v_lshrrev_b32_e32 v40, 3, v38
	v_and_b32_e32 v39, 0x2000, v39
	v_and_or_b32 v40, v40, 10, s53
	v_lshl_or_b32 v39, v40, 9, v39
	v_lshlrev_b32_e32 v40, 5, v38
	v_and_b32_e32 v40, 0x1e0, v40
	v_or3_b32 v39, v39, v40, v165
	v_cvt_pk_bf16_f32 v40, v16, v17
	v_mul_f32_e32 v17, v17, v17
	v_fmac_f32_e32 v17, v16, v16
	v_mul_f32_e32 v16, v19, v19
	v_fmac_f32_e32 v16, v18, v18
	v_cvt_pk_bf16_f32 v41, v18, v19
	v_add_f32_e32 v16, v17, v16
	v_mul_f32_e32 v17, v89, v89
	v_mul_f32_e32 v18, v91, v91
	v_fmac_f32_e32 v17, v88, v88
	v_fmac_f32_e32 v18, v90, v90
	v_add_f32_e32 v17, v17, v18
	v_add_f32_e32 v16, v16, v17
	v_mul_f32_e32 v17, v85, v85
	v_mul_f32_e32 v18, v87, v87
	v_fmac_f32_e32 v17, v84, v84
	v_fmac_f32_e32 v18, v86, v86
	v_add_f32_e32 v17, v17, v18
	v_mul_f32_e32 v18, v97, v97
	v_mul_f32_e32 v19, v99, v99
	v_fmac_f32_e32 v18, v96, v96
	v_fmac_f32_e32 v19, v98, v98
	v_add_f32_e32 v18, v18, v19
	v_add_f32_e32 v17, v17, v18
	v_add_f32_e32 v18, v16, v17
	ds_bpermute_b32 v19, v112, v18
	v_lshlrev_b32_e32 v144, 1, v39
	v_lshl_add_u64 v[16:17], v[48:49], 0, v[144:145]
	v_cvt_pk_bf16_f32 v42, v88, v89
	v_cvt_pk_bf16_f32 v43, v90, v91
	global_store_dwordx4 v[16:17], v[40:43], off sc1
	s_waitcnt lgkmcnt(0)
	v_add_f32_e32 v16, v18, v19
	ds_bpermute_b32 v17, v113, v16
	v_lshl_add_u64 v[18:19], v[36:37], 0, v[144:145]
	v_cvt_pk_bf16_f32 v40, v84, v85
	v_cvt_pk_bf16_f32 v41, v86, v87
	v_cvt_pk_bf16_f32 v42, v96, v97
	v_cvt_pk_bf16_f32 v43, v98, v99
	global_store_dwordx4 v[18:19], v[40:43], off sc1
	s_and_saveexec_b64 s[6:7], s[38:39]
	s_cbranch_execz .LBB0_646
	v_ashrrev_i32_e32 v39, 31, v38
	v_lshlrev_b64 v[18:19], 7, v[38:39]
	v_lshl_add_u64 v[18:19], s[18:19], 0, v[18:19]
	v_lshl_add_u64 v[18:19], s[0:1], 2, v[18:19]
	s_lshl_b32 s14, s49, 2
	v_lshl_add_u64 v[18:19], v[18:19], 0, s[14:15]
	s_waitcnt lgkmcnt(0)
	v_add_f32_e32 v16, v16, v17
	global_store_dword v[18:19], v16, off
.LBB0_646:
	s_or_b64 exec, exec, s[6:7]
	v_add_u32_e32 v16, 0xa0, v140
	s_waitcnt lgkmcnt(0)
	v_lshlrev_b32_e32 v17, 6, v16
	v_lshrrev_b32_e32 v18, 3, v16
	v_and_b32_e32 v17, 0x2000, v17
	v_and_or_b32 v18, v18, 12, s53
	v_lshl_or_b32 v17, v18, 9, v17
	v_lshlrev_b32_e32 v18, 5, v16
	v_and_b32_e32 v18, 0x1e0, v18
	v_or3_b32 v17, v17, v18, v165
	v_lshlrev_b32_e32 v144, 1, v17
	v_mul_f32_e32 v17, v25, v25
	v_mul_f32_e32 v18, v27, v27
	v_fmac_f32_e32 v17, v24, v24
	v_fmac_f32_e32 v18, v26, v26
	v_add_f32_e32 v17, v17, v18
	v_mul_f32_e32 v18, v29, v29
	v_mul_f32_e32 v19, v31, v31
	v_fmac_f32_e32 v18, v28, v28
	v_fmac_f32_e32 v19, v30, v30
	v_add_f32_e32 v18, v18, v19
	v_add_f32_e32 v17, v17, v18
	v_mul_f32_e32 v18, v21, v21
	v_mul_f32_e32 v19, v23, v23
	v_fmac_f32_e32 v18, v20, v20
	v_fmac_f32_e32 v19, v22, v22
	v_cvt_pk_bf16_f32 v38, v24, v25
	v_add_f32_e32 v18, v18, v19
	v_mul_f32_e32 v19, v33, v33
	v_mul_f32_e32 v24, v35, v35
	v_fmac_f32_e32 v19, v32, v32
	v_fmac_f32_e32 v24, v34, v34
	v_add_f32_e32 v19, v19, v24
	v_add_f32_e32 v18, v18, v19
	v_add_f32_e32 v17, v17, v18
	ds_bpermute_b32 v24, v112, v17
	v_lshl_add_u64 v[18:19], v[48:49], 0, v[144:145]
	v_cvt_pk_bf16_f32 v39, v26, v27
	v_cvt_pk_bf16_f32 v40, v28, v29
	v_cvt_pk_bf16_f32 v41, v30, v31
	global_store_dwordx4 v[18:19], v[38:41], off sc1
	s_waitcnt lgkmcnt(0)
	v_add_f32_e32 v18, v17, v24
	ds_bpermute_b32 v19, v113, v18
	v_lshl_add_u64 v[24:25], v[36:37], 0, v[144:145]
	v_cvt_pk_bf16_f32 v20, v20, v21
	v_cvt_pk_bf16_f32 v21, v22, v23
	v_cvt_pk_bf16_f32 v22, v32, v33
	v_cvt_pk_bf16_f32 v23, v34, v35
	global_store_dwordx4 v[24:25], v[20:23], off sc1
	s_and_saveexec_b64 s[6:7], s[38:39]
	s_cbranch_execz .LBB0_648
	v_ashrrev_i32_e32 v17, 31, v16
	v_lshlrev_b64 v[16:17], 7, v[16:17]
	v_lshl_add_u64 v[16:17], s[18:19], 0, v[16:17]
	v_lshl_add_u64 v[16:17], s[0:1], 2, v[16:17]
	s_lshl_b32 s14, s49, 2
	v_lshl_add_u64 v[16:17], v[16:17], 0, s[14:15]
	s_waitcnt lgkmcnt(0)
	v_add_f32_e32 v18, v18, v19
	global_store_dword v[16:17], v18, off
.LBB0_648:
	s_or_b64 exec, exec, s[6:7]
	v_add_u32_e32 v16, 0xb0, v140
	v_lshlrev_b32_e32 v17, 6, v16
	v_lshrrev_b32_e32 v18, 3, v16
	v_and_b32_e32 v17, 0x2000, v17
	v_and_or_b32 v18, v18, 14, s53
	v_lshl_or_b32 v17, v18, 9, v17
	v_lshlrev_b32_e32 v18, 5, v16
	v_and_b32_e32 v18, 0x1e0, v18
	v_or3_b32 v17, v17, v18, v165
	v_cvt_pk_bf16_f32 v18, v4, v5
	v_mul_f32_e32 v5, v5, v5
	v_fmac_f32_e32 v5, v4, v4
	v_mul_f32_e32 v4, v7, v7
	v_fmac_f32_e32 v4, v6, v6
	s_waitcnt lgkmcnt(0)
	v_cvt_pk_bf16_f32 v19, v6, v7
	v_add_f32_e32 v4, v5, v4
	v_mul_f32_e32 v5, v9, v9
	v_mul_f32_e32 v6, v11, v11
	v_fmac_f32_e32 v5, v8, v8
	v_fmac_f32_e32 v6, v10, v10
	v_add_f32_e32 v5, v5, v6
	v_add_f32_e32 v4, v4, v5
	v_mul_f32_e32 v5, v1, v1
	v_mul_f32_e32 v6, v3, v3
	v_fmac_f32_e32 v5, v0, v0
	v_fmac_f32_e32 v6, v2, v2
	v_add_f32_e32 v5, v5, v6
	v_mul_f32_e32 v6, v13, v13
	v_mul_f32_e32 v7, v15, v15
	v_fmac_f32_e32 v6, v12, v12
	v_fmac_f32_e32 v7, v14, v14
	v_add_f32_e32 v6, v6, v7
	v_add_f32_e32 v5, v5, v6
	v_add_f32_e32 v6, v4, v5
	ds_bpermute_b32 v7, v112, v6
	v_lshlrev_b32_e32 v144, 1, v17
	v_lshl_add_u64 v[4:5], v[48:49], 0, v[144:145]
	v_cvt_pk_bf16_f32 v20, v8, v9
	v_cvt_pk_bf16_f32 v21, v10, v11
	global_store_dwordx4 v[4:5], v[18:21], off sc1
	v_cvt_pk_bf16_f32 v4, v0, v1
	s_waitcnt lgkmcnt(0)
	v_add_f32_e32 v0, v6, v7
	ds_bpermute_b32 v1, v113, v0
	v_cvt_pk_bf16_f32 v5, v2, v3
	v_lshl_add_u64 v[2:3], v[36:37], 0, v[144:145]
	v_cvt_pk_bf16_f32 v6, v12, v13
	v_cvt_pk_bf16_f32 v7, v14, v15
	global_store_dwordx4 v[2:3], v[4:7], off sc1
	s_and_saveexec_b64 s[6:7], s[38:39]
	s_cbranch_execz .LBB0_650
	v_ashrrev_i32_e32 v17, 31, v16
	v_lshlrev_b64 v[2:3], 7, v[16:17]
	v_lshl_add_u64 v[2:3], s[18:19], 0, v[2:3]
	v_lshl_add_u64 v[2:3], s[0:1], 2, v[2:3]
	s_lshl_b32 s14, s49, 2
	v_lshl_add_u64 v[2:3], v[2:3], 0, s[14:15]
	s_waitcnt lgkmcnt(0)
	v_add_f32_e32 v0, v0, v1
	global_store_dword v[2:3], v0, off
